# v42
# speedup vs baseline: 1.0094x; 1.0094x over previous
; #define PG8_STAGE(bufoff, gbase, voff) do { _Pragma("unroll") for (int _i = 0; _i < 2; ++_i) \
;         __builtin_amdgcn_global_load_lds((const unsigned*)((const char*)(gbase) + (voff)[_i]), (PG8_LAS unsigned*)(lds + (bufoff) + ldsw + _i * 8192), 16, 0, 0); } while (0)
; #define PG8_LDA(dst, b, h) do { _Pragma("unroll") for (int m = 0; m < 4; ++m) _Pragma("unroll") for (int k = 0; k < 2; ++k) dst[m][k] = *(const PG8_LAS bf16x8*)(lds + PG8_SA(b, h) + aoff + m * 2048 + k * 1024); } while (0)
; #define PG8_LDB(dst, b, h) do { _Pragma("unroll") for (int n = 0; n < 2; ++n) _Pragma("unroll") for (int k = 0; k < 2; ++k) dst[n][k] = *(const PG8_LAS bf16x8*)(lds + PG8_SB(b, h) + boff + n * 2048 + k * 1024); } while (0)
; #define PG8_MMA(ai, bj, At, Bt) do { __builtin_amdgcn_s_setprio(1); _Pragma("unroll") for (int m = 0; m < 4; ++m) _Pragma("unroll") for (int n = 0; n < 2; ++n) _Pragma("unroll") for (int k = 0; k < 2; ++k) \
;         acc[ai][bj][m][n] = __builtin_amdgcn_mfma_f32_16x16x32_bf16(Bt[n][k], At[m][k], acc[ai][bj][m][n], 0, 0, 0); __builtin_amdgcn_s_setprio(0); } while (0)
; #define PG8_BAR __builtin_amdgcn_s_barrier()
; template <class Epi, class Sched, bool ALIGN_EPI = false, bool SP2 = false>
; __device__ __forceinline__ void gemm_phase(PG8_LAS unsigned char* lds, const Gemm g, const Sched& S, const Epi& E) {
;     ...
;         const bool has_next = S.next(ui + 1, nxt);
;         const char* nA = has_next ? (const char*)g.A + (size_t)nxt.pm * tstep : cA; const char* nB = has_next ? (const char*)g.Bt + (size_t)nxt.pn * tstep : cB;
;         for (int t = 0; t < nt; t += 2) {
;             const bool last = (t == nt - 2);
;             const char* a1 = cA + (size_t)(t + 1) * kstep;
;             const char* a2 = last ? nA : cA + (size_t)(t + 2) * kstep; const char* b2 = last ? nB : cB + (size_t)(t + 2) * kstep;
;             const char* a3 = a2 + kstep; const char* b3 = b2 + kstep;
;             if (last && has_next) S.a_ready(nxt);
;             if constexpr (SP2) {
;             PG8_LDB(B0, 0, 0); PG8_LDB(B1, 0, 1); PG8_SCHED; PG8_LDA(At, 0, 0); PG8_STAGE(PG8_SA(1, 1), a1 + hstep, voffA);
;             PG8_WAIT_V(8); PG8_WAIT_L(0); PG8_BAR; PG8_MMA(0, 0, At, B0); PG8_MMA(0, 1, At, B1); PG8_BAR; PG8_SCHED;
;             PG8_LDA(At, 0, 1); PG8_STAGE(PG8_SB(0, 0), b2, voffB); PG8_STAGE(PG8_SB(0, 1), b2 + hstep, voffB); PG8_STAGE(PG8_SA(0, 0), a2, voffA);
.LBB0_168:
	s_ashr_i32 s29, s28, 31
	v_cmp_lt_i64_e32 vcc, s[30:31], v[140:141]
	s_lshl_b64 s[30:31], s[28:29], 20
	s_add_u32 s30, s6, s30
	s_addc_u32 s31, s7, s31
	s_and_b64 s[34:35], vcc, exec
	s_cselect_b32 s29, s31, s39
	s_cselect_b32 s57, s30, s38
	s_ashr_i32 s27, s26, 31
	s_lshl_b64 s[34:35], s[26:27], 20
	s_add_u32 s34, s22, s34
	s_addc_u32 s35, s23, s35
	s_and_b64 s[42:43], vcc, exec
	s_cselect_b32 s27, s35, s41
	s_cselect_b32 s58, s34, s40
	s_add_u32 s38, s38, 0x80080
	s_addc_u32 s39, s39, 0
	s_add_u32 s59, s40, 0x100
	s_addc_u32 s60, s41, 0
	s_mov_b32 s61, -2
	ds_read_b128 v[152:155], v149
	ds_read_b128 v[156:159], v149 offset:1024
	ds_read_b128 v[160:163], v149 offset:2048
	ds_read_b128 v[164:167], v149 offset:3072
	ds_read_b128 v[168:171], v150
	ds_read_b128 v[172:175], v150 offset:1024
	ds_read_b128 v[176:179], v150 offset:2048
	ds_read_b128 v[180:183], v150 offset:3072
	s_add_u32 s40, s38, 0xfff80080
	s_addc_u32 s41, s39, -1
	s_cmp_eq_u32 s61, 28
	s_cselect_b32 s43, s29, s41
	s_cselect_b32 s42, s57, s40
	s_cselect_b32 s41, s27, s60
	s_cselect_b32 s40, s58, s59
	s_add_i32 m0, s37, 0xc000
	ds_read_b128 v[184:187], v151
	ds_read_b128 v[188:191], v151 offset:1024
	ds_read_b128 v[192:195], v151 offset:2048
	ds_read_b128 v[196:199], v151 offset:3072
	ds_read_b128 v[200:203], v151 offset:4096
	ds_read_b128 v[204:207], v151 offset:5120
	ds_read_b128 v[208:211], v151 offset:6144
	ds_read_b128 v[214:217], v151 offset:7168
	global_load_lds_dwordx4 v136, s[38:39]
	s_add_i32 m0, s37, 0xe000
	s_nop 0
	global_load_lds_dwordx4 v138, s[38:39]
	s_waitcnt vmcnt(8)
	s_waitcnt lgkmcnt(0)
	s_barrier
	s_waitcnt lgkmcnt(0)
	v_mfma_f32_16x16x32_bf16 v[124:127], v[152:155], v[184:187], 0
	v_mfma_f32_16x16x32_bf16 v[120:123], v[160:163], v[184:187], 0
	v_mfma_f32_16x16x32_bf16 v[108:111], v[152:155], v[192:195], 0
	v_mfma_f32_16x16x32_bf16 v[104:107], v[160:163], v[192:195], 0
	v_mfma_f32_16x16x32_bf16 v[92:95], v[152:155], v[200:203], 0
	v_mfma_f32_16x16x32_bf16 v[88:91], v[160:163], v[200:203], 0
	v_mfma_f32_16x16x32_bf16 v[76:79], v[152:155], v[208:211], 0
	v_mfma_f32_16x16x32_bf16 v[72:75], v[160:163], v[208:211], 0
	v_mfma_f32_16x16x32_bf16 v[124:127], v[156:159], v[188:191], v[124:127]
	v_mfma_f32_16x16x32_bf16 v[120:123], v[164:167], v[188:191], v[120:123]
	v_mfma_f32_16x16x32_bf16 v[108:111], v[156:159], v[196:199], v[108:111]
	v_mfma_f32_16x16x32_bf16 v[104:107], v[164:167], v[196:199], v[104:107]
	v_mfma_f32_16x16x32_bf16 v[92:95], v[156:159], v[204:207], v[92:95]
	v_mfma_f32_16x16x32_bf16 v[88:91], v[164:167], v[204:207], v[88:91]
	v_mfma_f32_16x16x32_bf16 v[76:79], v[156:159], v[214:217], v[76:79]
	v_mfma_f32_16x16x32_bf16 v[72:75], v[164:167], v[214:217], v[72:75]
	v_mfma_f32_16x16x32_bf16 v[116:119], v[168:171], v[184:187], 0
	v_mfma_f32_16x16x32_bf16 v[112:115], v[176:179], v[184:187], 0
	v_mfma_f32_16x16x32_bf16 v[100:103], v[168:171], v[192:195], 0
	v_mfma_f32_16x16x32_bf16 v[96:99], v[176:179], v[192:195], 0
	v_mfma_f32_16x16x32_bf16 v[84:87], v[168:171], v[200:203], 0
	v_mfma_f32_16x16x32_bf16 v[80:83], v[176:179], v[200:203], 0
	v_mfma_f32_16x16x32_bf16 v[68:71], v[168:171], v[208:211], 0
	v_mfma_f32_16x16x32_bf16 v[64:67], v[176:179], v[208:211], 0
	v_mfma_f32_16x16x32_bf16 v[116:119], v[172:175], v[188:191], v[116:119]
	v_mfma_f32_16x16x32_bf16 v[112:115], v[180:183], v[188:191], v[112:115]
	v_mfma_f32_16x16x32_bf16 v[100:103], v[172:175], v[196:199], v[100:103]
	v_mfma_f32_16x16x32_bf16 v[96:99], v[180:183], v[196:199], v[96:99]
	v_mfma_f32_16x16x32_bf16 v[84:87], v[172:175], v[204:207], v[84:87]
	v_mfma_f32_16x16x32_bf16 v[80:83], v[180:183], v[204:207], v[80:83]
	v_mfma_f32_16x16x32_bf16 v[68:71], v[172:175], v[214:217], v[68:71]
	v_mfma_f32_16x16x32_bf16 v[64:67], v[180:183], v[214:217], v[64:67]
	s_barrier
	s_add_i32 s62, s53, s24
	s_mov_b32 m0, s62
	ds_read_b128 v[184:187], v151 offset:16384
	ds_read_b128 v[188:191], v151 offset:17408
	ds_read_b128 v[192:195], v151 offset:18432
	ds_read_b128 v[196:199], v151 offset:19456
	ds_read_b128 v[200:203], v151 offset:20480
	ds_read_b128 v[204:207], v151 offset:21504
	ds_read_b128 v[208:211], v151 offset:22528
	ds_read_b128 v[214:217], v151 offset:23552
	global_load_lds_dwordx4 v132, s[40:41]
	s_add_i32 m0, s62, 0x2000
	s_add_u32 s62, s40, 0x80000
	s_addc_u32 s63, s41, 0
	s_add_i32 s64, s54, s24
	global_load_lds_dwordx4 v128, s[40:41]
	s_mov_b32 m0, s64
	s_nop 0
	global_load_lds_dwordx4 v132, s[62:63]
	s_add_i32 m0, s64, 0x2000
	s_nop 0
	global_load_lds_dwordx4 v128, s[62:63]
	s_mov_b32 m0, s37
	s_nop 0
	global_load_lds_dwordx4 v134, s[42:43]
	s_mov_b32 m0, s45
	s_nop 0
	global_load_lds_dwordx4 v130, s[42:43]
	s_waitcnt vmcnt(8)
	s_waitcnt lgkmcnt(0)
	s_barrier
; #define PG8_STAGE(bufoff, gbase, voff) do { _Pragma("unroll") for (int _i = 0; _i < 2; ++_i) \
;         __builtin_amdgcn_global_load_lds((const unsigned*)((const char*)(gbase) + (voff)[_i]), (PG8_LAS unsigned*)(lds + (bufoff) + ldsw + _i * 8192), 16, 0, 0); } while (0)
; #define PG8_LDA(dst, b, h) do { _Pragma("unroll") for (int m = 0; m < 4; ++m) _Pragma("unroll") for (int k = 0; k < 2; ++k) dst[m][k] = *(const PG8_LAS bf16x8*)(lds + PG8_SA(b, h) + aoff + m * 2048 + k * 1024); } while (0)
; #define PG8_LDB(dst, b, h) do { _Pragma("unroll") for (int n = 0; n < 2; ++n) _Pragma("unroll") for (int k = 0; k < 2; ++k) dst[n][k] = *(const PG8_LAS bf16x8*)(lds + PG8_SB(b, h) + boff + n * 2048 + k * 1024); } while (0)
; #define PG8_MMA(ai, bj, At, Bt) do { __builtin_amdgcn_s_setprio(1); _Pragma("unroll") for (int m = 0; m < 4; ++m) _Pragma("unroll") for (int n = 0; n < 2; ++n) _Pragma("unroll") for (int k = 0; k < 2; ++k) \
;         acc[ai][bj][m][n] = __builtin_amdgcn_mfma_f32_16x16x32_bf16(Bt[n][k], At[m][k], acc[ai][bj][m][n], 0, 0, 0); __builtin_amdgcn_s_setprio(0); } while (0)
; #define PG8_WAIT_V(n) asm volatile("s_waitcnt vmcnt(" #n ")" ::: "memory")
; #define PG8_WAIT_L(n) asm volatile("s_waitcnt lgkmcnt(" #n ")" ::: "memory")
; #define PG8_BAR __builtin_amdgcn_s_barrier()
; #define PG8_SCHED __builtin_amdgcn_sched_barrier(0)
; template <class Epi, class Sched, bool ALIGN_EPI = false, bool SP2 = false>
; __device__ __forceinline__ void gemm_phase(PG8_LAS unsigned char* lds, const Gemm g, const Sched& S, const Epi& E) {
;     ...
;             PG8_WAIT_V(8); PG8_WAIT_L(0); PG8_BAR; PG8_MMA(1, 0, At, B0); PG8_MMA(1, 1, At, B1); PG8_BAR; PG8_SCHED;
;             PG8_LDB(B0, 1, 0); PG8_LDB(B1, 1, 1); PG8_SCHED; PG8_LDA(At, 1, 0); PG8_STAGE(PG8_SA(0, 1), a2 + hstep, voffA);
;             PG8_WAIT_V(8); PG8_WAIT_L(0); PG8_BAR; PG8_MMA(0, 0, At, B0); PG8_MMA(0, 1, At, B1); PG8_BAR; PG8_SCHED;
	s_waitcnt lgkmcnt(0)
	v_mfma_f32_16x16x32_bf16 v[60:63], v[152:155], v[184:187], 0
	v_mfma_f32_16x16x32_bf16 v[56:59], v[160:163], v[184:187], 0
	v_mfma_f32_16x16x32_bf16 v[44:47], v[152:155], v[192:195], 0
	v_mfma_f32_16x16x32_bf16 v[40:43], v[160:163], v[192:195], 0
	v_mfma_f32_16x16x32_bf16 v[28:31], v[152:155], v[200:203], 0
	v_mfma_f32_16x16x32_bf16 v[24:27], v[160:163], v[200:203], 0
	v_mfma_f32_16x16x32_bf16 v[12:15], v[152:155], v[208:211], 0
	v_mfma_f32_16x16x32_bf16 v[8:11], v[160:163], v[208:211], 0
	v_mfma_f32_16x16x32_bf16 v[60:63], v[156:159], v[188:191], v[60:63]
	v_mfma_f32_16x16x32_bf16 v[56:59], v[164:167], v[188:191], v[56:59]
	v_mfma_f32_16x16x32_bf16 v[44:47], v[156:159], v[196:199], v[44:47]
	v_mfma_f32_16x16x32_bf16 v[40:43], v[164:167], v[196:199], v[40:43]
	v_mfma_f32_16x16x32_bf16 v[28:31], v[156:159], v[204:207], v[28:31]
	v_mfma_f32_16x16x32_bf16 v[24:27], v[164:167], v[204:207], v[24:27]
	v_mfma_f32_16x16x32_bf16 v[12:15], v[156:159], v[214:217], v[12:15]
	v_mfma_f32_16x16x32_bf16 v[8:11], v[164:167], v[214:217], v[8:11]
	v_mfma_f32_16x16x32_bf16 v[52:55], v[168:171], v[184:187], 0
	v_mfma_f32_16x16x32_bf16 v[48:51], v[176:179], v[184:187], 0
	v_mfma_f32_16x16x32_bf16 v[36:39], v[168:171], v[192:195], 0
	v_mfma_f32_16x16x32_bf16 v[32:35], v[176:179], v[192:195], 0
	v_mfma_f32_16x16x32_bf16 v[20:23], v[168:171], v[200:203], 0
	v_mfma_f32_16x16x32_bf16 v[16:19], v[176:179], v[200:203], 0
	v_mfma_f32_16x16x32_bf16 v[4:7], v[168:171], v[208:211], 0
	v_mfma_f32_16x16x32_bf16 v[0:3], v[176:179], v[208:211], 0
	v_mfma_f32_16x16x32_bf16 v[52:55], v[172:175], v[188:191], v[52:55]
	v_mfma_f32_16x16x32_bf16 v[48:51], v[180:183], v[188:191], v[48:51]
	v_mfma_f32_16x16x32_bf16 v[36:39], v[172:175], v[196:199], v[36:39]
	v_mfma_f32_16x16x32_bf16 v[32:35], v[180:183], v[196:199], v[32:35]
	v_mfma_f32_16x16x32_bf16 v[20:23], v[172:175], v[204:207], v[20:23]
	v_mfma_f32_16x16x32_bf16 v[16:19], v[180:183], v[204:207], v[16:19]
	v_mfma_f32_16x16x32_bf16 v[4:7], v[172:175], v[214:217], v[4:7]
	v_mfma_f32_16x16x32_bf16 v[0:3], v[180:183], v[214:217], v[0:3]
	s_barrier
	s_add_i32 s62, 0, 0x18000
	s_add_i32 s63, 0, 0x1c000
	v_add_u32_e32 v164, s62, v147
	v_add_u32_e32 v180, s63, v147
	ds_read_b128 v[152:155], v164
	ds_read_b128 v[156:159], v164 offset:1024
	ds_read_b128 v[160:163], v164 offset:2048
	ds_read_b128 v[164:167], v164 offset:3072
	ds_read_b128 v[168:171], v180
	ds_read_b128 v[172:175], v180 offset:1024
	ds_read_b128 v[176:179], v180 offset:2048
	ds_read_b128 v[180:183], v180 offset:3072
	s_add_u32 s84, s42, 0x80
	s_addc_u32 s85, s43, 0
	s_add_u32 s42, s42, 0x80000
	s_addc_u32 s43, s43, 0
	s_mov_b32 m0, s46
	ds_read_b128 v[184:187], v151 offset:32768
	ds_read_b128 v[188:191], v151 offset:33792
	ds_read_b128 v[192:195], v151 offset:34816
	ds_read_b128 v[196:199], v151 offset:35840
	ds_read_b128 v[200:203], v151 offset:36864
	ds_read_b128 v[204:207], v151 offset:37888
	ds_read_b128 v[208:211], v151 offset:38912
	ds_read_b128 v[214:217], v151 offset:39936
	global_load_lds_dwordx4 v134, s[42:43]
	s_mov_b32 m0, s47
	s_nop 0
	global_load_lds_dwordx4 v130, s[42:43]
	s_waitcnt vmcnt(8)
	s_waitcnt lgkmcnt(0)
	s_barrier
	s_waitcnt lgkmcnt(0)
	v_mfma_f32_16x16x32_bf16 v[124:127], v[152:155], v[184:187], v[124:127]
	v_mfma_f32_16x16x32_bf16 v[120:123], v[160:163], v[184:187], v[120:123]
	v_mfma_f32_16x16x32_bf16 v[108:111], v[152:155], v[192:195], v[108:111]
	v_mfma_f32_16x16x32_bf16 v[104:107], v[160:163], v[192:195], v[104:107]
	v_mfma_f32_16x16x32_bf16 v[92:95], v[152:155], v[200:203], v[92:95]
	v_mfma_f32_16x16x32_bf16 v[88:91], v[160:163], v[200:203], v[88:91]
	v_mfma_f32_16x16x32_bf16 v[76:79], v[152:155], v[208:211], v[76:79]
	v_mfma_f32_16x16x32_bf16 v[72:75], v[160:163], v[208:211], v[72:75]
	v_mfma_f32_16x16x32_bf16 v[124:127], v[156:159], v[188:191], v[124:127]
	v_mfma_f32_16x16x32_bf16 v[120:123], v[164:167], v[188:191], v[120:123]
	v_mfma_f32_16x16x32_bf16 v[108:111], v[156:159], v[196:199], v[108:111]
	v_mfma_f32_16x16x32_bf16 v[104:107], v[164:167], v[196:199], v[104:107]
	v_mfma_f32_16x16x32_bf16 v[92:95], v[156:159], v[204:207], v[92:95]
	v_mfma_f32_16x16x32_bf16 v[88:91], v[164:167], v[204:207], v[88:91]
	v_mfma_f32_16x16x32_bf16 v[76:79], v[156:159], v[214:217], v[76:79]
	v_mfma_f32_16x16x32_bf16 v[72:75], v[164:167], v[214:217], v[72:75]
	v_mfma_f32_16x16x32_bf16 v[116:119], v[168:171], v[184:187], v[116:119]
	v_mfma_f32_16x16x32_bf16 v[112:115], v[176:179], v[184:187], v[112:115]
	v_mfma_f32_16x16x32_bf16 v[100:103], v[168:171], v[192:195], v[100:103]
	v_mfma_f32_16x16x32_bf16 v[96:99], v[176:179], v[192:195], v[96:99]
	v_mfma_f32_16x16x32_bf16 v[84:87], v[168:171], v[200:203], v[84:87]
	v_mfma_f32_16x16x32_bf16 v[80:83], v[176:179], v[200:203], v[80:83]
	v_mfma_f32_16x16x32_bf16 v[68:71], v[168:171], v[208:211], v[68:71]
	v_mfma_f32_16x16x32_bf16 v[64:67], v[176:179], v[208:211], v[64:67]
	v_mfma_f32_16x16x32_bf16 v[116:119], v[172:175], v[188:191], v[116:119]
	v_mfma_f32_16x16x32_bf16 v[112:115], v[180:183], v[188:191], v[112:115]
	v_mfma_f32_16x16x32_bf16 v[100:103], v[172:175], v[196:199], v[100:103]
	v_mfma_f32_16x16x32_bf16 v[96:99], v[180:183], v[196:199], v[96:99]
	v_mfma_f32_16x16x32_bf16 v[84:87], v[172:175], v[204:207], v[84:87]
	v_mfma_f32_16x16x32_bf16 v[80:83], v[180:183], v[204:207], v[80:83]
	v_mfma_f32_16x16x32_bf16 v[68:71], v[172:175], v[214:217], v[68:71]
	v_mfma_f32_16x16x32_bf16 v[64:67], v[180:183], v[214:217], v[64:67]
	s_barrier
; #define PG8_STAGE(bufoff, gbase, voff) do { _Pragma("unroll") for (int _i = 0; _i < 2; ++_i) \
;         __builtin_amdgcn_global_load_lds((const unsigned*)((const char*)(gbase) + (voff)[_i]), (PG8_LAS unsigned*)(lds + (bufoff) + ldsw + _i * 8192), 16, 0, 0); } while (0)
; #define PG8_LDA(dst, b, h) do { _Pragma("unroll") for (int m = 0; m < 4; ++m) _Pragma("unroll") for (int k = 0; k < 2; ++k) dst[m][k] = *(const PG8_LAS bf16x8*)(lds + PG8_SA(b, h) + aoff + m * 2048 + k * 1024); } while (0)
; #define PG8_MMA(ai, bj, At, Bt) do { __builtin_amdgcn_s_setprio(1); _Pragma("unroll") for (int m = 0; m < 4; ++m) _Pragma("unroll") for (int n = 0; n < 2; ++n) _Pragma("unroll") for (int k = 0; k < 2; ++k) \
;         acc[ai][bj][m][n] = __builtin_amdgcn_mfma_f32_16x16x32_bf16(Bt[n][k], At[m][k], acc[ai][bj][m][n], 0, 0, 0); __builtin_amdgcn_s_setprio(0); } while (0)
; #define PG8_WAIT_V(n) asm volatile("s_waitcnt vmcnt(" #n ")" ::: "memory")
; #define PG8_WAIT_L(n) asm volatile("s_waitcnt lgkmcnt(" #n ")" ::: "memory")
; #define PG8_BAR __builtin_amdgcn_s_barrier()
; #define PG8_SCHED __builtin_amdgcn_sched_barrier(0)
; template <class Epi, class Sched, bool ALIGN_EPI = false, bool SP2 = false>
; __device__ __forceinline__ void gemm_phase(PG8_LAS unsigned char* lds, const Gemm g, const Sched& S, const Epi& E) {
;     ...
;             PG8_WAIT_V(8); PG8_WAIT_L(0); PG8_BAR; PG8_MMA(0, 0, At, B0); PG8_MMA(0, 1, At, B1); PG8_BAR; PG8_SCHED;
;             PG8_LDA(At, 1, 1); PG8_STAGE(PG8_SB(1, 0), b3, voffB); PG8_STAGE(PG8_SB(1, 1), b3 + hstep, voffB); PG8_STAGE(PG8_SA(1, 0), a3, voffA);
;             PG8_WAIT_V(8); PG8_WAIT_L(0); PG8_BAR; PG8_MMA(1, 0, At, B0); PG8_MMA(1, 1, At, B1); PG8_BAR; PG8_SCHED;
	s_add_i32 s42, s62, s24
	s_add_u32 s86, s40, 0x80
	s_addc_u32 s87, s41, 0
	s_mov_b32 m0, s42
	ds_read_b128 v[184:187], v151 offset:49152
	ds_read_b128 v[188:191], v151 offset:50176
	ds_read_b128 v[192:195], v151 offset:51200
	ds_read_b128 v[196:199], v151 offset:52224
	ds_read_b128 v[200:203], v151 offset:53248
	ds_read_b128 v[204:207], v151 offset:54272
	ds_read_b128 v[208:211], v151 offset:55296
	ds_read_b128 v[214:217], v151 offset:56320
	global_load_lds_dwordx4 v132, s[86:87]
	s_add_i32 m0, s42, 0x2000
	s_add_u32 s40, s40, 0x80080
	s_addc_u32 s41, s41, 0
	s_add_i32 s42, s63, s24
	global_load_lds_dwordx4 v128, s[86:87]
	s_mov_b32 m0, s42
	s_nop 0
	global_load_lds_dwordx4 v132, s[40:41]
	s_add_i32 m0, s42, 0x2000
	s_nop 0
	global_load_lds_dwordx4 v128, s[40:41]
	s_mov_b32 m0, s49
	s_nop 0
	global_load_lds_dwordx4 v134, s[84:85]
	s_mov_b32 m0, s50
	s_nop 0
	global_load_lds_dwordx4 v130, s[84:85]
	s_waitcnt vmcnt(8)
	s_waitcnt lgkmcnt(0)
	s_barrier
	s_waitcnt lgkmcnt(0)
	v_mfma_f32_16x16x32_bf16 v[60:63], v[152:155], v[184:187], v[60:63]
	v_mfma_f32_16x16x32_bf16 v[56:59], v[160:163], v[184:187], v[56:59]
	v_mfma_f32_16x16x32_bf16 v[44:47], v[152:155], v[192:195], v[44:47]
	v_mfma_f32_16x16x32_bf16 v[40:43], v[160:163], v[192:195], v[40:43]
	v_mfma_f32_16x16x32_bf16 v[28:31], v[152:155], v[200:203], v[28:31]
	v_mfma_f32_16x16x32_bf16 v[24:27], v[160:163], v[200:203], v[24:27]
	v_mfma_f32_16x16x32_bf16 v[12:15], v[152:155], v[208:211], v[12:15]
	v_mfma_f32_16x16x32_bf16 v[8:11], v[160:163], v[208:211], v[8:11]
	v_mfma_f32_16x16x32_bf16 v[60:63], v[156:159], v[188:191], v[60:63]
	v_mfma_f32_16x16x32_bf16 v[56:59], v[164:167], v[188:191], v[56:59]
	v_mfma_f32_16x16x32_bf16 v[44:47], v[156:159], v[196:199], v[44:47]
	v_mfma_f32_16x16x32_bf16 v[40:43], v[164:167], v[196:199], v[40:43]
	v_mfma_f32_16x16x32_bf16 v[28:31], v[156:159], v[204:207], v[28:31]
	v_mfma_f32_16x16x32_bf16 v[24:27], v[164:167], v[204:207], v[24:27]
	v_mfma_f32_16x16x32_bf16 v[12:15], v[156:159], v[214:217], v[12:15]
	v_mfma_f32_16x16x32_bf16 v[8:11], v[164:167], v[214:217], v[8:11]
	v_mfma_f32_16x16x32_bf16 v[52:55], v[168:171], v[184:187], v[52:55]
	v_mfma_f32_16x16x32_bf16 v[48:51], v[176:179], v[184:187], v[48:51]
	v_mfma_f32_16x16x32_bf16 v[36:39], v[168:171], v[192:195], v[36:39]
	v_mfma_f32_16x16x32_bf16 v[32:35], v[176:179], v[192:195], v[32:35]
	v_mfma_f32_16x16x32_bf16 v[20:23], v[168:171], v[200:203], v[20:23]
	v_mfma_f32_16x16x32_bf16 v[16:19], v[176:179], v[200:203], v[16:19]
	v_mfma_f32_16x16x32_bf16 v[4:7], v[168:171], v[208:211], v[4:7]
	v_mfma_f32_16x16x32_bf16 v[0:3], v[176:179], v[208:211], v[0:3]
	v_mfma_f32_16x16x32_bf16 v[52:55], v[172:175], v[188:191], v[52:55]
	v_mfma_f32_16x16x32_bf16 v[48:51], v[180:183], v[188:191], v[48:51]
	v_mfma_f32_16x16x32_bf16 v[36:39], v[172:175], v[196:199], v[36:39]
	v_mfma_f32_16x16x32_bf16 v[32:35], v[180:183], v[196:199], v[32:35]
	v_mfma_f32_16x16x32_bf16 v[20:23], v[172:175], v[204:207], v[20:23]
	v_mfma_f32_16x16x32_bf16 v[16:19], v[180:183], v[204:207], v[16:19]
	v_mfma_f32_16x16x32_bf16 v[4:7], v[172:175], v[214:217], v[4:7]
	v_mfma_f32_16x16x32_bf16 v[0:3], v[180:183], v[214:217], v[0:3]
	s_barrier
	s_add_i32 s61, s61, 2
	s_add_u32 s38, s38, 0x100
	s_addc_u32 s39, s39, 0
	s_add_u32 s59, s59, 0x100
	s_addc_u32 s60, s60, 0
	s_cmp_gt_u32 s61, 29
	.p2align	6

; #define PG8_STAGE(bufoff, gbase, voff) do { _Pragma("unroll") for (int _i = 0; _i < 2; ++_i) \
;         __builtin_amdgcn_global_load_lds((const unsigned*)((const char*)(gbase) + (voff)[_i]), (PG8_LAS unsigned*)(lds + (bufoff) + ldsw + _i * 8192), 16, 0, 0); } while (0)
; #define PG8_LDA(dst, b, h) do { _Pragma("unroll") for (int m = 0; m < 4; ++m) _Pragma("unroll") for (int k = 0; k < 2; ++k) dst[m][k] = *(const PG8_LAS bf16x8*)(lds + PG8_SA(b, h) + aoff + m * 2048 + k * 1024); } while (0)
; #define PG8_LDB(dst, b, h) do { _Pragma("unroll") for (int n = 0; n < 2; ++n) _Pragma("unroll") for (int k = 0; k < 2; ++k) dst[n][k] = *(const PG8_LAS bf16x8*)(lds + PG8_SB(b, h) + boff + n * 2048 + k * 1024); } while (0)
; #define PG8_WAIT_V(n) asm volatile("s_waitcnt vmcnt(" #n ")" ::: "memory")
; #define PG8_WAIT_L(n) asm volatile("s_waitcnt lgkmcnt(" #n ")" ::: "memory")
; #define PG8_BAR __builtin_amdgcn_s_barrier()
; #define PG8_SCHED __builtin_amdgcn_sched_barrier(0)
; template <class Epi, class Sched, bool ALIGN_EPI = false, bool SP2 = false>
; __device__ __forceinline__ void gemm_phase(PG8_LAS unsigned char* lds, const Gemm g, const Sched& S, const Epi& E) {
;     ...
;         const bool has_next = S.next(ui + 1, nxt);
;         const char* nA = has_next ? (const char*)g.A + (size_t)nxt.pm * tstep : cA; const char* nB = has_next ? (const char*)g.Bt + (size_t)nxt.pn * tstep : cB;
;         for (int t = 0; t < nt; t += 2) {
;             const bool last = (t == nt - 2);
;             const char* a1 = cA + (size_t)(t + 1) * kstep;
;             const char* a2 = last ? nA : cA + (size_t)(t + 2) * kstep; const char* b2 = last ? nB : cB + (size_t)(t + 2) * kstep;
;             const char* a3 = a2 + kstep; const char* b3 = b2 + kstep;
;             if (last && has_next) S.a_ready(nxt);
;             if constexpr (SP2) {
;             PG8_LDB(B0, 0, 0); PG8_LDB(B1, 0, 1); PG8_SCHED; PG8_LDA(At, 0, 0); PG8_STAGE(PG8_SA(1, 1), a1 + hstep, voffA);
;             PG8_WAIT_V(8); PG8_WAIT_L(0); PG8_BAR; PG8_MMA(0, 0, At, B0); PG8_MMA(0, 1, At, B1); PG8_BAR; PG8_SCHED;
;             PG8_LDA(At, 0, 1); PG8_STAGE(PG8_SB(0, 0), b2, voffB); PG8_STAGE(PG8_SB(0, 1), b2 + hstep, voffB); PG8_STAGE(PG8_SA(0, 0), a2, voffA);
;             PG8_WAIT_V(8); PG8_WAIT_L(0); PG8_BAR; PG8_MMA(1, 0, At, B0); PG8_MMA(1, 1, At, B1); PG8_BAR; PG8_SCHED;
.LBB0_244:
	s_add_u32 s67, s46, 0x100
	v_mov_b32_e32 v220, v251
	s_addc_u32 s68, s47, 0
	s_mov_b32 s69, -2
	ds_read_b128 v[140:143], v169
	ds_read_b128 v[144:147], v169 offset:1024
	ds_read_b128 v[148:151], v169 offset:2048
	ds_read_b128 v[152:155], v169 offset:3072
	ds_read_b128 v[156:159], v170
	ds_read_b128 v[160:163], v170 offset:1024
	ds_read_b128 v[172:175], v170 offset:2048
	ds_read_b128 v[176:179], v170 offset:3072
	s_add_u32 s46, s44, 0x100
	s_addc_u32 s47, s45, 0
	s_cmpk_eq_i32 s69, 0x54
	s_cselect_b32 s51, s11, s47
	s_cselect_b32 s50, s10, s46
	s_cselect_b32 s49, s13, s68
	s_cselect_b32 s48, s12, s67
	s_add_i32 m0, s26, 0xc000
	ds_read_b128 v[180:183], v171
	ds_read_b128 v[184:187], v171 offset:1024
	ds_read_b128 v[188:191], v171 offset:2048
	ds_read_b128 v[192:195], v171 offset:3072
	ds_read_b128 v[196:199], v171 offset:4096
	ds_read_b128 v[200:203], v171 offset:5120
	ds_read_b128 v[204:207], v171 offset:6144
	ds_read_b128 v[208:211], v171 offset:7168
	global_load_lds_dwordx4 v136, s[44:45]
	s_add_i32 m0, s26, 0xe000
	s_nop 0
	global_load_lds_dwordx4 v138, s[44:45]
	s_waitcnt vmcnt(8)
	s_waitcnt lgkmcnt(0)
	s_barrier
	s_waitcnt lgkmcnt(0)
	v_mfma_f32_16x16x32_bf16 v[124:127], v[140:143], v[180:183], 0
	v_mfma_f32_16x16x32_bf16 v[120:123], v[148:151], v[180:183], 0
	v_mfma_f32_16x16x32_bf16 v[116:119], v[140:143], v[188:191], 0
	v_mfma_f32_16x16x32_bf16 v[112:115], v[148:151], v[188:191], 0
	v_mfma_f32_16x16x32_bf16 v[108:111], v[140:143], v[196:199], 0
	v_mfma_f32_16x16x32_bf16 v[96:99], v[148:151], v[196:199], 0
	v_mfma_f32_16x16x32_bf16 v[84:87], v[140:143], v[204:207], 0
	v_mfma_f32_16x16x32_bf16 v[76:79], v[148:151], v[204:207], 0
	v_mfma_f32_16x16x32_bf16 v[124:127], v[144:147], v[184:187], v[124:127]
	v_mfma_f32_16x16x32_bf16 v[120:123], v[152:155], v[184:187], v[120:123]
	v_mfma_f32_16x16x32_bf16 v[116:119], v[144:147], v[192:195], v[116:119]
	v_mfma_f32_16x16x32_bf16 v[112:115], v[152:155], v[192:195], v[112:115]
	v_mfma_f32_16x16x32_bf16 v[108:111], v[144:147], v[200:203], v[108:111]
	v_mfma_f32_16x16x32_bf16 v[96:99], v[152:155], v[200:203], v[96:99]
	v_mfma_f32_16x16x32_bf16 v[84:87], v[144:147], v[208:211], v[84:87]
	v_mfma_f32_16x16x32_bf16 v[76:79], v[152:155], v[208:211], v[76:79]
	v_mfma_f32_16x16x32_bf16 v[104:107], v[156:159], v[180:183], 0
	v_mfma_f32_16x16x32_bf16 v[100:103], v[172:175], v[180:183], 0
	v_mfma_f32_16x16x32_bf16 v[92:95], v[156:159], v[188:191], 0
	v_mfma_f32_16x16x32_bf16 v[88:91], v[172:175], v[188:191], 0
	v_mfma_f32_16x16x32_bf16 v[80:83], v[156:159], v[196:199], 0
	v_mfma_f32_16x16x32_bf16 v[72:75], v[172:175], v[196:199], 0
	v_mfma_f32_16x16x32_bf16 v[68:71], v[156:159], v[204:207], 0
	v_mfma_f32_16x16x32_bf16 v[64:67], v[172:175], v[204:207], 0
	v_mfma_f32_16x16x32_bf16 v[104:107], v[160:163], v[184:187], v[104:107]
	v_mfma_f32_16x16x32_bf16 v[100:103], v[176:179], v[184:187], v[100:103]
	v_mfma_f32_16x16x32_bf16 v[92:95], v[160:163], v[192:195], v[92:95]
	v_mfma_f32_16x16x32_bf16 v[88:91], v[176:179], v[192:195], v[88:91]
	v_mfma_f32_16x16x32_bf16 v[80:83], v[160:163], v[200:203], v[80:83]
	v_mfma_f32_16x16x32_bf16 v[72:75], v[176:179], v[200:203], v[72:75]
	v_mfma_f32_16x16x32_bf16 v[68:71], v[160:163], v[208:211], v[68:71]
	v_mfma_f32_16x16x32_bf16 v[64:67], v[176:179], v[208:211], v[64:67]
	s_barrier
	s_add_i32 s44, s61, s25
	s_mov_b32 m0, s44
	ds_read_b128 v[180:183], v171 offset:16384
	ds_read_b128 v[184:187], v171 offset:17408
	ds_read_b128 v[188:191], v171 offset:18432
	ds_read_b128 v[192:195], v171 offset:19456
	ds_read_b128 v[196:199], v171 offset:20480
	ds_read_b128 v[200:203], v171 offset:21504
	ds_read_b128 v[204:207], v171 offset:22528
	ds_read_b128 v[208:211], v171 offset:23552
	global_load_lds_dwordx4 v130, s[48:49]
	s_add_i32 m0, s44, 0x2000
	s_add_u32 s44, s48, 0x160000
	s_addc_u32 s45, s49, 0
	s_add_i32 s70, s62, s25
	global_load_lds_dwordx4 v134, s[48:49]
	s_mov_b32 m0, s70
	s_nop 0
	global_load_lds_dwordx4 v130, s[44:45]
	s_add_i32 m0, s70, 0x2000
	s_nop 0
	global_load_lds_dwordx4 v134, s[44:45]
	s_mov_b32 m0, s26
	s_nop 0
	global_load_lds_dwordx4 v128, s[50:51]
	s_mov_b32 m0, s27
	s_nop 0
	global_load_lds_dwordx4 v132, s[50:51]
	s_waitcnt vmcnt(8)
	s_waitcnt lgkmcnt(0)
	s_barrier
	s_waitcnt lgkmcnt(0)
	v_mfma_f32_16x16x32_bf16 v[60:63], v[140:143], v[180:183], 0
	v_mfma_f32_16x16x32_bf16 v[56:59], v[148:151], v[180:183], 0
	v_mfma_f32_16x16x32_bf16 v[52:55], v[140:143], v[188:191], 0
	v_mfma_f32_16x16x32_bf16 v[48:51], v[148:151], v[188:191], 0
	v_mfma_f32_16x16x32_bf16 v[44:47], v[140:143], v[196:199], 0
	v_mfma_f32_16x16x32_bf16 v[32:35], v[148:151], v[196:199], 0
	v_mfma_f32_16x16x32_bf16 v[20:23], v[140:143], v[204:207], 0
	v_mfma_f32_16x16x32_bf16 v[12:15], v[148:151], v[204:207], 0
	v_mfma_f32_16x16x32_bf16 v[60:63], v[144:147], v[184:187], v[60:63]
	v_mfma_f32_16x16x32_bf16 v[56:59], v[152:155], v[184:187], v[56:59]
	v_mfma_f32_16x16x32_bf16 v[52:55], v[144:147], v[192:195], v[52:55]
	v_mfma_f32_16x16x32_bf16 v[48:51], v[152:155], v[192:195], v[48:51]
	v_mfma_f32_16x16x32_bf16 v[44:47], v[144:147], v[200:203], v[44:47]
	v_mfma_f32_16x16x32_bf16 v[32:35], v[152:155], v[200:203], v[32:35]
	v_mfma_f32_16x16x32_bf16 v[20:23], v[144:147], v[208:211], v[20:23]
	v_mfma_f32_16x16x32_bf16 v[12:15], v[152:155], v[208:211], v[12:15]
	v_mfma_f32_16x16x32_bf16 v[40:43], v[156:159], v[180:183], 0
	v_mfma_f32_16x16x32_bf16 v[36:39], v[172:175], v[180:183], 0
	v_mfma_f32_16x16x32_bf16 v[28:31], v[156:159], v[188:191], 0
	v_mfma_f32_16x16x32_bf16 v[24:27], v[172:175], v[188:191], 0
	v_mfma_f32_16x16x32_bf16 v[16:19], v[156:159], v[196:199], 0
	v_mfma_f32_16x16x32_bf16 v[8:11], v[172:175], v[196:199], 0
	v_mfma_f32_16x16x32_bf16 v[4:7], v[156:159], v[204:207], 0
	v_mfma_f32_16x16x32_bf16 v[0:3], v[172:175], v[204:207], 0
	v_mfma_f32_16x16x32_bf16 v[40:43], v[160:163], v[184:187], v[40:43]
	v_mfma_f32_16x16x32_bf16 v[36:39], v[176:179], v[184:187], v[36:39]
	v_mfma_f32_16x16x32_bf16 v[28:31], v[160:163], v[192:195], v[28:31]
	v_mfma_f32_16x16x32_bf16 v[24:27], v[176:179], v[192:195], v[24:27]
	v_mfma_f32_16x16x32_bf16 v[16:19], v[160:163], v[200:203], v[16:19]
	v_mfma_f32_16x16x32_bf16 v[8:11], v[176:179], v[200:203], v[8:11]
	v_mfma_f32_16x16x32_bf16 v[4:7], v[160:163], v[208:211], v[4:7]
	v_mfma_f32_16x16x32_bf16 v[0:3], v[176:179], v[208:211], v[0:3]
	s_barrier
; #define PG8_STAGE(bufoff, gbase, voff) do { _Pragma("unroll") for (int _i = 0; _i < 2; ++_i) \
;         __builtin_amdgcn_global_load_lds((const unsigned*)((const char*)(gbase) + (voff)[_i]), (PG8_LAS unsigned*)(lds + (bufoff) + ldsw + _i * 8192), 16, 0, 0); } while (0)
; #define PG8_LDA(dst, b, h) do { _Pragma("unroll") for (int m = 0; m < 4; ++m) _Pragma("unroll") for (int k = 0; k < 2; ++k) dst[m][k] = *(const PG8_LAS bf16x8*)(lds + PG8_SA(b, h) + aoff + m * 2048 + k * 1024); } while (0)
; #define PG8_LDB(dst, b, h) do { _Pragma("unroll") for (int n = 0; n < 2; ++n) _Pragma("unroll") for (int k = 0; k < 2; ++k) dst[n][k] = *(const PG8_LAS bf16x8*)(lds + PG8_SB(b, h) + boff + n * 2048 + k * 1024); } while (0)
; #define PG8_MMA(ai, bj, At, Bt) do { __builtin_amdgcn_s_setprio(1); _Pragma("unroll") for (int m = 0; m < 4; ++m) _Pragma("unroll") for (int n = 0; n < 2; ++n) _Pragma("unroll") for (int k = 0; k < 2; ++k) \
;         acc[ai][bj][m][n] = __builtin_amdgcn_mfma_f32_16x16x32_bf16(Bt[n][k], At[m][k], acc[ai][bj][m][n], 0, 0, 0); __builtin_amdgcn_s_setprio(0); } while (0)
; #define PG8_WAIT_V(n) asm volatile("s_waitcnt vmcnt(" #n ")" ::: "memory")
; #define PG8_WAIT_L(n) asm volatile("s_waitcnt lgkmcnt(" #n ")" ::: "memory")
; #define PG8_BAR __builtin_amdgcn_s_barrier()
; #define PG8_SCHED __builtin_amdgcn_sched_barrier(0)
; template <class Epi, class Sched, bool ALIGN_EPI = false, bool SP2 = false>
; __device__ __forceinline__ void gemm_phase(PG8_LAS unsigned char* lds, const Gemm g, const Sched& S, const Epi& E) {
;     ...
;             PG8_WAIT_V(8); PG8_WAIT_L(0); PG8_BAR; PG8_MMA(1, 0, At, B0); PG8_MMA(1, 1, At, B1); PG8_BAR; PG8_SCHED;
;             PG8_LDB(B0, 1, 0); PG8_LDB(B1, 1, 1); PG8_SCHED; PG8_LDA(At, 1, 0); PG8_STAGE(PG8_SA(0, 1), a2 + hstep, voffA);
;             PG8_WAIT_V(8); PG8_WAIT_L(0); PG8_BAR; PG8_MMA(0, 0, At, B0); PG8_MMA(0, 1, At, B1); PG8_BAR; PG8_SCHED;
;             PG8_LDA(At, 1, 1); PG8_STAGE(PG8_SB(1, 0), b3, voffB); PG8_STAGE(PG8_SB(1, 1), b3 + hstep, voffB); PG8_STAGE(PG8_SA(1, 0), a3, voffA);
;             PG8_WAIT_V(8); PG8_WAIT_L(0); PG8_BAR; PG8_MMA(1, 0, At, B0); PG8_MMA(1, 1, At, B1); PG8_BAR; PG8_SCHED;
	s_add_i32 s70, 0, 0x18000
	s_add_i32 s71, 0, 0x1c000
	v_add_u32_e32 v152, s70, v167
	v_add_u32_e32 v176, s71, v167
	ds_read_b128 v[140:143], v152
	ds_read_b128 v[144:147], v152 offset:1024
	ds_read_b128 v[148:151], v152 offset:2048
	ds_read_b128 v[152:155], v152 offset:3072
	ds_read_b128 v[156:159], v176
	ds_read_b128 v[160:163], v176 offset:1024
	ds_read_b128 v[172:175], v176 offset:2048
	ds_read_b128 v[176:179], v176 offset:3072
	s_add_u32 s44, s50, 0x160000
	s_addc_u32 s45, s51, 0
	s_mov_b32 m0, s52
	ds_read_b128 v[180:183], v171 offset:32768
	ds_read_b128 v[184:187], v171 offset:33792
	ds_read_b128 v[188:191], v171 offset:34816
	ds_read_b128 v[192:195], v171 offset:35840
	ds_read_b128 v[196:199], v171 offset:36864
	ds_read_b128 v[200:203], v171 offset:37888
	ds_read_b128 v[204:207], v171 offset:38912
	ds_read_b128 v[208:211], v171 offset:39936
	global_load_lds_dwordx4 v128, s[44:45]
	s_mov_b32 m0, s53
	s_nop 0
	global_load_lds_dwordx4 v132, s[44:45]
	s_waitcnt vmcnt(8)
	s_waitcnt lgkmcnt(0)
	s_barrier
	s_waitcnt lgkmcnt(0)
	v_mfma_f32_16x16x32_bf16 v[124:127], v[140:143], v[180:183], v[124:127]
	v_mfma_f32_16x16x32_bf16 v[120:123], v[148:151], v[180:183], v[120:123]
	v_mfma_f32_16x16x32_bf16 v[116:119], v[140:143], v[188:191], v[116:119]
	v_mfma_f32_16x16x32_bf16 v[112:115], v[148:151], v[188:191], v[112:115]
	v_mfma_f32_16x16x32_bf16 v[108:111], v[140:143], v[196:199], v[108:111]
	v_mfma_f32_16x16x32_bf16 v[96:99], v[148:151], v[196:199], v[96:99]
	v_mfma_f32_16x16x32_bf16 v[84:87], v[140:143], v[204:207], v[84:87]
	v_mfma_f32_16x16x32_bf16 v[76:79], v[148:151], v[204:207], v[76:79]
	v_mfma_f32_16x16x32_bf16 v[124:127], v[144:147], v[184:187], v[124:127]
	v_mfma_f32_16x16x32_bf16 v[120:123], v[152:155], v[184:187], v[120:123]
	v_mfma_f32_16x16x32_bf16 v[116:119], v[144:147], v[192:195], v[116:119]
	v_mfma_f32_16x16x32_bf16 v[112:115], v[152:155], v[192:195], v[112:115]
	v_mfma_f32_16x16x32_bf16 v[108:111], v[144:147], v[200:203], v[108:111]
	v_mfma_f32_16x16x32_bf16 v[96:99], v[152:155], v[200:203], v[96:99]
	v_mfma_f32_16x16x32_bf16 v[84:87], v[144:147], v[208:211], v[84:87]
	v_mfma_f32_16x16x32_bf16 v[76:79], v[152:155], v[208:211], v[76:79]
	v_mfma_f32_16x16x32_bf16 v[104:107], v[156:159], v[180:183], v[104:107]
	v_mfma_f32_16x16x32_bf16 v[100:103], v[172:175], v[180:183], v[100:103]
	v_mfma_f32_16x16x32_bf16 v[92:95], v[156:159], v[188:191], v[92:95]
	v_mfma_f32_16x16x32_bf16 v[88:91], v[172:175], v[188:191], v[88:91]
	v_mfma_f32_16x16x32_bf16 v[80:83], v[156:159], v[196:199], v[80:83]
	v_mfma_f32_16x16x32_bf16 v[72:75], v[172:175], v[196:199], v[72:75]
	v_mfma_f32_16x16x32_bf16 v[68:71], v[156:159], v[204:207], v[68:71]
	v_mfma_f32_16x16x32_bf16 v[64:67], v[172:175], v[204:207], v[64:67]
	v_mfma_f32_16x16x32_bf16 v[104:107], v[160:163], v[184:187], v[104:107]
	v_mfma_f32_16x16x32_bf16 v[100:103], v[176:179], v[184:187], v[100:103]
	v_mfma_f32_16x16x32_bf16 v[92:95], v[160:163], v[192:195], v[92:95]
	v_mfma_f32_16x16x32_bf16 v[88:91], v[176:179], v[192:195], v[88:91]
	v_mfma_f32_16x16x32_bf16 v[80:83], v[160:163], v[200:203], v[80:83]
	v_mfma_f32_16x16x32_bf16 v[72:75], v[176:179], v[200:203], v[72:75]
	v_mfma_f32_16x16x32_bf16 v[68:71], v[160:163], v[208:211], v[68:71]
	v_mfma_f32_16x16x32_bf16 v[64:67], v[176:179], v[208:211], v[64:67]
	s_barrier
	s_add_i32 s44, s70, s25
	s_add_u32 s86, s48, 0x80
	s_addc_u32 s87, s49, 0
	s_mov_b32 m0, s44
	ds_read_b128 v[180:183], v171 offset:49152
	ds_read_b128 v[184:187], v171 offset:50176
	ds_read_b128 v[188:191], v171 offset:51200
	ds_read_b128 v[192:195], v171 offset:52224
	ds_read_b128 v[196:199], v171 offset:53248
	ds_read_b128 v[200:203], v171 offset:54272
	ds_read_b128 v[204:207], v171 offset:55296
	ds_read_b128 v[208:211], v171 offset:56320
	global_load_lds_dwordx4 v130, s[86:87]
	s_add_i32 m0, s44, 0x2000
	s_add_u32 s44, s48, 0x160080
	s_addc_u32 s45, s49, 0
	s_add_i32 s48, s71, s25
	global_load_lds_dwordx4 v134, s[86:87]
	s_mov_b32 m0, s48
	s_nop 0
	global_load_lds_dwordx4 v130, s[44:45]
	s_add_i32 m0, s48, 0x2000
	s_nop 0
	global_load_lds_dwordx4 v134, s[44:45]
	s_add_u32 s84, s50, 0x80
	s_addc_u32 s85, s51, 0
	s_mov_b32 m0, s57
	s_nop 0
	global_load_lds_dwordx4 v128, s[84:85]
	s_mov_b32 m0, s58
	s_nop 0
	global_load_lds_dwordx4 v132, s[84:85]
	s_waitcnt vmcnt(8)
	s_waitcnt lgkmcnt(0)
	s_barrier
	s_waitcnt lgkmcnt(0)
	v_mfma_f32_16x16x32_bf16 v[60:63], v[140:143], v[180:183], v[60:63]
	v_mfma_f32_16x16x32_bf16 v[56:59], v[148:151], v[180:183], v[56:59]
	v_mfma_f32_16x16x32_bf16 v[52:55], v[140:143], v[188:191], v[52:55]
	v_mfma_f32_16x16x32_bf16 v[48:51], v[148:151], v[188:191], v[48:51]
	v_mfma_f32_16x16x32_bf16 v[44:47], v[140:143], v[196:199], v[44:47]
	v_mfma_f32_16x16x32_bf16 v[32:35], v[148:151], v[196:199], v[32:35]
	v_mfma_f32_16x16x32_bf16 v[20:23], v[140:143], v[204:207], v[20:23]
	v_mfma_f32_16x16x32_bf16 v[12:15], v[148:151], v[204:207], v[12:15]
	v_mfma_f32_16x16x32_bf16 v[60:63], v[144:147], v[184:187], v[60:63]
	v_mfma_f32_16x16x32_bf16 v[56:59], v[152:155], v[184:187], v[56:59]
	v_mfma_f32_16x16x32_bf16 v[52:55], v[144:147], v[192:195], v[52:55]
	v_mfma_f32_16x16x32_bf16 v[48:51], v[152:155], v[192:195], v[48:51]
	v_mfma_f32_16x16x32_bf16 v[44:47], v[144:147], v[200:203], v[44:47]
	v_mfma_f32_16x16x32_bf16 v[32:35], v[152:155], v[200:203], v[32:35]
	v_mfma_f32_16x16x32_bf16 v[20:23], v[144:147], v[208:211], v[20:23]
	v_mfma_f32_16x16x32_bf16 v[12:15], v[152:155], v[208:211], v[12:15]
	v_mfma_f32_16x16x32_bf16 v[40:43], v[156:159], v[180:183], v[40:43]
	v_mfma_f32_16x16x32_bf16 v[36:39], v[172:175], v[180:183], v[36:39]
	v_mfma_f32_16x16x32_bf16 v[28:31], v[156:159], v[188:191], v[28:31]
	v_mfma_f32_16x16x32_bf16 v[24:27], v[172:175], v[188:191], v[24:27]
	v_mfma_f32_16x16x32_bf16 v[16:19], v[156:159], v[196:199], v[16:19]
	v_mfma_f32_16x16x32_bf16 v[8:11], v[172:175], v[196:199], v[8:11]
	v_mfma_f32_16x16x32_bf16 v[4:7], v[156:159], v[204:207], v[4:7]
	v_mfma_f32_16x16x32_bf16 v[0:3], v[172:175], v[204:207], v[0:3]
	v_mfma_f32_16x16x32_bf16 v[40:43], v[160:163], v[184:187], v[40:43]
	v_mfma_f32_16x16x32_bf16 v[36:39], v[176:179], v[184:187], v[36:39]
	v_mfma_f32_16x16x32_bf16 v[28:31], v[160:163], v[192:195], v[28:31]
	v_mfma_f32_16x16x32_bf16 v[24:27], v[176:179], v[192:195], v[24:27]
	v_mfma_f32_16x16x32_bf16 v[16:19], v[160:163], v[200:203], v[16:19]
	v_mfma_f32_16x16x32_bf16 v[8:11], v[176:179], v[200:203], v[8:11]
	v_mfma_f32_16x16x32_bf16 v[4:7], v[160:163], v[208:211], v[4:7]
	v_mfma_f32_16x16x32_bf16 v[0:3], v[176:179], v[208:211], v[0:3]
	s_barrier
	s_add_i32 s69, s69, 2
	s_add_u32 s67, s67, 0x100
	s_addc_u32 s68, s68, 0
	s_cmpk_gt_u32 s69, 0x55
	s_mov_b64 s[44:45], s[46:47]
	.p2align	6

; #define PG8_STAGE(bufoff, gbase, voff) do { _Pragma("unroll") for (int _i = 0; _i < 2; ++_i) \
;         __builtin_amdgcn_global_load_lds((const unsigned*)((const char*)(gbase) + (voff)[_i]), (PG8_LAS unsigned*)(lds + (bufoff) + ldsw + _i * 8192), 16, 0, 0); } while (0)
; #define PG8_LDA(dst, b, h) do { _Pragma("unroll") for (int m = 0; m < 4; ++m) _Pragma("unroll") for (int k = 0; k < 2; ++k) dst[m][k] = *(const PG8_LAS bf16x8*)(lds + PG8_SA(b, h) + aoff + m * 2048 + k * 1024); } while (0)
; #define PG8_LDB(dst, b, h) do { _Pragma("unroll") for (int n = 0; n < 2; ++n) _Pragma("unroll") for (int k = 0; k < 2; ++k) dst[n][k] = *(const PG8_LAS bf16x8*)(lds + PG8_SB(b, h) + boff + n * 2048 + k * 1024); } while (0)
; #define PG8_MMA(ai, bj, At, Bt) do { __builtin_amdgcn_s_setprio(1); _Pragma("unroll") for (int m = 0; m < 4; ++m) _Pragma("unroll") for (int n = 0; n < 2; ++n) _Pragma("unroll") for (int k = 0; k < 2; ++k) \
;         acc[ai][bj][m][n] = __builtin_amdgcn_mfma_f32_16x16x32_bf16(Bt[n][k], At[m][k], acc[ai][bj][m][n], 0, 0, 0); __builtin_amdgcn_s_setprio(0); } while (0)
; #define PG8_BAR __builtin_amdgcn_s_barrier()
; template <class Epi, class Sched, bool ALIGN_EPI = false, bool SP2 = false>
; __device__ __forceinline__ void gemm_phase(PG8_LAS unsigned char* lds, const Gemm g, const Sched& S, const Epi& E) {
;     ...
;         const bool has_next = S.next(ui + 1, nxt);
;         const char* nA = has_next ? (const char*)g.A + (size_t)nxt.pm * tstep : cA; const char* nB = has_next ? (const char*)g.Bt + (size_t)nxt.pn * tstep : cB;
;         for (int t = 0; t < nt; t += 2) {
;             const bool last = (t == nt - 2);
;             const char* a1 = cA + (size_t)(t + 1) * kstep;
;             const char* a2 = last ? nA : cA + (size_t)(t + 2) * kstep; const char* b2 = last ? nB : cB + (size_t)(t + 2) * kstep;
;             const char* a3 = a2 + kstep; const char* b3 = b2 + kstep;
;             if (last && has_next) S.a_ready(nxt);
;             if constexpr (SP2) {
;             PG8_LDB(B0, 0, 0); PG8_LDB(B1, 0, 1); PG8_SCHED; PG8_LDA(At, 0, 0); PG8_STAGE(PG8_SA(1, 1), a1 + hstep, voffA);
;             PG8_WAIT_V(8); PG8_WAIT_L(0); PG8_BAR; PG8_MMA(0, 0, At, B0); PG8_MMA(0, 1, At, B1); PG8_BAR; PG8_SCHED;
;             PG8_LDA(At, 0, 1); PG8_STAGE(PG8_SB(0, 0), b2, voffB); PG8_STAGE(PG8_SB(0, 1), b2 + hstep, voffB); PG8_STAGE(PG8_SA(0, 0), a2, voffA);
.LBB0_363:
	s_ashr_i32 s77, s76, 31
	s_lshl_b64 s[38:39], s[76:77], 20
	v_cmp_lt_i64_e32 vcc, s[78:79], v[178:179]
	s_add_u32 s78, s73, s38
	s_addc_u32 s79, s96, s39
	s_and_b64 s[38:39], vcc, exec
	s_cselect_b32 s77, s79, s85
	s_cselect_b32 s83, s78, s84
	s_ashr_i32 s75, s74, 31
	s_lshl_b64 s[38:39], s[74:75], 20
	s_add_u32 s80, s97, s38
	s_addc_u32 s81, s90, s39
	s_and_b64 s[38:39], vcc, exec
	s_cselect_b32 s75, s81, s87
	s_cselect_b32 vcc_lo, s80, s86
	s_add_u32 s84, s84, 0x80080
	s_addc_u32 s85, s85, 0
	s_add_u32 vcc_hi, s86, 0x100
	s_addc_u32 s38, s87, 0
	s_mov_b32 s39, -2
	ds_read_b128 v[128:131], v214
	ds_read_b128 v[132:135], v214 offset:1024
	ds_read_b128 v[136:139], v214 offset:2048
	ds_read_b128 v[140:143], v214 offset:3072
	ds_read_b128 v[144:147], v215
	ds_read_b128 v[148:151], v215 offset:1024
	ds_read_b128 v[152:155], v215 offset:2048
	ds_read_b128 v[156:159], v215 offset:3072
	s_add_u32 s58, s84, 0xfff80080
	s_addc_u32 s59, s85, -1
	s_cmp_eq_u32 s39, 28
	s_cselect_b32 s89, s77, s59
	s_cselect_b32 s88, s83, s58
	s_cselect_b32 s87, s75, s38
	s_cselect_b32 s86, vcc_lo, vcc_hi
	s_add_i32 m0, s7, 0xc000
	ds_read_b128 v[160:163], v216
	ds_read_b128 v[182:185], v216 offset:1024
	ds_read_b128 v[186:189], v216 offset:2048
	ds_read_b128 v[190:193], v216 offset:3072
	ds_read_b128 v[222:225], v216 offset:4096
	ds_read_b128 v[232:235], v216 offset:5120
	ds_read_b128 v[236:239], v216 offset:6144
	ds_read_b128 v[240:243], v216 offset:7168
	global_load_lds_dwordx4 v174, s[84:85]
	s_add_i32 m0, s7, 0xe000
	s_nop 0
	global_load_lds_dwordx4 v176, s[84:85]
	s_waitcnt vmcnt(8)
	s_waitcnt lgkmcnt(0)
	s_barrier
	s_waitcnt lgkmcnt(0)
	v_mfma_f32_16x16x32_bf16 v[124:127], v[128:131], v[160:163], 0
	v_mfma_f32_16x16x32_bf16 v[120:123], v[136:139], v[160:163], 0
	v_mfma_f32_16x16x32_bf16 v[116:119], v[128:131], v[186:189], 0
	v_mfma_f32_16x16x32_bf16 v[112:115], v[136:139], v[186:189], 0
	v_mfma_f32_16x16x32_bf16 v[100:103], v[128:131], v[222:225], 0
	v_mfma_f32_16x16x32_bf16 v[96:99], v[136:139], v[222:225], 0
	v_mfma_f32_16x16x32_bf16 v[84:87], v[128:131], v[236:239], 0
	v_mfma_f32_16x16x32_bf16 v[80:83], v[136:139], v[236:239], 0
	v_mfma_f32_16x16x32_bf16 v[124:127], v[132:135], v[182:185], v[124:127]
	v_mfma_f32_16x16x32_bf16 v[120:123], v[140:143], v[182:185], v[120:123]
	v_mfma_f32_16x16x32_bf16 v[116:119], v[132:135], v[190:193], v[116:119]
	v_mfma_f32_16x16x32_bf16 v[112:115], v[140:143], v[190:193], v[112:115]
	v_mfma_f32_16x16x32_bf16 v[100:103], v[132:135], v[232:235], v[100:103]
	v_mfma_f32_16x16x32_bf16 v[96:99], v[140:143], v[232:235], v[96:99]
	v_mfma_f32_16x16x32_bf16 v[84:87], v[132:135], v[240:243], v[84:87]
	v_mfma_f32_16x16x32_bf16 v[80:83], v[140:143], v[240:243], v[80:83]
	v_mfma_f32_16x16x32_bf16 v[108:111], v[144:147], v[160:163], 0
	v_mfma_f32_16x16x32_bf16 v[104:107], v[152:155], v[160:163], 0
	v_mfma_f32_16x16x32_bf16 v[92:95], v[144:147], v[186:189], 0
	v_mfma_f32_16x16x32_bf16 v[88:91], v[152:155], v[186:189], 0
	v_mfma_f32_16x16x32_bf16 v[76:79], v[144:147], v[222:225], 0
	v_mfma_f32_16x16x32_bf16 v[72:75], v[152:155], v[222:225], 0
	v_mfma_f32_16x16x32_bf16 v[68:71], v[144:147], v[236:239], 0
	v_mfma_f32_16x16x32_bf16 v[64:67], v[152:155], v[236:239], 0
	v_mfma_f32_16x16x32_bf16 v[108:111], v[148:151], v[182:185], v[108:111]
	v_mfma_f32_16x16x32_bf16 v[104:107], v[156:159], v[182:185], v[104:107]
	v_mfma_f32_16x16x32_bf16 v[92:95], v[148:151], v[190:193], v[92:95]
	v_mfma_f32_16x16x32_bf16 v[88:91], v[156:159], v[190:193], v[88:91]
	v_mfma_f32_16x16x32_bf16 v[76:79], v[148:151], v[232:235], v[76:79]
	v_mfma_f32_16x16x32_bf16 v[72:75], v[156:159], v[232:235], v[72:75]
	v_mfma_f32_16x16x32_bf16 v[68:71], v[148:151], v[240:243], v[68:71]
	v_mfma_f32_16x16x32_bf16 v[64:67], v[156:159], v[240:243], v[64:67]
	s_barrier
	s_add_i32 s58, s34, s24
	v_lshl_add_u64 v[194:195], s[86:87], 0, v[168:169]
	s_mov_b32 m0, s58
	ds_read_b128 v[160:163], v216 offset:16384
	ds_read_b128 v[182:185], v216 offset:17408
	ds_read_b128 v[186:189], v216 offset:18432
	ds_read_b128 v[190:193], v216 offset:19456
	ds_read_b128 v[222:225], v216 offset:20480
	ds_read_b128 v[232:235], v216 offset:21504
	ds_read_b128 v[236:239], v216 offset:22528
	ds_read_b128 v[240:243], v216 offset:23552
	global_load_lds_dwordx4 v168, s[86:87]
	s_add_i32 m0, s58, 0x2000
	s_add_u32 s58, s86, 0x80000
	v_lshl_add_u64 v[230:231], s[86:87], 0, v[164:165]
	s_addc_u32 s59, s87, 0
	s_add_i32 s48, s35, s24
	global_load_lds_dwordx4 v164, s[86:87]
	s_mov_b32 m0, s48
	v_lshl_add_u64 v[246:247], s[88:89], 0, v[166:167]
	global_load_lds_dwordx4 v168, s[58:59]
	s_add_i32 m0, s48, 0x2000
	s_nop 0
	global_load_lds_dwordx4 v164, s[58:59]
	v_lshl_add_u64 v[244:245], s[88:89], 0, v[170:171]
	s_mov_b32 m0, s7
	s_nop 0
	global_load_lds_dwordx4 v170, s[88:89]
	s_mov_b32 m0, s8
	s_nop 0
	global_load_lds_dwordx4 v166, s[88:89]
	s_waitcnt vmcnt(8)
	s_waitcnt lgkmcnt(0)
	s_barrier
; #define PG8_STAGE(bufoff, gbase, voff) do { _Pragma("unroll") for (int _i = 0; _i < 2; ++_i) \
;         __builtin_amdgcn_global_load_lds((const unsigned*)((const char*)(gbase) + (voff)[_i]), (PG8_LAS unsigned*)(lds + (bufoff) + ldsw + _i * 8192), 16, 0, 0); } while (0)
; #define PG8_LDA(dst, b, h) do { _Pragma("unroll") for (int m = 0; m < 4; ++m) _Pragma("unroll") for (int k = 0; k < 2; ++k) dst[m][k] = *(const PG8_LAS bf16x8*)(lds + PG8_SA(b, h) + aoff + m * 2048 + k * 1024); } while (0)
; #define PG8_LDB(dst, b, h) do { _Pragma("unroll") for (int n = 0; n < 2; ++n) _Pragma("unroll") for (int k = 0; k < 2; ++k) dst[n][k] = *(const PG8_LAS bf16x8*)(lds + PG8_SB(b, h) + boff + n * 2048 + k * 1024); } while (0)
; #define PG8_MMA(ai, bj, At, Bt) do { __builtin_amdgcn_s_setprio(1); _Pragma("unroll") for (int m = 0; m < 4; ++m) _Pragma("unroll") for (int n = 0; n < 2; ++n) _Pragma("unroll") for (int k = 0; k < 2; ++k) \
;         acc[ai][bj][m][n] = __builtin_amdgcn_mfma_f32_16x16x32_bf16(Bt[n][k], At[m][k], acc[ai][bj][m][n], 0, 0, 0); __builtin_amdgcn_s_setprio(0); } while (0)
; #define PG8_WAIT_V(n) asm volatile("s_waitcnt vmcnt(" #n ")" ::: "memory")
; #define PG8_WAIT_L(n) asm volatile("s_waitcnt lgkmcnt(" #n ")" ::: "memory")
; #define PG8_BAR __builtin_amdgcn_s_barrier()
; #define PG8_SCHED __builtin_amdgcn_sched_barrier(0)
; template <class Epi, class Sched, bool ALIGN_EPI = false, bool SP2 = false>
; __device__ __forceinline__ void gemm_phase(PG8_LAS unsigned char* lds, const Gemm g, const Sched& S, const Epi& E) {
;     ...
;             PG8_WAIT_V(8); PG8_WAIT_L(0); PG8_BAR; PG8_MMA(1, 0, At, B0); PG8_MMA(1, 1, At, B1); PG8_BAR; PG8_SCHED;
;             PG8_LDB(B0, 1, 0); PG8_LDB(B1, 1, 1); PG8_SCHED; PG8_LDA(At, 1, 0); PG8_STAGE(PG8_SA(0, 1), a2 + hstep, voffA);
;             PG8_WAIT_V(8); PG8_WAIT_L(0); PG8_BAR; PG8_MMA(0, 0, At, B0); PG8_MMA(0, 1, At, B1); PG8_BAR; PG8_SCHED;
	s_waitcnt lgkmcnt(0)
	v_mfma_f32_16x16x32_bf16 v[60:63], v[128:131], v[160:163], 0
	v_mfma_f32_16x16x32_bf16 v[56:59], v[136:139], v[160:163], 0
	v_mfma_f32_16x16x32_bf16 v[52:55], v[128:131], v[186:189], 0
	v_mfma_f32_16x16x32_bf16 v[48:51], v[136:139], v[186:189], 0
	v_mfma_f32_16x16x32_bf16 v[36:39], v[128:131], v[222:225], 0
	v_mfma_f32_16x16x32_bf16 v[32:35], v[136:139], v[222:225], 0
	v_mfma_f32_16x16x32_bf16 v[20:23], v[128:131], v[236:239], 0
	v_mfma_f32_16x16x32_bf16 v[16:19], v[136:139], v[236:239], 0
	v_mfma_f32_16x16x32_bf16 v[60:63], v[132:135], v[182:185], v[60:63]
	v_mfma_f32_16x16x32_bf16 v[56:59], v[140:143], v[182:185], v[56:59]
	v_mfma_f32_16x16x32_bf16 v[52:55], v[132:135], v[190:193], v[52:55]
	v_mfma_f32_16x16x32_bf16 v[48:51], v[140:143], v[190:193], v[48:51]
	v_mfma_f32_16x16x32_bf16 v[36:39], v[132:135], v[232:235], v[36:39]
	v_mfma_f32_16x16x32_bf16 v[32:35], v[140:143], v[232:235], v[32:35]
	v_mfma_f32_16x16x32_bf16 v[20:23], v[132:135], v[240:243], v[20:23]
	v_mfma_f32_16x16x32_bf16 v[16:19], v[140:143], v[240:243], v[16:19]
	v_mfma_f32_16x16x32_bf16 v[44:47], v[144:147], v[160:163], 0
	v_mfma_f32_16x16x32_bf16 v[40:43], v[152:155], v[160:163], 0
	v_mfma_f32_16x16x32_bf16 v[28:31], v[144:147], v[186:189], 0
	v_mfma_f32_16x16x32_bf16 v[24:27], v[152:155], v[186:189], 0
	v_mfma_f32_16x16x32_bf16 v[12:15], v[144:147], v[222:225], 0
	v_mfma_f32_16x16x32_bf16 v[8:11], v[152:155], v[222:225], 0
	v_mfma_f32_16x16x32_bf16 v[4:7], v[144:147], v[236:239], 0
	v_mfma_f32_16x16x32_bf16 v[0:3], v[152:155], v[236:239], 0
	v_mfma_f32_16x16x32_bf16 v[44:47], v[148:151], v[182:185], v[44:47]
	v_mfma_f32_16x16x32_bf16 v[40:43], v[156:159], v[182:185], v[40:43]
	v_mfma_f32_16x16x32_bf16 v[28:31], v[148:151], v[190:193], v[28:31]
	v_mfma_f32_16x16x32_bf16 v[24:27], v[156:159], v[190:193], v[24:27]
	v_mfma_f32_16x16x32_bf16 v[12:15], v[148:151], v[232:235], v[12:15]
	v_mfma_f32_16x16x32_bf16 v[8:11], v[156:159], v[232:235], v[8:11]
	v_mfma_f32_16x16x32_bf16 v[4:7], v[148:151], v[240:243], v[4:7]
	v_mfma_f32_16x16x32_bf16 v[0:3], v[156:159], v[240:243], v[0:3]
	s_barrier
	s_add_i32 s48, 0, 0x18000
	s_add_i32 s60, 0, 0x1c000
	v_add_u32_e32 v140, s48, v197
	v_add_u32_e32 v156, s60, v197
	ds_read_b128 v[128:131], v140
	ds_read_b128 v[132:135], v140 offset:1024
	ds_read_b128 v[136:139], v140 offset:2048
	ds_read_b128 v[140:143], v140 offset:3072
	ds_read_b128 v[144:147], v156
	ds_read_b128 v[148:151], v156 offset:1024
	ds_read_b128 v[152:155], v156 offset:2048
	ds_read_b128 v[156:159], v156 offset:3072
	s_add_u32 s58, s88, 0x80000
	s_addc_u32 s59, s89, 0
	s_mov_b32 m0, s9
	ds_read_b128 v[160:163], v216 offset:32768
	ds_read_b128 v[182:185], v216 offset:33792
	ds_read_b128 v[186:189], v216 offset:34816
	ds_read_b128 v[190:193], v216 offset:35840
	ds_read_b128 v[222:225], v216 offset:36864
	ds_read_b128 v[232:235], v216 offset:37888
	ds_read_b128 v[236:239], v216 offset:38912
	ds_read_b128 v[240:243], v216 offset:39936
	global_load_lds_dwordx4 v170, s[58:59]
	s_mov_b32 m0, s26
	s_nop 0
	global_load_lds_dwordx4 v166, s[58:59]
	s_waitcnt vmcnt(8)
	s_waitcnt lgkmcnt(0)
	s_barrier
	s_waitcnt lgkmcnt(0)
	v_mfma_f32_16x16x32_bf16 v[124:127], v[128:131], v[160:163], v[124:127]
	v_mfma_f32_16x16x32_bf16 v[120:123], v[136:139], v[160:163], v[120:123]
	v_mfma_f32_16x16x32_bf16 v[116:119], v[128:131], v[186:189], v[116:119]
	v_mfma_f32_16x16x32_bf16 v[112:115], v[136:139], v[186:189], v[112:115]
	v_mfma_f32_16x16x32_bf16 v[100:103], v[128:131], v[222:225], v[100:103]
	v_mfma_f32_16x16x32_bf16 v[96:99], v[136:139], v[222:225], v[96:99]
	v_mfma_f32_16x16x32_bf16 v[84:87], v[128:131], v[236:239], v[84:87]
	v_mfma_f32_16x16x32_bf16 v[80:83], v[136:139], v[236:239], v[80:83]
	v_mfma_f32_16x16x32_bf16 v[124:127], v[132:135], v[182:185], v[124:127]
	v_mfma_f32_16x16x32_bf16 v[120:123], v[140:143], v[182:185], v[120:123]
	v_mfma_f32_16x16x32_bf16 v[116:119], v[132:135], v[190:193], v[116:119]
	v_mfma_f32_16x16x32_bf16 v[112:115], v[140:143], v[190:193], v[112:115]
	v_mfma_f32_16x16x32_bf16 v[100:103], v[132:135], v[232:235], v[100:103]
	v_mfma_f32_16x16x32_bf16 v[96:99], v[140:143], v[232:235], v[96:99]
	v_mfma_f32_16x16x32_bf16 v[84:87], v[132:135], v[240:243], v[84:87]
	v_mfma_f32_16x16x32_bf16 v[80:83], v[140:143], v[240:243], v[80:83]
	v_mfma_f32_16x16x32_bf16 v[108:111], v[144:147], v[160:163], v[108:111]
	v_mfma_f32_16x16x32_bf16 v[104:107], v[152:155], v[160:163], v[104:107]
	v_mfma_f32_16x16x32_bf16 v[92:95], v[144:147], v[186:189], v[92:95]
	v_mfma_f32_16x16x32_bf16 v[88:91], v[152:155], v[186:189], v[88:91]
	v_mfma_f32_16x16x32_bf16 v[76:79], v[144:147], v[222:225], v[76:79]
	v_mfma_f32_16x16x32_bf16 v[72:75], v[152:155], v[222:225], v[72:75]
	v_mfma_f32_16x16x32_bf16 v[68:71], v[144:147], v[236:239], v[68:71]
	v_mfma_f32_16x16x32_bf16 v[64:67], v[152:155], v[236:239], v[64:67]
	v_mfma_f32_16x16x32_bf16 v[108:111], v[148:151], v[182:185], v[108:111]
	v_mfma_f32_16x16x32_bf16 v[104:107], v[156:159], v[182:185], v[104:107]
	v_mfma_f32_16x16x32_bf16 v[92:95], v[148:151], v[190:193], v[92:95]
	v_mfma_f32_16x16x32_bf16 v[88:91], v[156:159], v[190:193], v[88:91]
	v_mfma_f32_16x16x32_bf16 v[76:79], v[148:151], v[232:235], v[76:79]
	v_mfma_f32_16x16x32_bf16 v[72:75], v[156:159], v[232:235], v[72:75]
	v_mfma_f32_16x16x32_bf16 v[68:71], v[148:151], v[240:243], v[68:71]
	v_mfma_f32_16x16x32_bf16 v[64:67], v[156:159], v[240:243], v[64:67]
	s_barrier
; #define PG8_STAGE(bufoff, gbase, voff) do { _Pragma("unroll") for (int _i = 0; _i < 2; ++_i) \
;         __builtin_amdgcn_global_load_lds((const unsigned*)((const char*)(gbase) + (voff)[_i]), (PG8_LAS unsigned*)(lds + (bufoff) + ldsw + _i * 8192), 16, 0, 0); } while (0)
; #define PG8_LDA(dst, b, h) do { _Pragma("unroll") for (int m = 0; m < 4; ++m) _Pragma("unroll") for (int k = 0; k < 2; ++k) dst[m][k] = *(const PG8_LAS bf16x8*)(lds + PG8_SA(b, h) + aoff + m * 2048 + k * 1024); } while (0)
; #define PG8_MMA(ai, bj, At, Bt) do { __builtin_amdgcn_s_setprio(1); _Pragma("unroll") for (int m = 0; m < 4; ++m) _Pragma("unroll") for (int n = 0; n < 2; ++n) _Pragma("unroll") for (int k = 0; k < 2; ++k) \
;         acc[ai][bj][m][n] = __builtin_amdgcn_mfma_f32_16x16x32_bf16(Bt[n][k], At[m][k], acc[ai][bj][m][n], 0, 0, 0); __builtin_amdgcn_s_setprio(0); } while (0)
; #define PG8_WAIT_V(n) asm volatile("s_waitcnt vmcnt(" #n ")" ::: "memory")
; #define PG8_WAIT_L(n) asm volatile("s_waitcnt lgkmcnt(" #n ")" ::: "memory")
; #define PG8_BAR __builtin_amdgcn_s_barrier()
; #define PG8_SCHED __builtin_amdgcn_sched_barrier(0)
; template <class Epi, class Sched, bool ALIGN_EPI = false, bool SP2 = false>
; __device__ __forceinline__ void gemm_phase(PG8_LAS unsigned char* lds, const Gemm g, const Sched& S, const Epi& E) {
;     ...
;             PG8_LDA(At, 1, 1); PG8_STAGE(PG8_SB(1, 0), b3, voffB); PG8_STAGE(PG8_SB(1, 1), b3 + hstep, voffB); PG8_STAGE(PG8_SA(1, 0), a3, voffA);
;             PG8_WAIT_V(8); PG8_WAIT_L(0); PG8_BAR; PG8_MMA(1, 0, At, B0); PG8_MMA(1, 1, At, B1); PG8_BAR; PG8_SCHED;
	s_add_i32 s48, s48, s24
	v_lshl_add_u64 v[194:195], v[194:195], 0, s[54:55]
	s_mov_b32 m0, s48
	ds_read_b128 v[160:163], v216 offset:49152
	ds_read_b128 v[182:185], v216 offset:50176
	ds_read_b128 v[186:189], v216 offset:51200
	ds_read_b128 v[190:193], v216 offset:52224
	ds_read_b128 v[222:225], v216 offset:53248
	ds_read_b128 v[232:235], v216 offset:54272
	ds_read_b128 v[236:239], v216 offset:55296
	ds_read_b128 v[240:243], v216 offset:56320
	global_load_lds_dwordx4 v[194:195], off
	s_add_i32 m0, s48, 0x2000
	s_add_u32 s58, s86, 0x80080
	v_lshl_add_u64 v[194:195], v[230:231], 0, s[54:55]
	s_addc_u32 s59, s87, 0
	s_add_i32 s48, s60, s24
	global_load_lds_dwordx4 v[194:195], off
	s_mov_b32 m0, s48
	s_nop 0
	global_load_lds_dwordx4 v168, s[58:59]
	s_add_i32 m0, s48, 0x2000
	s_nop 0
	global_load_lds_dwordx4 v164, s[58:59]
	v_lshl_add_u64 v[194:195], v[244:245], 0, s[54:55]
	s_mov_b32 m0, s36
	s_nop 0
	global_load_lds_dwordx4 v[194:195], off
	v_lshl_add_u64 v[194:195], v[246:247], 0, s[54:55]
	s_mov_b32 m0, s37
	s_nop 0
	global_load_lds_dwordx4 v[194:195], off
	s_waitcnt vmcnt(8)
	s_waitcnt lgkmcnt(0)
	s_barrier
	s_waitcnt lgkmcnt(0)
	v_mfma_f32_16x16x32_bf16 v[60:63], v[128:131], v[160:163], v[60:63]
	v_mfma_f32_16x16x32_bf16 v[56:59], v[136:139], v[160:163], v[56:59]
	v_mfma_f32_16x16x32_bf16 v[52:55], v[128:131], v[186:189], v[52:55]
	v_mfma_f32_16x16x32_bf16 v[48:51], v[136:139], v[186:189], v[48:51]
	v_mfma_f32_16x16x32_bf16 v[36:39], v[128:131], v[222:225], v[36:39]
	v_mfma_f32_16x16x32_bf16 v[32:35], v[136:139], v[222:225], v[32:35]
	v_mfma_f32_16x16x32_bf16 v[20:23], v[128:131], v[236:239], v[20:23]
	v_mfma_f32_16x16x32_bf16 v[16:19], v[136:139], v[236:239], v[16:19]
	v_mfma_f32_16x16x32_bf16 v[60:63], v[132:135], v[182:185], v[60:63]
	v_mfma_f32_16x16x32_bf16 v[56:59], v[140:143], v[182:185], v[56:59]
	v_mfma_f32_16x16x32_bf16 v[52:55], v[132:135], v[190:193], v[52:55]
	v_mfma_f32_16x16x32_bf16 v[48:51], v[140:143], v[190:193], v[48:51]
	v_mfma_f32_16x16x32_bf16 v[36:39], v[132:135], v[232:235], v[36:39]
	v_mfma_f32_16x16x32_bf16 v[32:35], v[140:143], v[232:235], v[32:35]
	v_mfma_f32_16x16x32_bf16 v[20:23], v[132:135], v[240:243], v[20:23]
	v_mfma_f32_16x16x32_bf16 v[16:19], v[140:143], v[240:243], v[16:19]
	v_mfma_f32_16x16x32_bf16 v[44:47], v[144:147], v[160:163], v[44:47]
	v_mfma_f32_16x16x32_bf16 v[40:43], v[152:155], v[160:163], v[40:43]
	v_mfma_f32_16x16x32_bf16 v[28:31], v[144:147], v[186:189], v[28:31]
	v_mfma_f32_16x16x32_bf16 v[24:27], v[152:155], v[186:189], v[24:27]
	v_mfma_f32_16x16x32_bf16 v[12:15], v[144:147], v[222:225], v[12:15]
	v_mfma_f32_16x16x32_bf16 v[8:11], v[152:155], v[222:225], v[8:11]
	v_mfma_f32_16x16x32_bf16 v[4:7], v[144:147], v[236:239], v[4:7]
	v_mfma_f32_16x16x32_bf16 v[0:3], v[152:155], v[236:239], v[0:3]
	v_mfma_f32_16x16x32_bf16 v[44:47], v[148:151], v[182:185], v[44:47]
	v_mfma_f32_16x16x32_bf16 v[40:43], v[156:159], v[182:185], v[40:43]
	v_mfma_f32_16x16x32_bf16 v[28:31], v[148:151], v[190:193], v[28:31]
	v_mfma_f32_16x16x32_bf16 v[24:27], v[156:159], v[190:193], v[24:27]
	v_mfma_f32_16x16x32_bf16 v[12:15], v[148:151], v[232:235], v[12:15]
	v_mfma_f32_16x16x32_bf16 v[8:11], v[156:159], v[232:235], v[8:11]
	v_mfma_f32_16x16x32_bf16 v[4:7], v[148:151], v[240:243], v[4:7]
	v_mfma_f32_16x16x32_bf16 v[0:3], v[156:159], v[240:243], v[0:3]
	s_barrier
	s_add_i32 s39, s39, 2
	s_add_u32 s84, s84, 0x100
	s_addc_u32 s85, s85, 0
	s_add_u32 vcc_hi, vcc_hi, 0x100
	s_addc_u32 s38, s38, 0
	s_cmp_gt_u32 s39, 29
	.p2align	6

; #define PG8_STAGE(bufoff, gbase, voff) do { _Pragma("unroll") for (int _i = 0; _i < 2; ++_i) \
;         __builtin_amdgcn_global_load_lds((const unsigned*)((const char*)(gbase) + (voff)[_i]), (PG8_LAS unsigned*)(lds + (bufoff) + ldsw + _i * 8192), 16, 0, 0); } while (0)
; #define PG8_LDA(dst, b, h) do { _Pragma("unroll") for (int m = 0; m < 4; ++m) _Pragma("unroll") for (int k = 0; k < 2; ++k) dst[m][k] = *(const PG8_LAS bf16x8*)(lds + PG8_SA(b, h) + aoff + m * 2048 + k * 1024); } while (0)
; #define PG8_LDB(dst, b, h) do { _Pragma("unroll") for (int n = 0; n < 2; ++n) _Pragma("unroll") for (int k = 0; k < 2; ++k) dst[n][k] = *(const PG8_LAS bf16x8*)(lds + PG8_SB(b, h) + boff + n * 2048 + k * 1024); } while (0)
; #define PG8_MMA(ai, bj, At, Bt) do { __builtin_amdgcn_s_setprio(1); _Pragma("unroll") for (int m = 0; m < 4; ++m) _Pragma("unroll") for (int n = 0; n < 2; ++n) _Pragma("unroll") for (int k = 0; k < 2; ++k) \
;         acc[ai][bj][m][n] = __builtin_amdgcn_mfma_f32_16x16x32_bf16(Bt[n][k], At[m][k], acc[ai][bj][m][n], 0, 0, 0); __builtin_amdgcn_s_setprio(0); } while (0)
; #define PG8_BAR __builtin_amdgcn_s_barrier()
; template <class Epi, class Sched, bool ALIGN_EPI = false, bool SP2 = false>
; __device__ __forceinline__ void gemm_phase(PG8_LAS unsigned char* lds, const Gemm g, const Sched& S, const Epi& E) {
;     ...
;         const bool has_next = S.next(ui + 1, nxt);
;         const char* nA = has_next ? (const char*)g.A + (size_t)nxt.pm * tstep : cA; const char* nB = has_next ? (const char*)g.Bt + (size_t)nxt.pn * tstep : cB;
;         for (int t = 0; t < nt; t += 2) {
;             const bool last = (t == nt - 2);
;             const char* a1 = cA + (size_t)(t + 1) * kstep;
;             const char* a2 = last ? nA : cA + (size_t)(t + 2) * kstep; const char* b2 = last ? nB : cB + (size_t)(t + 2) * kstep;
;             const char* a3 = a2 + kstep; const char* b3 = b2 + kstep;
;             if (last && has_next) S.a_ready(nxt);
;             if constexpr (SP2) {
;             PG8_LDB(B0, 0, 0); PG8_LDB(B1, 0, 1); PG8_SCHED; PG8_LDA(At, 0, 0); PG8_STAGE(PG8_SA(1, 1), a1 + hstep, voffA);
;             PG8_WAIT_V(8); PG8_WAIT_L(0); PG8_BAR; PG8_MMA(0, 0, At, B0); PG8_MMA(0, 1, At, B1); PG8_BAR; PG8_SCHED;
;             PG8_LDA(At, 0, 1); PG8_STAGE(PG8_SB(0, 0), b2, voffB); PG8_STAGE(PG8_SB(0, 1), b2 + hstep, voffB); PG8_STAGE(PG8_SA(0, 0), a2, voffA);
.LBB0_734:
	s_ashr_i32 s39, s38, 31
	v_cmp_lt_i64_e32 vcc, s[40:41], v[140:141]
	s_lshl_b64 s[40:41], s[38:39], 19
	s_add_u32 s40, s9, s40
	s_addc_u32 s41, s22, s41
	s_and_b64 s[42:43], vcc, exec
	s_cselect_b32 s39, s41, s47
	s_cselect_b32 s65, s40, s46
	s_ashr_i32 s37, s36, 31
	s_lshl_b64 s[42:43], s[36:37], 19
	s_add_u32 s42, s23, s42
	s_addc_u32 s43, s52, s43
	s_and_b64 s[50:51], vcc, exec
	s_cselect_b32 s37, s43, s49
	s_cselect_b32 s66, s42, s48
	s_add_u32 s46, s46, 0x40080
	s_addc_u32 s47, s47, 0
	s_add_u32 s67, s48, 0x100
	s_addc_u32 s68, s49, 0
	s_mov_b32 s69, -2
	ds_read_b128 v[144:147], v155
	ds_read_b128 v[148:151], v155 offset:1024
	ds_read_b128 v[158:161], v155 offset:2048
	ds_read_b128 v[162:165], v155 offset:3072
	ds_read_b128 v[166:169], v156
	ds_read_b128 v[170:173], v156 offset:1024
	ds_read_b128 v[174:177], v156 offset:2048
	ds_read_b128 v[178:181], v156 offset:3072
	s_add_u32 s48, s46, 0xfffc0080
	s_addc_u32 s49, s47, -1
	s_cmp_eq_u32 s69, 12
	s_cselect_b32 s51, s39, s49
	s_cselect_b32 s50, s65, s48
	s_cselect_b32 s49, s37, s68
	s_cselect_b32 s48, s66, s67
	s_add_i32 m0, s45, 0xc000
	ds_read_b128 v[182:185], v157
	ds_read_b128 v[186:189], v157 offset:1024
	ds_read_b128 v[190:193], v157 offset:2048
	ds_read_b128 v[194:197], v157 offset:3072
	ds_read_b128 v[198:201], v157 offset:4096
	ds_read_b128 v[202:205], v157 offset:5120
	ds_read_b128 v[206:209], v157 offset:6144
	ds_read_b128 v[214:217], v157 offset:7168
	global_load_lds_dwordx4 v136, s[46:47]
	s_add_i32 m0, s45, 0xe000
	s_nop 0
	global_load_lds_dwordx4 v138, s[46:47]
	s_waitcnt vmcnt(8)
	s_waitcnt lgkmcnt(0)
	s_barrier
	s_waitcnt lgkmcnt(0)
	v_mfma_f32_16x16x32_bf16 v[124:127], v[144:147], v[182:185], 0
	v_mfma_f32_16x16x32_bf16 v[120:123], v[158:161], v[182:185], 0
	v_mfma_f32_16x16x32_bf16 v[116:119], v[144:147], v[190:193], 0
	v_mfma_f32_16x16x32_bf16 v[112:115], v[158:161], v[190:193], 0
	v_mfma_f32_16x16x32_bf16 v[96:99], v[144:147], v[198:201], 0
	v_mfma_f32_16x16x32_bf16 v[88:91], v[158:161], v[198:201], 0
	v_mfma_f32_16x16x32_bf16 v[80:83], v[144:147], v[206:209], 0
	v_mfma_f32_16x16x32_bf16 v[72:75], v[158:161], v[206:209], 0
	v_mfma_f32_16x16x32_bf16 v[124:127], v[148:151], v[186:189], v[124:127]
	v_mfma_f32_16x16x32_bf16 v[120:123], v[162:165], v[186:189], v[120:123]
	v_mfma_f32_16x16x32_bf16 v[116:119], v[148:151], v[194:197], v[116:119]
	v_mfma_f32_16x16x32_bf16 v[112:115], v[162:165], v[194:197], v[112:115]
	v_mfma_f32_16x16x32_bf16 v[96:99], v[148:151], v[202:205], v[96:99]
	v_mfma_f32_16x16x32_bf16 v[88:91], v[162:165], v[202:205], v[88:91]
	v_mfma_f32_16x16x32_bf16 v[80:83], v[148:151], v[214:217], v[80:83]
	v_mfma_f32_16x16x32_bf16 v[72:75], v[162:165], v[214:217], v[72:75]
	v_mfma_f32_16x16x32_bf16 v[108:111], v[166:169], v[182:185], 0
	v_mfma_f32_16x16x32_bf16 v[104:107], v[174:177], v[182:185], 0
	v_mfma_f32_16x16x32_bf16 v[100:103], v[166:169], v[190:193], 0
	v_mfma_f32_16x16x32_bf16 v[92:95], v[174:177], v[190:193], 0
	v_mfma_f32_16x16x32_bf16 v[84:87], v[166:169], v[198:201], 0
	v_mfma_f32_16x16x32_bf16 v[76:79], v[174:177], v[198:201], 0
	v_mfma_f32_16x16x32_bf16 v[68:71], v[166:169], v[206:209], 0
	v_mfma_f32_16x16x32_bf16 v[64:67], v[174:177], v[206:209], 0
	v_mfma_f32_16x16x32_bf16 v[108:111], v[170:173], v[186:189], v[108:111]
	v_mfma_f32_16x16x32_bf16 v[104:107], v[178:181], v[186:189], v[104:107]
	v_mfma_f32_16x16x32_bf16 v[100:103], v[170:173], v[194:197], v[100:103]
	v_mfma_f32_16x16x32_bf16 v[92:95], v[178:181], v[194:197], v[92:95]
	v_mfma_f32_16x16x32_bf16 v[84:87], v[170:173], v[202:205], v[84:87]
	v_mfma_f32_16x16x32_bf16 v[76:79], v[178:181], v[202:205], v[76:79]
	v_mfma_f32_16x16x32_bf16 v[68:71], v[170:173], v[214:217], v[68:71]
	v_mfma_f32_16x16x32_bf16 v[64:67], v[178:181], v[214:217], v[64:67]
	s_barrier
	s_add_i32 s70, s62, s53
	s_mov_b32 m0, s70
	ds_read_b128 v[182:185], v157 offset:16384
	ds_read_b128 v[186:189], v157 offset:17408
	ds_read_b128 v[190:193], v157 offset:18432
	ds_read_b128 v[194:197], v157 offset:19456
	ds_read_b128 v[198:201], v157 offset:20480
	ds_read_b128 v[202:205], v157 offset:21504
	ds_read_b128 v[206:209], v157 offset:22528
	ds_read_b128 v[214:217], v157 offset:23552
	global_load_lds_dwordx4 v130, s[48:49]
	s_add_i32 m0, s70, 0x2000
	s_add_u32 s70, s48, 0x40000
	s_addc_u32 s71, s49, 0
	s_add_i32 s72, s63, s53
	global_load_lds_dwordx4 v134, s[48:49]
	s_mov_b32 m0, s72
	s_nop 0
	global_load_lds_dwordx4 v130, s[70:71]
	s_add_i32 m0, s72, 0x2000
	s_nop 0
	global_load_lds_dwordx4 v134, s[70:71]
	s_mov_b32 m0, s45
	s_nop 0
	global_load_lds_dwordx4 v128, s[50:51]
	s_mov_b32 m0, s54
	s_nop 0
	global_load_lds_dwordx4 v132, s[50:51]
	s_waitcnt vmcnt(8)
	s_waitcnt lgkmcnt(0)
	s_barrier
; #define PG8_STAGE(bufoff, gbase, voff) do { _Pragma("unroll") for (int _i = 0; _i < 2; ++_i) \
;         __builtin_amdgcn_global_load_lds((const unsigned*)((const char*)(gbase) + (voff)[_i]), (PG8_LAS unsigned*)(lds + (bufoff) + ldsw + _i * 8192), 16, 0, 0); } while (0)
; #define PG8_LDA(dst, b, h) do { _Pragma("unroll") for (int m = 0; m < 4; ++m) _Pragma("unroll") for (int k = 0; k < 2; ++k) dst[m][k] = *(const PG8_LAS bf16x8*)(lds + PG8_SA(b, h) + aoff + m * 2048 + k * 1024); } while (0)
; #define PG8_LDB(dst, b, h) do { _Pragma("unroll") for (int n = 0; n < 2; ++n) _Pragma("unroll") for (int k = 0; k < 2; ++k) dst[n][k] = *(const PG8_LAS bf16x8*)(lds + PG8_SB(b, h) + boff + n * 2048 + k * 1024); } while (0)
; #define PG8_MMA(ai, bj, At, Bt) do { __builtin_amdgcn_s_setprio(1); _Pragma("unroll") for (int m = 0; m < 4; ++m) _Pragma("unroll") for (int n = 0; n < 2; ++n) _Pragma("unroll") for (int k = 0; k < 2; ++k) \
;         acc[ai][bj][m][n] = __builtin_amdgcn_mfma_f32_16x16x32_bf16(Bt[n][k], At[m][k], acc[ai][bj][m][n], 0, 0, 0); __builtin_amdgcn_s_setprio(0); } while (0)
; #define PG8_WAIT_V(n) asm volatile("s_waitcnt vmcnt(" #n ")" ::: "memory")
; #define PG8_WAIT_L(n) asm volatile("s_waitcnt lgkmcnt(" #n ")" ::: "memory")
; #define PG8_BAR __builtin_amdgcn_s_barrier()
; #define PG8_SCHED __builtin_amdgcn_sched_barrier(0)
; template <class Epi, class Sched, bool ALIGN_EPI = false, bool SP2 = false>
; __device__ __forceinline__ void gemm_phase(PG8_LAS unsigned char* lds, const Gemm g, const Sched& S, const Epi& E) {
;     ...
;             PG8_WAIT_V(8); PG8_WAIT_L(0); PG8_BAR; PG8_MMA(1, 0, At, B0); PG8_MMA(1, 1, At, B1); PG8_BAR; PG8_SCHED;
;             PG8_LDB(B0, 1, 0); PG8_LDB(B1, 1, 1); PG8_SCHED; PG8_LDA(At, 1, 0); PG8_STAGE(PG8_SA(0, 1), a2 + hstep, voffA);
;             PG8_WAIT_V(8); PG8_WAIT_L(0); PG8_BAR; PG8_MMA(0, 0, At, B0); PG8_MMA(0, 1, At, B1); PG8_BAR; PG8_SCHED;
	s_waitcnt lgkmcnt(0)
	v_mfma_f32_16x16x32_bf16 v[60:63], v[144:147], v[182:185], 0
	v_mfma_f32_16x16x32_bf16 v[56:59], v[158:161], v[182:185], 0
	v_mfma_f32_16x16x32_bf16 v[48:51], v[144:147], v[190:193], 0
	v_mfma_f32_16x16x32_bf16 v[40:43], v[158:161], v[190:193], 0
	v_mfma_f32_16x16x32_bf16 v[32:35], v[144:147], v[198:201], 0
	v_mfma_f32_16x16x32_bf16 v[24:27], v[158:161], v[198:201], 0
	v_mfma_f32_16x16x32_bf16 v[16:19], v[144:147], v[206:209], 0
	v_mfma_f32_16x16x32_bf16 v[8:11], v[158:161], v[206:209], 0
	v_mfma_f32_16x16x32_bf16 v[60:63], v[148:151], v[186:189], v[60:63]
	v_mfma_f32_16x16x32_bf16 v[56:59], v[162:165], v[186:189], v[56:59]
	v_mfma_f32_16x16x32_bf16 v[48:51], v[148:151], v[194:197], v[48:51]
	v_mfma_f32_16x16x32_bf16 v[40:43], v[162:165], v[194:197], v[40:43]
	v_mfma_f32_16x16x32_bf16 v[32:35], v[148:151], v[202:205], v[32:35]
	v_mfma_f32_16x16x32_bf16 v[24:27], v[162:165], v[202:205], v[24:27]
	v_mfma_f32_16x16x32_bf16 v[16:19], v[148:151], v[214:217], v[16:19]
	v_mfma_f32_16x16x32_bf16 v[8:11], v[162:165], v[214:217], v[8:11]
	v_mfma_f32_16x16x32_bf16 v[52:55], v[166:169], v[182:185], 0
	v_mfma_f32_16x16x32_bf16 v[44:47], v[174:177], v[182:185], 0
	v_mfma_f32_16x16x32_bf16 v[36:39], v[166:169], v[190:193], 0
	v_mfma_f32_16x16x32_bf16 v[28:31], v[174:177], v[190:193], 0
	v_mfma_f32_16x16x32_bf16 v[20:23], v[166:169], v[198:201], 0
	v_mfma_f32_16x16x32_bf16 v[12:15], v[174:177], v[198:201], 0
	v_mfma_f32_16x16x32_bf16 v[4:7], v[166:169], v[206:209], 0
	v_mfma_f32_16x16x32_bf16 v[0:3], v[174:177], v[206:209], 0
	v_mfma_f32_16x16x32_bf16 v[52:55], v[170:173], v[186:189], v[52:55]
	v_mfma_f32_16x16x32_bf16 v[44:47], v[178:181], v[186:189], v[44:47]
	v_mfma_f32_16x16x32_bf16 v[36:39], v[170:173], v[194:197], v[36:39]
	v_mfma_f32_16x16x32_bf16 v[28:31], v[178:181], v[194:197], v[28:31]
	v_mfma_f32_16x16x32_bf16 v[20:23], v[170:173], v[202:205], v[20:23]
	v_mfma_f32_16x16x32_bf16 v[12:15], v[178:181], v[202:205], v[12:15]
	v_mfma_f32_16x16x32_bf16 v[4:7], v[170:173], v[214:217], v[4:7]
	v_mfma_f32_16x16x32_bf16 v[0:3], v[178:181], v[214:217], v[0:3]
	s_barrier
	s_add_i32 s70, 0, 0x18000
	s_add_i32 s71, 0, 0x1c000
	v_add_u32_e32 v162, s70, v153
	v_add_u32_e32 v178, s71, v153
	ds_read_b128 v[144:147], v162
	ds_read_b128 v[148:151], v162 offset:1024
	ds_read_b128 v[158:161], v162 offset:2048
	ds_read_b128 v[162:165], v162 offset:3072
	ds_read_b128 v[166:169], v178
	ds_read_b128 v[170:173], v178 offset:1024
	ds_read_b128 v[174:177], v178 offset:2048
	ds_read_b128 v[178:181], v178 offset:3072
	s_add_u32 s80, s50, 0x80
	s_addc_u32 s81, s51, 0
	s_add_u32 s50, s50, 0x40000
	s_addc_u32 s51, s51, 0
	s_mov_b32 m0, s55
	ds_read_b128 v[182:185], v157 offset:32768
	ds_read_b128 v[186:189], v157 offset:33792
	ds_read_b128 v[190:193], v157 offset:34816
	ds_read_b128 v[194:197], v157 offset:35840
	ds_read_b128 v[198:201], v157 offset:36864
	ds_read_b128 v[202:205], v157 offset:37888
	ds_read_b128 v[206:209], v157 offset:38912
	ds_read_b128 v[214:217], v157 offset:39936
	global_load_lds_dwordx4 v128, s[50:51]
	s_mov_b32 m0, s56
	s_nop 0
	global_load_lds_dwordx4 v132, s[50:51]
	s_waitcnt vmcnt(8)
	s_waitcnt lgkmcnt(0)
	s_barrier
	s_waitcnt lgkmcnt(0)
	v_mfma_f32_16x16x32_bf16 v[124:127], v[144:147], v[182:185], v[124:127]
	v_mfma_f32_16x16x32_bf16 v[120:123], v[158:161], v[182:185], v[120:123]
	v_mfma_f32_16x16x32_bf16 v[116:119], v[144:147], v[190:193], v[116:119]
	v_mfma_f32_16x16x32_bf16 v[112:115], v[158:161], v[190:193], v[112:115]
	v_mfma_f32_16x16x32_bf16 v[96:99], v[144:147], v[198:201], v[96:99]
	v_mfma_f32_16x16x32_bf16 v[88:91], v[158:161], v[198:201], v[88:91]
	v_mfma_f32_16x16x32_bf16 v[80:83], v[144:147], v[206:209], v[80:83]
	v_mfma_f32_16x16x32_bf16 v[72:75], v[158:161], v[206:209], v[72:75]
	v_mfma_f32_16x16x32_bf16 v[124:127], v[148:151], v[186:189], v[124:127]
	v_mfma_f32_16x16x32_bf16 v[120:123], v[162:165], v[186:189], v[120:123]
	v_mfma_f32_16x16x32_bf16 v[116:119], v[148:151], v[194:197], v[116:119]
	v_mfma_f32_16x16x32_bf16 v[112:115], v[162:165], v[194:197], v[112:115]
	v_mfma_f32_16x16x32_bf16 v[96:99], v[148:151], v[202:205], v[96:99]
	v_mfma_f32_16x16x32_bf16 v[88:91], v[162:165], v[202:205], v[88:91]
	v_mfma_f32_16x16x32_bf16 v[80:83], v[148:151], v[214:217], v[80:83]
	v_mfma_f32_16x16x32_bf16 v[72:75], v[162:165], v[214:217], v[72:75]
	v_mfma_f32_16x16x32_bf16 v[108:111], v[166:169], v[182:185], v[108:111]
	v_mfma_f32_16x16x32_bf16 v[104:107], v[174:177], v[182:185], v[104:107]
	v_mfma_f32_16x16x32_bf16 v[100:103], v[166:169], v[190:193], v[100:103]
	v_mfma_f32_16x16x32_bf16 v[92:95], v[174:177], v[190:193], v[92:95]
	v_mfma_f32_16x16x32_bf16 v[84:87], v[166:169], v[198:201], v[84:87]
	v_mfma_f32_16x16x32_bf16 v[76:79], v[174:177], v[198:201], v[76:79]
	v_mfma_f32_16x16x32_bf16 v[68:71], v[166:169], v[206:209], v[68:71]
	v_mfma_f32_16x16x32_bf16 v[64:67], v[174:177], v[206:209], v[64:67]
	v_mfma_f32_16x16x32_bf16 v[108:111], v[170:173], v[186:189], v[108:111]
	v_mfma_f32_16x16x32_bf16 v[104:107], v[178:181], v[186:189], v[104:107]
	v_mfma_f32_16x16x32_bf16 v[100:103], v[170:173], v[194:197], v[100:103]
	v_mfma_f32_16x16x32_bf16 v[92:95], v[178:181], v[194:197], v[92:95]
	v_mfma_f32_16x16x32_bf16 v[84:87], v[170:173], v[202:205], v[84:87]
	v_mfma_f32_16x16x32_bf16 v[76:79], v[178:181], v[202:205], v[76:79]
	v_mfma_f32_16x16x32_bf16 v[68:71], v[170:173], v[214:217], v[68:71]
	v_mfma_f32_16x16x32_bf16 v[64:67], v[178:181], v[214:217], v[64:67]
	s_barrier
; #define PG8_STAGE(bufoff, gbase, voff) do { _Pragma("unroll") for (int _i = 0; _i < 2; ++_i) \
;         __builtin_amdgcn_global_load_lds((const unsigned*)((const char*)(gbase) + (voff)[_i]), (PG8_LAS unsigned*)(lds + (bufoff) + ldsw + _i * 8192), 16, 0, 0); } while (0)
; #define PG8_LDA(dst, b, h) do { _Pragma("unroll") for (int m = 0; m < 4; ++m) _Pragma("unroll") for (int k = 0; k < 2; ++k) dst[m][k] = *(const PG8_LAS bf16x8*)(lds + PG8_SA(b, h) + aoff + m * 2048 + k * 1024); } while (0)
; #define PG8_MMA(ai, bj, At, Bt) do { __builtin_amdgcn_s_setprio(1); _Pragma("unroll") for (int m = 0; m < 4; ++m) _Pragma("unroll") for (int n = 0; n < 2; ++n) _Pragma("unroll") for (int k = 0; k < 2; ++k) \
;         acc[ai][bj][m][n] = __builtin_amdgcn_mfma_f32_16x16x32_bf16(Bt[n][k], At[m][k], acc[ai][bj][m][n], 0, 0, 0); __builtin_amdgcn_s_setprio(0); } while (0)
; #define PG8_WAIT_V(n) asm volatile("s_waitcnt vmcnt(" #n ")" ::: "memory")
; #define PG8_WAIT_L(n) asm volatile("s_waitcnt lgkmcnt(" #n ")" ::: "memory")
; #define PG8_BAR __builtin_amdgcn_s_barrier()
; #define PG8_SCHED __builtin_amdgcn_sched_barrier(0)
; template <class Epi, class Sched, bool ALIGN_EPI = false, bool SP2 = false>
; __device__ __forceinline__ void gemm_phase(PG8_LAS unsigned char* lds, const Gemm g, const Sched& S, const Epi& E) {
;     ...
;             PG8_LDA(At, 1, 1); PG8_STAGE(PG8_SB(1, 0), b3, voffB); PG8_STAGE(PG8_SB(1, 1), b3 + hstep, voffB); PG8_STAGE(PG8_SA(1, 0), a3, voffA);
;             PG8_WAIT_V(8); PG8_WAIT_L(0); PG8_BAR; PG8_MMA(1, 0, At, B0); PG8_MMA(1, 1, At, B1); PG8_BAR; PG8_SCHED;
	s_add_i32 s50, s70, s53
	s_add_u32 s82, s48, 0x80
	s_addc_u32 s83, s49, 0
	s_mov_b32 m0, s50
	ds_read_b128 v[182:185], v157 offset:49152
	ds_read_b128 v[186:189], v157 offset:50176
	ds_read_b128 v[190:193], v157 offset:51200
	ds_read_b128 v[194:197], v157 offset:52224
	ds_read_b128 v[198:201], v157 offset:53248
	ds_read_b128 v[202:205], v157 offset:54272
	ds_read_b128 v[206:209], v157 offset:55296
	ds_read_b128 v[214:217], v157 offset:56320
	global_load_lds_dwordx4 v130, s[82:83]
	s_add_i32 m0, s50, 0x2000
	s_add_u32 s48, s48, 0x40080
	s_addc_u32 s49, s49, 0
	s_add_i32 s50, s71, s53
	global_load_lds_dwordx4 v134, s[82:83]
	s_mov_b32 m0, s50
	s_nop 0
	global_load_lds_dwordx4 v130, s[48:49]
	s_add_i32 m0, s50, 0x2000
	s_nop 0
	global_load_lds_dwordx4 v134, s[48:49]
	s_mov_b32 m0, s58
	s_nop 0
	global_load_lds_dwordx4 v128, s[80:81]
	s_mov_b32 m0, s59
	s_nop 0
	global_load_lds_dwordx4 v132, s[80:81]
	s_waitcnt vmcnt(8)
	s_waitcnt lgkmcnt(0)
	s_barrier
	s_waitcnt lgkmcnt(0)
	v_mfma_f32_16x16x32_bf16 v[60:63], v[144:147], v[182:185], v[60:63]
	v_mfma_f32_16x16x32_bf16 v[56:59], v[158:161], v[182:185], v[56:59]
	v_mfma_f32_16x16x32_bf16 v[48:51], v[144:147], v[190:193], v[48:51]
	v_mfma_f32_16x16x32_bf16 v[40:43], v[158:161], v[190:193], v[40:43]
	v_mfma_f32_16x16x32_bf16 v[32:35], v[144:147], v[198:201], v[32:35]
	v_mfma_f32_16x16x32_bf16 v[24:27], v[158:161], v[198:201], v[24:27]
	v_mfma_f32_16x16x32_bf16 v[16:19], v[144:147], v[206:209], v[16:19]
	v_mfma_f32_16x16x32_bf16 v[8:11], v[158:161], v[206:209], v[8:11]
	v_mfma_f32_16x16x32_bf16 v[60:63], v[148:151], v[186:189], v[60:63]
	v_mfma_f32_16x16x32_bf16 v[56:59], v[162:165], v[186:189], v[56:59]
	v_mfma_f32_16x16x32_bf16 v[48:51], v[148:151], v[194:197], v[48:51]
	v_mfma_f32_16x16x32_bf16 v[40:43], v[162:165], v[194:197], v[40:43]
	v_mfma_f32_16x16x32_bf16 v[32:35], v[148:151], v[202:205], v[32:35]
	v_mfma_f32_16x16x32_bf16 v[24:27], v[162:165], v[202:205], v[24:27]
	v_mfma_f32_16x16x32_bf16 v[16:19], v[148:151], v[214:217], v[16:19]
	v_mfma_f32_16x16x32_bf16 v[8:11], v[162:165], v[214:217], v[8:11]
	v_mfma_f32_16x16x32_bf16 v[52:55], v[166:169], v[182:185], v[52:55]
	v_mfma_f32_16x16x32_bf16 v[44:47], v[174:177], v[182:185], v[44:47]
	v_mfma_f32_16x16x32_bf16 v[36:39], v[166:169], v[190:193], v[36:39]
	v_mfma_f32_16x16x32_bf16 v[28:31], v[174:177], v[190:193], v[28:31]
	v_mfma_f32_16x16x32_bf16 v[20:23], v[166:169], v[198:201], v[20:23]
	v_mfma_f32_16x16x32_bf16 v[12:15], v[174:177], v[198:201], v[12:15]
	v_mfma_f32_16x16x32_bf16 v[4:7], v[166:169], v[206:209], v[4:7]
	v_mfma_f32_16x16x32_bf16 v[0:3], v[174:177], v[206:209], v[0:3]
	v_mfma_f32_16x16x32_bf16 v[52:55], v[170:173], v[186:189], v[52:55]
	v_mfma_f32_16x16x32_bf16 v[44:47], v[178:181], v[186:189], v[44:47]
	v_mfma_f32_16x16x32_bf16 v[36:39], v[170:173], v[194:197], v[36:39]
	v_mfma_f32_16x16x32_bf16 v[28:31], v[178:181], v[194:197], v[28:31]
	v_mfma_f32_16x16x32_bf16 v[20:23], v[170:173], v[202:205], v[20:23]
	v_mfma_f32_16x16x32_bf16 v[12:15], v[178:181], v[202:205], v[12:15]
	v_mfma_f32_16x16x32_bf16 v[4:7], v[170:173], v[214:217], v[4:7]
	v_mfma_f32_16x16x32_bf16 v[0:3], v[178:181], v[214:217], v[0:3]
	s_barrier
	s_add_i32 s69, s69, 2
	s_add_u32 s46, s46, 0x100
	s_addc_u32 s47, s47, 0
	s_add_u32 s67, s67, 0x100
	s_addc_u32 s68, s68, 0
	s_cmp_gt_u32 s69, 13
	.p2align	6

; #define PG8_STAGE(bufoff, gbase, voff) do { _Pragma("unroll") for (int _i = 0; _i < 2; ++_i) \
;         __builtin_amdgcn_global_load_lds((const unsigned*)((const char*)(gbase) + (voff)[_i]), (PG8_LAS unsigned*)(lds + (bufoff) + ldsw + _i * 8192), 16, 0, 0); } while (0)
; #define PG8_LDA(dst, b, h) do { _Pragma("unroll") for (int m = 0; m < 4; ++m) _Pragma("unroll") for (int k = 0; k < 2; ++k) dst[m][k] = *(const PG8_LAS bf16x8*)(lds + PG8_SA(b, h) + aoff + m * 2048 + k * 1024); } while (0)
; #define PG8_LDB(dst, b, h) do { _Pragma("unroll") for (int n = 0; n < 2; ++n) _Pragma("unroll") for (int k = 0; k < 2; ++k) dst[n][k] = *(const PG8_LAS bf16x8*)(lds + PG8_SB(b, h) + boff + n * 2048 + k * 1024); } while (0)
; #define PG8_MMA(ai, bj, At, Bt) do { __builtin_amdgcn_s_setprio(1); _Pragma("unroll") for (int m = 0; m < 4; ++m) _Pragma("unroll") for (int n = 0; n < 2; ++n) _Pragma("unroll") for (int k = 0; k < 2; ++k) \
;         acc[ai][bj][m][n] = __builtin_amdgcn_mfma_f32_16x16x32_bf16(Bt[n][k], At[m][k], acc[ai][bj][m][n], 0, 0, 0); __builtin_amdgcn_s_setprio(0); } while (0)
; #define PG8_BAR __builtin_amdgcn_s_barrier()
; template <class Epi, class Sched, bool ALIGN_EPI = false, bool SP2 = false>
; __device__ __forceinline__ void gemm_phase(PG8_LAS unsigned char* lds, const Gemm g, const Sched& S, const Epi& E) {
;     ...
;         const bool has_next = S.next(ui + 1, nxt);
;         const char* nA = has_next ? (const char*)g.A + (size_t)nxt.pm * tstep : cA; const char* nB = has_next ? (const char*)g.Bt + (size_t)nxt.pn * tstep : cB;
;         for (int t = 0; t < nt; t += 2) {
;             const bool last = (t == nt - 2);
;             const char* a1 = cA + (size_t)(t + 1) * kstep;
;             const char* a2 = last ? nA : cA + (size_t)(t + 2) * kstep; const char* b2 = last ? nB : cB + (size_t)(t + 2) * kstep;
;             const char* a3 = a2 + kstep; const char* b3 = b2 + kstep;
;             if (last && has_next) S.a_ready(nxt);
;             if constexpr (SP2) {
;             PG8_LDB(B0, 0, 0); PG8_LDB(B1, 0, 1); PG8_SCHED; PG8_LDA(At, 0, 0); PG8_STAGE(PG8_SA(1, 1), a1 + hstep, voffA);
;             PG8_WAIT_V(8); PG8_WAIT_L(0); PG8_BAR; PG8_MMA(0, 0, At, B0); PG8_MMA(0, 1, At, B1); PG8_BAR; PG8_SCHED;
;             PG8_LDA(At, 0, 1); PG8_STAGE(PG8_SB(0, 0), b2, voffB); PG8_STAGE(PG8_SB(0, 1), b2 + hstep, voffB); PG8_STAGE(PG8_SA(0, 0), a2, voffA);
.LBB0_754:
	s_ashr_i32 s29, s28, 31
	v_cmp_lt_i64_e32 vcc, s[30:31], v[160:161]
	s_lshl_b64 s[30:31], s[28:29], 19
	s_add_u32 s30, s9, s30
	s_addc_u32 s31, s22, s31
	s_and_b64 s[34:35], vcc, exec
	s_cselect_b32 s29, s31, s39
	s_cselect_b32 s57, s30, s38
	s_ashr_i32 s27, s26, 31
	s_lshl_b64 s[34:35], s[26:27], 19
	s_add_u32 s34, s23, s34
	s_addc_u32 s35, s44, s35
	s_and_b64 s[42:43], vcc, exec
	s_cselect_b32 s27, s35, s41
	s_cselect_b32 s58, s34, s40
	s_add_u32 s38, s38, 0x40080
	s_addc_u32 s39, s39, 0
	s_add_u32 s59, s40, 0x100
	s_addc_u32 s60, s41, 0
	s_mov_b32 s61, -2
	ds_read_b128 v[128:131], v177
	ds_read_b128 v[132:135], v177 offset:1024
	ds_read_b128 v[136:139], v177 offset:2048
	ds_read_b128 v[140:143], v177 offset:3072
	ds_read_b128 v[144:147], v178
	ds_read_b128 v[164:167], v178 offset:1024
	ds_read_b128 v[168:171], v178 offset:2048
	ds_read_b128 v[180:183], v178 offset:3072
	s_add_u32 s40, s38, 0xfffc0080
	s_addc_u32 s41, s39, -1
	s_cmp_eq_u32 s61, 12
	s_cselect_b32 s43, s29, s41
	s_cselect_b32 s42, s57, s40
	s_cselect_b32 s41, s27, s60
	s_cselect_b32 s40, s58, s59
	s_add_i32 m0, s37, 0xc000
	ds_read_b128 v[184:187], v179
	ds_read_b128 v[188:191], v179 offset:1024
	ds_read_b128 v[192:195], v179 offset:2048
	ds_read_b128 v[196:199], v179 offset:3072
	ds_read_b128 v[200:203], v179 offset:4096
	ds_read_b128 v[204:207], v179 offset:5120
	ds_read_b128 v[208:211], v179 offset:6144
	ds_read_b128 v[214:217], v179 offset:7168
	global_load_lds_dwordx4 v156, s[38:39]
	s_add_i32 m0, s37, 0xe000
	s_nop 0
	global_load_lds_dwordx4 v158, s[38:39]
	s_waitcnt vmcnt(8)
	s_waitcnt lgkmcnt(0)
	s_barrier
	s_waitcnt lgkmcnt(0)
	v_mfma_f32_16x16x32_bf16 v[124:127], v[128:131], v[184:187], 0
	v_mfma_f32_16x16x32_bf16 v[120:123], v[136:139], v[184:187], 0
	v_mfma_f32_16x16x32_bf16 v[108:111], v[128:131], v[192:195], 0
	v_mfma_f32_16x16x32_bf16 v[104:107], v[136:139], v[192:195], 0
	v_mfma_f32_16x16x32_bf16 v[92:95], v[128:131], v[200:203], 0
	v_mfma_f32_16x16x32_bf16 v[88:91], v[136:139], v[200:203], 0
	v_mfma_f32_16x16x32_bf16 v[76:79], v[128:131], v[208:211], 0
	v_mfma_f32_16x16x32_bf16 v[72:75], v[136:139], v[208:211], 0
	v_mfma_f32_16x16x32_bf16 v[124:127], v[132:135], v[188:191], v[124:127]
	v_mfma_f32_16x16x32_bf16 v[120:123], v[140:143], v[188:191], v[120:123]
	v_mfma_f32_16x16x32_bf16 v[108:111], v[132:135], v[196:199], v[108:111]
	v_mfma_f32_16x16x32_bf16 v[104:107], v[140:143], v[196:199], v[104:107]
	v_mfma_f32_16x16x32_bf16 v[92:95], v[132:135], v[204:207], v[92:95]
	v_mfma_f32_16x16x32_bf16 v[88:91], v[140:143], v[204:207], v[88:91]
	v_mfma_f32_16x16x32_bf16 v[76:79], v[132:135], v[214:217], v[76:79]
	v_mfma_f32_16x16x32_bf16 v[72:75], v[140:143], v[214:217], v[72:75]
	v_mfma_f32_16x16x32_bf16 v[116:119], v[144:147], v[184:187], 0
	v_mfma_f32_16x16x32_bf16 v[112:115], v[168:171], v[184:187], 0
	v_mfma_f32_16x16x32_bf16 v[100:103], v[144:147], v[192:195], 0
	v_mfma_f32_16x16x32_bf16 v[96:99], v[168:171], v[192:195], 0
	v_mfma_f32_16x16x32_bf16 v[84:87], v[144:147], v[200:203], 0
	v_mfma_f32_16x16x32_bf16 v[80:83], v[168:171], v[200:203], 0
	v_mfma_f32_16x16x32_bf16 v[68:71], v[144:147], v[208:211], 0
	v_mfma_f32_16x16x32_bf16 v[64:67], v[168:171], v[208:211], 0
	v_mfma_f32_16x16x32_bf16 v[116:119], v[164:167], v[188:191], v[116:119]
	v_mfma_f32_16x16x32_bf16 v[112:115], v[180:183], v[188:191], v[112:115]
	v_mfma_f32_16x16x32_bf16 v[100:103], v[164:167], v[196:199], v[100:103]
	v_mfma_f32_16x16x32_bf16 v[96:99], v[180:183], v[196:199], v[96:99]
	v_mfma_f32_16x16x32_bf16 v[84:87], v[164:167], v[204:207], v[84:87]
	v_mfma_f32_16x16x32_bf16 v[80:83], v[180:183], v[204:207], v[80:83]
	v_mfma_f32_16x16x32_bf16 v[68:71], v[164:167], v[214:217], v[68:71]
	v_mfma_f32_16x16x32_bf16 v[64:67], v[180:183], v[214:217], v[64:67]
	s_barrier
	s_add_i32 s62, s54, s45
	s_mov_b32 m0, s62
	ds_read_b128 v[184:187], v179 offset:16384
	ds_read_b128 v[188:191], v179 offset:17408
	ds_read_b128 v[192:195], v179 offset:18432
	ds_read_b128 v[196:199], v179 offset:19456
	ds_read_b128 v[200:203], v179 offset:20480
	ds_read_b128 v[204:207], v179 offset:21504
	ds_read_b128 v[208:211], v179 offset:22528
	ds_read_b128 v[214:217], v179 offset:23552
	global_load_lds_dwordx4 v150, s[40:41]
	s_add_i32 m0, s62, 0x2000
	s_add_u32 s62, s40, 0x40000
	s_addc_u32 s63, s41, 0
	s_add_i32 s64, s55, s45
	global_load_lds_dwordx4 v154, s[40:41]
	s_mov_b32 m0, s64
	s_nop 0
	global_load_lds_dwordx4 v150, s[62:63]
	s_add_i32 m0, s64, 0x2000
	s_nop 0
	global_load_lds_dwordx4 v154, s[62:63]
	s_mov_b32 m0, s37
	s_nop 0
	global_load_lds_dwordx4 v148, s[42:43]
	s_mov_b32 m0, s46
	s_nop 0
	global_load_lds_dwordx4 v152, s[42:43]
	s_waitcnt vmcnt(8)
	s_waitcnt lgkmcnt(0)
	s_barrier
; #define PG8_STAGE(bufoff, gbase, voff) do { _Pragma("unroll") for (int _i = 0; _i < 2; ++_i) \
;         __builtin_amdgcn_global_load_lds((const unsigned*)((const char*)(gbase) + (voff)[_i]), (PG8_LAS unsigned*)(lds + (bufoff) + ldsw + _i * 8192), 16, 0, 0); } while (0)
; #define PG8_LDA(dst, b, h) do { _Pragma("unroll") for (int m = 0; m < 4; ++m) _Pragma("unroll") for (int k = 0; k < 2; ++k) dst[m][k] = *(const PG8_LAS bf16x8*)(lds + PG8_SA(b, h) + aoff + m * 2048 + k * 1024); } while (0)
; #define PG8_LDB(dst, b, h) do { _Pragma("unroll") for (int n = 0; n < 2; ++n) _Pragma("unroll") for (int k = 0; k < 2; ++k) dst[n][k] = *(const PG8_LAS bf16x8*)(lds + PG8_SB(b, h) + boff + n * 2048 + k * 1024); } while (0)
; #define PG8_MMA(ai, bj, At, Bt) do { __builtin_amdgcn_s_setprio(1); _Pragma("unroll") for (int m = 0; m < 4; ++m) _Pragma("unroll") for (int n = 0; n < 2; ++n) _Pragma("unroll") for (int k = 0; k < 2; ++k) \
;         acc[ai][bj][m][n] = __builtin_amdgcn_mfma_f32_16x16x32_bf16(Bt[n][k], At[m][k], acc[ai][bj][m][n], 0, 0, 0); __builtin_amdgcn_s_setprio(0); } while (0)
; #define PG8_WAIT_V(n) asm volatile("s_waitcnt vmcnt(" #n ")" ::: "memory")
; #define PG8_WAIT_L(n) asm volatile("s_waitcnt lgkmcnt(" #n ")" ::: "memory")
; #define PG8_BAR __builtin_amdgcn_s_barrier()
; #define PG8_SCHED __builtin_amdgcn_sched_barrier(0)
; template <class Epi, class Sched, bool ALIGN_EPI = false, bool SP2 = false>
; __device__ __forceinline__ void gemm_phase(PG8_LAS unsigned char* lds, const Gemm g, const Sched& S, const Epi& E) {
;     ...
;             PG8_WAIT_V(8); PG8_WAIT_L(0); PG8_BAR; PG8_MMA(1, 0, At, B0); PG8_MMA(1, 1, At, B1); PG8_BAR; PG8_SCHED;
;             PG8_LDB(B0, 1, 0); PG8_LDB(B1, 1, 1); PG8_SCHED; PG8_LDA(At, 1, 0); PG8_STAGE(PG8_SA(0, 1), a2 + hstep, voffA);
;             PG8_WAIT_V(8); PG8_WAIT_L(0); PG8_BAR; PG8_MMA(0, 0, At, B0); PG8_MMA(0, 1, At, B1); PG8_BAR; PG8_SCHED;
	s_waitcnt lgkmcnt(0)
	v_mfma_f32_16x16x32_bf16 v[60:63], v[128:131], v[184:187], 0
	v_mfma_f32_16x16x32_bf16 v[56:59], v[136:139], v[184:187], 0
	v_mfma_f32_16x16x32_bf16 v[44:47], v[128:131], v[192:195], 0
	v_mfma_f32_16x16x32_bf16 v[40:43], v[136:139], v[192:195], 0
	v_mfma_f32_16x16x32_bf16 v[28:31], v[128:131], v[200:203], 0
	v_mfma_f32_16x16x32_bf16 v[24:27], v[136:139], v[200:203], 0
	v_mfma_f32_16x16x32_bf16 v[12:15], v[128:131], v[208:211], 0
	v_mfma_f32_16x16x32_bf16 v[8:11], v[136:139], v[208:211], 0
	v_mfma_f32_16x16x32_bf16 v[60:63], v[132:135], v[188:191], v[60:63]
	v_mfma_f32_16x16x32_bf16 v[56:59], v[140:143], v[188:191], v[56:59]
	v_mfma_f32_16x16x32_bf16 v[44:47], v[132:135], v[196:199], v[44:47]
	v_mfma_f32_16x16x32_bf16 v[40:43], v[140:143], v[196:199], v[40:43]
	v_mfma_f32_16x16x32_bf16 v[28:31], v[132:135], v[204:207], v[28:31]
	v_mfma_f32_16x16x32_bf16 v[24:27], v[140:143], v[204:207], v[24:27]
	v_mfma_f32_16x16x32_bf16 v[12:15], v[132:135], v[214:217], v[12:15]
	v_mfma_f32_16x16x32_bf16 v[8:11], v[140:143], v[214:217], v[8:11]
	v_mfma_f32_16x16x32_bf16 v[52:55], v[144:147], v[184:187], 0
	v_mfma_f32_16x16x32_bf16 v[48:51], v[168:171], v[184:187], 0
	v_mfma_f32_16x16x32_bf16 v[36:39], v[144:147], v[192:195], 0
	v_mfma_f32_16x16x32_bf16 v[32:35], v[168:171], v[192:195], 0
	v_mfma_f32_16x16x32_bf16 v[20:23], v[144:147], v[200:203], 0
	v_mfma_f32_16x16x32_bf16 v[16:19], v[168:171], v[200:203], 0
	v_mfma_f32_16x16x32_bf16 v[4:7], v[144:147], v[208:211], 0
	v_mfma_f32_16x16x32_bf16 v[0:3], v[168:171], v[208:211], 0
	v_mfma_f32_16x16x32_bf16 v[52:55], v[164:167], v[188:191], v[52:55]
	v_mfma_f32_16x16x32_bf16 v[48:51], v[180:183], v[188:191], v[48:51]
	v_mfma_f32_16x16x32_bf16 v[36:39], v[164:167], v[196:199], v[36:39]
	v_mfma_f32_16x16x32_bf16 v[32:35], v[180:183], v[196:199], v[32:35]
	v_mfma_f32_16x16x32_bf16 v[20:23], v[164:167], v[204:207], v[20:23]
	v_mfma_f32_16x16x32_bf16 v[16:19], v[180:183], v[204:207], v[16:19]
	v_mfma_f32_16x16x32_bf16 v[4:7], v[164:167], v[214:217], v[4:7]
	v_mfma_f32_16x16x32_bf16 v[0:3], v[180:183], v[214:217], v[0:3]
	s_barrier
	s_add_i32 s62, 0, 0x18000
	s_add_i32 s63, 0, 0x1c000
	v_add_u32_e32 v140, s62, v175
	v_add_u32_e32 v180, s63, v175
	ds_read_b128 v[128:131], v140
	ds_read_b128 v[132:135], v140 offset:1024
	ds_read_b128 v[136:139], v140 offset:2048
	ds_read_b128 v[140:143], v140 offset:3072
	ds_read_b128 v[144:147], v180
	ds_read_b128 v[164:167], v180 offset:1024
	ds_read_b128 v[168:171], v180 offset:2048
	ds_read_b128 v[180:183], v180 offset:3072
	s_add_u32 s84, s42, 0x80
	s_addc_u32 s85, s43, 0
	s_add_u32 s42, s42, 0x40000
	s_addc_u32 s43, s43, 0
	s_mov_b32 m0, s47
	ds_read_b128 v[184:187], v179 offset:32768
	ds_read_b128 v[188:191], v179 offset:33792
	ds_read_b128 v[192:195], v179 offset:34816
	ds_read_b128 v[196:199], v179 offset:35840
	ds_read_b128 v[200:203], v179 offset:36864
	ds_read_b128 v[204:207], v179 offset:37888
	ds_read_b128 v[208:211], v179 offset:38912
	ds_read_b128 v[214:217], v179 offset:39936
	global_load_lds_dwordx4 v148, s[42:43]
	s_mov_b32 m0, s48
	s_nop 0
	global_load_lds_dwordx4 v152, s[42:43]
	s_waitcnt vmcnt(8)
	s_waitcnt lgkmcnt(0)
	s_barrier
	s_waitcnt lgkmcnt(0)
	v_mfma_f32_16x16x32_bf16 v[124:127], v[128:131], v[184:187], v[124:127]
	v_mfma_f32_16x16x32_bf16 v[120:123], v[136:139], v[184:187], v[120:123]
	v_mfma_f32_16x16x32_bf16 v[108:111], v[128:131], v[192:195], v[108:111]
	v_mfma_f32_16x16x32_bf16 v[104:107], v[136:139], v[192:195], v[104:107]
	v_mfma_f32_16x16x32_bf16 v[92:95], v[128:131], v[200:203], v[92:95]
	v_mfma_f32_16x16x32_bf16 v[88:91], v[136:139], v[200:203], v[88:91]
	v_mfma_f32_16x16x32_bf16 v[76:79], v[128:131], v[208:211], v[76:79]
	v_mfma_f32_16x16x32_bf16 v[72:75], v[136:139], v[208:211], v[72:75]
	v_mfma_f32_16x16x32_bf16 v[124:127], v[132:135], v[188:191], v[124:127]
	v_mfma_f32_16x16x32_bf16 v[120:123], v[140:143], v[188:191], v[120:123]
	v_mfma_f32_16x16x32_bf16 v[108:111], v[132:135], v[196:199], v[108:111]
	v_mfma_f32_16x16x32_bf16 v[104:107], v[140:143], v[196:199], v[104:107]
	v_mfma_f32_16x16x32_bf16 v[92:95], v[132:135], v[204:207], v[92:95]
	v_mfma_f32_16x16x32_bf16 v[88:91], v[140:143], v[204:207], v[88:91]
	v_mfma_f32_16x16x32_bf16 v[76:79], v[132:135], v[214:217], v[76:79]
	v_mfma_f32_16x16x32_bf16 v[72:75], v[140:143], v[214:217], v[72:75]
	v_mfma_f32_16x16x32_bf16 v[116:119], v[144:147], v[184:187], v[116:119]
	v_mfma_f32_16x16x32_bf16 v[112:115], v[168:171], v[184:187], v[112:115]
	v_mfma_f32_16x16x32_bf16 v[100:103], v[144:147], v[192:195], v[100:103]
	v_mfma_f32_16x16x32_bf16 v[96:99], v[168:171], v[192:195], v[96:99]
	v_mfma_f32_16x16x32_bf16 v[84:87], v[144:147], v[200:203], v[84:87]
	v_mfma_f32_16x16x32_bf16 v[80:83], v[168:171], v[200:203], v[80:83]
	v_mfma_f32_16x16x32_bf16 v[68:71], v[144:147], v[208:211], v[68:71]
	v_mfma_f32_16x16x32_bf16 v[64:67], v[168:171], v[208:211], v[64:67]
	v_mfma_f32_16x16x32_bf16 v[116:119], v[164:167], v[188:191], v[116:119]
	v_mfma_f32_16x16x32_bf16 v[112:115], v[180:183], v[188:191], v[112:115]
	v_mfma_f32_16x16x32_bf16 v[100:103], v[164:167], v[196:199], v[100:103]
	v_mfma_f32_16x16x32_bf16 v[96:99], v[180:183], v[196:199], v[96:99]
	v_mfma_f32_16x16x32_bf16 v[84:87], v[164:167], v[204:207], v[84:87]
	v_mfma_f32_16x16x32_bf16 v[80:83], v[180:183], v[204:207], v[80:83]
	v_mfma_f32_16x16x32_bf16 v[68:71], v[164:167], v[214:217], v[68:71]
	v_mfma_f32_16x16x32_bf16 v[64:67], v[180:183], v[214:217], v[64:67]
	s_barrier
; #define PG8_STAGE(bufoff, gbase, voff) do { _Pragma("unroll") for (int _i = 0; _i < 2; ++_i) \
;         __builtin_amdgcn_global_load_lds((const unsigned*)((const char*)(gbase) + (voff)[_i]), (PG8_LAS unsigned*)(lds + (bufoff) + ldsw + _i * 8192), 16, 0, 0); } while (0)
; #define PG8_LDA(dst, b, h) do { _Pragma("unroll") for (int m = 0; m < 4; ++m) _Pragma("unroll") for (int k = 0; k < 2; ++k) dst[m][k] = *(const PG8_LAS bf16x8*)(lds + PG8_SA(b, h) + aoff + m * 2048 + k * 1024); } while (0)
; #define PG8_MMA(ai, bj, At, Bt) do { __builtin_amdgcn_s_setprio(1); _Pragma("unroll") for (int m = 0; m < 4; ++m) _Pragma("unroll") for (int n = 0; n < 2; ++n) _Pragma("unroll") for (int k = 0; k < 2; ++k) \
;         acc[ai][bj][m][n] = __builtin_amdgcn_mfma_f32_16x16x32_bf16(Bt[n][k], At[m][k], acc[ai][bj][m][n], 0, 0, 0); __builtin_amdgcn_s_setprio(0); } while (0)
; #define PG8_WAIT_V(n) asm volatile("s_waitcnt vmcnt(" #n ")" ::: "memory")
; #define PG8_WAIT_L(n) asm volatile("s_waitcnt lgkmcnt(" #n ")" ::: "memory")
; #define PG8_BAR __builtin_amdgcn_s_barrier()
; #define PG8_SCHED __builtin_amdgcn_sched_barrier(0)
; template <class Epi, class Sched, bool ALIGN_EPI = false, bool SP2 = false>
; __device__ __forceinline__ void gemm_phase(PG8_LAS unsigned char* lds, const Gemm g, const Sched& S, const Epi& E) {
;     ...
;             PG8_LDA(At, 1, 1); PG8_STAGE(PG8_SB(1, 0), b3, voffB); PG8_STAGE(PG8_SB(1, 1), b3 + hstep, voffB); PG8_STAGE(PG8_SA(1, 0), a3, voffA);
;             PG8_WAIT_V(8); PG8_WAIT_L(0); PG8_BAR; PG8_MMA(1, 0, At, B0); PG8_MMA(1, 1, At, B1); PG8_BAR; PG8_SCHED;
	s_add_i32 s42, s62, s45
	s_add_u32 s86, s40, 0x80
	s_addc_u32 s87, s41, 0
	s_mov_b32 m0, s42
	ds_read_b128 v[184:187], v179 offset:49152
	ds_read_b128 v[188:191], v179 offset:50176
	ds_read_b128 v[192:195], v179 offset:51200
	ds_read_b128 v[196:199], v179 offset:52224
	ds_read_b128 v[200:203], v179 offset:53248
	ds_read_b128 v[204:207], v179 offset:54272
	ds_read_b128 v[208:211], v179 offset:55296
	ds_read_b128 v[214:217], v179 offset:56320
	global_load_lds_dwordx4 v150, s[86:87]
	s_add_i32 m0, s42, 0x2000
	s_add_u32 s40, s40, 0x40080
	s_addc_u32 s41, s41, 0
	s_add_i32 s42, s63, s45
	global_load_lds_dwordx4 v154, s[86:87]
	s_mov_b32 m0, s42
	s_nop 0
	global_load_lds_dwordx4 v150, s[40:41]
	s_add_i32 m0, s42, 0x2000
	s_nop 0
	global_load_lds_dwordx4 v154, s[40:41]
	s_mov_b32 m0, s50
	s_nop 0
	global_load_lds_dwordx4 v148, s[84:85]
	s_mov_b32 m0, s51
	s_nop 0
	global_load_lds_dwordx4 v152, s[84:85]
	s_waitcnt vmcnt(8)
	s_waitcnt lgkmcnt(0)
	s_barrier
	s_waitcnt lgkmcnt(0)
	v_mfma_f32_16x16x32_bf16 v[60:63], v[128:131], v[184:187], v[60:63]
	v_mfma_f32_16x16x32_bf16 v[56:59], v[136:139], v[184:187], v[56:59]
	v_mfma_f32_16x16x32_bf16 v[44:47], v[128:131], v[192:195], v[44:47]
	v_mfma_f32_16x16x32_bf16 v[40:43], v[136:139], v[192:195], v[40:43]
	v_mfma_f32_16x16x32_bf16 v[28:31], v[128:131], v[200:203], v[28:31]
	v_mfma_f32_16x16x32_bf16 v[24:27], v[136:139], v[200:203], v[24:27]
	v_mfma_f32_16x16x32_bf16 v[12:15], v[128:131], v[208:211], v[12:15]
	v_mfma_f32_16x16x32_bf16 v[8:11], v[136:139], v[208:211], v[8:11]
	v_mfma_f32_16x16x32_bf16 v[60:63], v[132:135], v[188:191], v[60:63]
	v_mfma_f32_16x16x32_bf16 v[56:59], v[140:143], v[188:191], v[56:59]
	v_mfma_f32_16x16x32_bf16 v[44:47], v[132:135], v[196:199], v[44:47]
	v_mfma_f32_16x16x32_bf16 v[40:43], v[140:143], v[196:199], v[40:43]
	v_mfma_f32_16x16x32_bf16 v[28:31], v[132:135], v[204:207], v[28:31]
	v_mfma_f32_16x16x32_bf16 v[24:27], v[140:143], v[204:207], v[24:27]
	v_mfma_f32_16x16x32_bf16 v[12:15], v[132:135], v[214:217], v[12:15]
	v_mfma_f32_16x16x32_bf16 v[8:11], v[140:143], v[214:217], v[8:11]
	v_mfma_f32_16x16x32_bf16 v[52:55], v[144:147], v[184:187], v[52:55]
	v_mfma_f32_16x16x32_bf16 v[48:51], v[168:171], v[184:187], v[48:51]
	v_mfma_f32_16x16x32_bf16 v[36:39], v[144:147], v[192:195], v[36:39]
	v_mfma_f32_16x16x32_bf16 v[32:35], v[168:171], v[192:195], v[32:35]
	v_mfma_f32_16x16x32_bf16 v[20:23], v[144:147], v[200:203], v[20:23]
	v_mfma_f32_16x16x32_bf16 v[16:19], v[168:171], v[200:203], v[16:19]
	v_mfma_f32_16x16x32_bf16 v[4:7], v[144:147], v[208:211], v[4:7]
	v_mfma_f32_16x16x32_bf16 v[0:3], v[168:171], v[208:211], v[0:3]
	v_mfma_f32_16x16x32_bf16 v[52:55], v[164:167], v[188:191], v[52:55]
	v_mfma_f32_16x16x32_bf16 v[48:51], v[180:183], v[188:191], v[48:51]
	v_mfma_f32_16x16x32_bf16 v[36:39], v[164:167], v[196:199], v[36:39]
	v_mfma_f32_16x16x32_bf16 v[32:35], v[180:183], v[196:199], v[32:35]
	v_mfma_f32_16x16x32_bf16 v[20:23], v[164:167], v[204:207], v[20:23]
	v_mfma_f32_16x16x32_bf16 v[16:19], v[180:183], v[204:207], v[16:19]
	v_mfma_f32_16x16x32_bf16 v[4:7], v[164:167], v[214:217], v[4:7]
	v_mfma_f32_16x16x32_bf16 v[0:3], v[180:183], v[214:217], v[0:3]
	s_barrier
	s_add_i32 s61, s61, 2
	s_add_u32 s38, s38, 0x100
	s_addc_u32 s39, s39, 0
	s_add_u32 s59, s59, 0x100
	s_addc_u32 s60, s60, 0
	s_cmp_gt_u32 s61, 13
	.p2align	6

; #define PG8_STAGE(bufoff, gbase, voff) do { _Pragma("unroll") for (int _i = 0; _i < 2; ++_i) \
;         __builtin_amdgcn_global_load_lds((const unsigned*)((const char*)(gbase) + (voff)[_i]), (PG8_LAS unsigned*)(lds + (bufoff) + ldsw + _i * 8192), 16, 0, 0); } while (0)
; #define PG8_LDA(dst, b, h) do { _Pragma("unroll") for (int m = 0; m < 4; ++m) _Pragma("unroll") for (int k = 0; k < 2; ++k) dst[m][k] = *(const PG8_LAS bf16x8*)(lds + PG8_SA(b, h) + aoff + m * 2048 + k * 1024); } while (0)
; #define PG8_LDB(dst, b, h) do { _Pragma("unroll") for (int n = 0; n < 2; ++n) _Pragma("unroll") for (int k = 0; k < 2; ++k) dst[n][k] = *(const PG8_LAS bf16x8*)(lds + PG8_SB(b, h) + boff + n * 2048 + k * 1024); } while (0)
; #define PG8_MMA(ai, bj, At, Bt) do { __builtin_amdgcn_s_setprio(1); _Pragma("unroll") for (int m = 0; m < 4; ++m) _Pragma("unroll") for (int n = 0; n < 2; ++n) _Pragma("unroll") for (int k = 0; k < 2; ++k) \
;         acc[ai][bj][m][n] = __builtin_amdgcn_mfma_f32_16x16x32_bf16(Bt[n][k], At[m][k], acc[ai][bj][m][n], 0, 0, 0); __builtin_amdgcn_s_setprio(0); } while (0)
; #define PG8_BAR __builtin_amdgcn_s_barrier()
; template <class Epi, class Sched, bool ALIGN_EPI = false, bool SP2 = false>
; __device__ __forceinline__ void gemm_phase(PG8_LAS unsigned char* lds, const Gemm g, const Sched& S, const Epi& E) {
;     ...
;         const bool has_next = S.next(ui + 1, nxt);
;         const char* nA = has_next ? (const char*)g.A + (size_t)nxt.pm * tstep : cA; const char* nB = has_next ? (const char*)g.Bt + (size_t)nxt.pn * tstep : cB;
;         for (int t = 0; t < nt; t += 2) {
;             const bool last = (t == nt - 2);
;             const char* a1 = cA + (size_t)(t + 1) * kstep;
;             const char* a2 = last ? nA : cA + (size_t)(t + 2) * kstep; const char* b2 = last ? nB : cB + (size_t)(t + 2) * kstep;
;             const char* a3 = a2 + kstep; const char* b3 = b2 + kstep;
;             if (last && has_next) S.a_ready(nxt);
;             if constexpr (SP2) {
;             PG8_LDB(B0, 0, 0); PG8_LDB(B1, 0, 1); PG8_SCHED; PG8_LDA(At, 0, 0); PG8_STAGE(PG8_SA(1, 1), a1 + hstep, voffA);
;             PG8_WAIT_V(8); PG8_WAIT_L(0); PG8_BAR; PG8_MMA(0, 0, At, B0); PG8_MMA(0, 1, At, B1); PG8_BAR; PG8_SCHED;
;             PG8_LDA(At, 0, 1); PG8_STAGE(PG8_SB(0, 0), b2, voffB); PG8_STAGE(PG8_SB(0, 1), b2 + hstep, voffB); PG8_STAGE(PG8_SA(0, 0), a2, voffA);
.LBB0_826:
	s_ashr_i32 s39, s38, 31
	v_cmp_lt_i64_e32 vcc, s[40:41], v[156:157]
	s_lshl_b64 s[40:41], s[38:39], 20
	s_add_u32 s40, s9, s40
	s_addc_u32 s41, s22, s41
	s_and_b64 s[42:43], vcc, exec
	s_cselect_b32 s39, s41, s47
	s_cselect_b32 s67, s40, s46
	s_ashr_i32 s37, s36, 31
	s_lshl_b64 s[42:43], s[36:37], 20
	s_add_u32 s42, s23, s42
	s_addc_u32 s43, s52, s43
	s_and_b64 s[50:51], vcc, exec
	s_cselect_b32 s37, s43, s49
	s_cselect_b32 s68, s42, s48
	s_add_u32 s46, s46, 0x80080
	s_addc_u32 s47, s47, 0
	s_add_u32 s69, s48, 0x100
	s_addc_u32 s70, s49, 0
	s_mov_b32 s71, -2
	ds_read_b128 v[128:131], v169
	ds_read_b128 v[132:135], v169 offset:1024
	ds_read_b128 v[136:139], v169 offset:2048
	ds_read_b128 v[140:143], v169 offset:3072
	ds_read_b128 v[160:163], v170
	ds_read_b128 v[172:175], v170 offset:1024
	ds_read_b128 v[176:179], v170 offset:2048
	ds_read_b128 v[180:183], v170 offset:3072
	s_add_u32 s48, s46, 0xfff80080
	s_addc_u32 s49, s47, -1
	s_cmp_eq_u32 s71, 28
	s_cselect_b32 s51, s39, s49
	s_cselect_b32 s50, s67, s48
	s_cselect_b32 s49, s37, s70
	s_cselect_b32 s48, s68, s69
	s_add_i32 m0, s45, 0xc000
	ds_read_b128 v[184:187], v171
	ds_read_b128 v[188:191], v171 offset:1024
	ds_read_b128 v[192:195], v171 offset:2048
	ds_read_b128 v[196:199], v171 offset:3072
	ds_read_b128 v[200:203], v171 offset:4096
	ds_read_b128 v[204:207], v171 offset:5120
	ds_read_b128 v[208:211], v171 offset:6144
	ds_read_b128 v[214:217], v171 offset:7168
	global_load_lds_dwordx4 v152, s[46:47]
	s_add_i32 m0, s45, 0xe000
	s_nop 0
	global_load_lds_dwordx4 v154, s[46:47]
	s_waitcnt vmcnt(8)
	s_waitcnt lgkmcnt(0)
	s_barrier
	s_waitcnt lgkmcnt(0)
	v_mfma_f32_16x16x32_bf16 v[124:127], v[128:131], v[184:187], 0
	v_mfma_f32_16x16x32_bf16 v[120:123], v[136:139], v[184:187], 0
	v_mfma_f32_16x16x32_bf16 v[116:119], v[128:131], v[192:195], 0
	v_mfma_f32_16x16x32_bf16 v[112:115], v[136:139], v[192:195], 0
	v_mfma_f32_16x16x32_bf16 v[108:111], v[128:131], v[200:203], 0
	v_mfma_f32_16x16x32_bf16 v[96:99], v[136:139], v[200:203], 0
	v_mfma_f32_16x16x32_bf16 v[80:83], v[128:131], v[208:211], 0
	v_mfma_f32_16x16x32_bf16 v[72:75], v[136:139], v[208:211], 0
	v_mfma_f32_16x16x32_bf16 v[124:127], v[132:135], v[188:191], v[124:127]
	v_mfma_f32_16x16x32_bf16 v[120:123], v[140:143], v[188:191], v[120:123]
	v_mfma_f32_16x16x32_bf16 v[116:119], v[132:135], v[196:199], v[116:119]
	v_mfma_f32_16x16x32_bf16 v[112:115], v[140:143], v[196:199], v[112:115]
	v_mfma_f32_16x16x32_bf16 v[108:111], v[132:135], v[204:207], v[108:111]
	v_mfma_f32_16x16x32_bf16 v[96:99], v[140:143], v[204:207], v[96:99]
	v_mfma_f32_16x16x32_bf16 v[80:83], v[132:135], v[214:217], v[80:83]
	v_mfma_f32_16x16x32_bf16 v[72:75], v[140:143], v[214:217], v[72:75]
	v_mfma_f32_16x16x32_bf16 v[104:107], v[160:163], v[184:187], 0
	v_mfma_f32_16x16x32_bf16 v[100:103], v[176:179], v[184:187], 0
	v_mfma_f32_16x16x32_bf16 v[92:95], v[160:163], v[192:195], 0
	v_mfma_f32_16x16x32_bf16 v[88:91], v[176:179], v[192:195], 0
	v_mfma_f32_16x16x32_bf16 v[84:87], v[160:163], v[200:203], 0
	v_mfma_f32_16x16x32_bf16 v[76:79], v[176:179], v[200:203], 0
	v_mfma_f32_16x16x32_bf16 v[68:71], v[160:163], v[208:211], 0
	v_mfma_f32_16x16x32_bf16 v[64:67], v[176:179], v[208:211], 0
	v_mfma_f32_16x16x32_bf16 v[104:107], v[172:175], v[188:191], v[104:107]
	v_mfma_f32_16x16x32_bf16 v[100:103], v[180:183], v[188:191], v[100:103]
	v_mfma_f32_16x16x32_bf16 v[92:95], v[172:175], v[196:199], v[92:95]
	v_mfma_f32_16x16x32_bf16 v[88:91], v[180:183], v[196:199], v[88:91]
	v_mfma_f32_16x16x32_bf16 v[84:87], v[172:175], v[204:207], v[84:87]
	v_mfma_f32_16x16x32_bf16 v[76:79], v[180:183], v[204:207], v[76:79]
	v_mfma_f32_16x16x32_bf16 v[68:71], v[172:175], v[214:217], v[68:71]
	v_mfma_f32_16x16x32_bf16 v[64:67], v[180:183], v[214:217], v[64:67]
	s_barrier
	s_add_i32 s72, s64, s53
	s_mov_b32 m0, s72
	ds_read_b128 v[184:187], v171 offset:16384
	ds_read_b128 v[188:191], v171 offset:17408
	ds_read_b128 v[192:195], v171 offset:18432
	ds_read_b128 v[196:199], v171 offset:19456
	ds_read_b128 v[200:203], v171 offset:20480
	ds_read_b128 v[204:207], v171 offset:21504
	ds_read_b128 v[208:211], v171 offset:22528
	ds_read_b128 v[214:217], v171 offset:23552
	global_load_lds_dwordx4 v146, s[48:49]
	s_add_i32 m0, s72, 0x2000
	s_add_u32 s72, s48, 0x80000
	s_addc_u32 s73, s49, 0
	s_add_i32 s74, s65, s53
	global_load_lds_dwordx4 v150, s[48:49]
	s_mov_b32 m0, s74
	s_nop 0
	global_load_lds_dwordx4 v146, s[72:73]
	s_add_i32 m0, s74, 0x2000
	s_nop 0
	global_load_lds_dwordx4 v150, s[72:73]
	s_mov_b32 m0, s45
	s_nop 0
	global_load_lds_dwordx4 v144, s[50:51]
	s_mov_b32 m0, s54
	s_nop 0
	global_load_lds_dwordx4 v148, s[50:51]
	s_waitcnt vmcnt(8)
	s_waitcnt lgkmcnt(0)
	s_barrier
; #define PG8_STAGE(bufoff, gbase, voff) do { _Pragma("unroll") for (int _i = 0; _i < 2; ++_i) \
;         __builtin_amdgcn_global_load_lds((const unsigned*)((const char*)(gbase) + (voff)[_i]), (PG8_LAS unsigned*)(lds + (bufoff) + ldsw + _i * 8192), 16, 0, 0); } while (0)
; #define PG8_LDA(dst, b, h) do { _Pragma("unroll") for (int m = 0; m < 4; ++m) _Pragma("unroll") for (int k = 0; k < 2; ++k) dst[m][k] = *(const PG8_LAS bf16x8*)(lds + PG8_SA(b, h) + aoff + m * 2048 + k * 1024); } while (0)
; #define PG8_LDB(dst, b, h) do { _Pragma("unroll") for (int n = 0; n < 2; ++n) _Pragma("unroll") for (int k = 0; k < 2; ++k) dst[n][k] = *(const PG8_LAS bf16x8*)(lds + PG8_SB(b, h) + boff + n * 2048 + k * 1024); } while (0)
; #define PG8_MMA(ai, bj, At, Bt) do { __builtin_amdgcn_s_setprio(1); _Pragma("unroll") for (int m = 0; m < 4; ++m) _Pragma("unroll") for (int n = 0; n < 2; ++n) _Pragma("unroll") for (int k = 0; k < 2; ++k) \
;         acc[ai][bj][m][n] = __builtin_amdgcn_mfma_f32_16x16x32_bf16(Bt[n][k], At[m][k], acc[ai][bj][m][n], 0, 0, 0); __builtin_amdgcn_s_setprio(0); } while (0)
; #define PG8_WAIT_V(n) asm volatile("s_waitcnt vmcnt(" #n ")" ::: "memory")
; #define PG8_WAIT_L(n) asm volatile("s_waitcnt lgkmcnt(" #n ")" ::: "memory")
; #define PG8_BAR __builtin_amdgcn_s_barrier()
; #define PG8_SCHED __builtin_amdgcn_sched_barrier(0)
; template <class Epi, class Sched, bool ALIGN_EPI = false, bool SP2 = false>
; __device__ __forceinline__ void gemm_phase(PG8_LAS unsigned char* lds, const Gemm g, const Sched& S, const Epi& E) {
;     ...
;             PG8_WAIT_V(8); PG8_WAIT_L(0); PG8_BAR; PG8_MMA(1, 0, At, B0); PG8_MMA(1, 1, At, B1); PG8_BAR; PG8_SCHED;
;             PG8_LDB(B0, 1, 0); PG8_LDB(B1, 1, 1); PG8_SCHED; PG8_LDA(At, 1, 0); PG8_STAGE(PG8_SA(0, 1), a2 + hstep, voffA);
;             PG8_WAIT_V(8); PG8_WAIT_L(0); PG8_BAR; PG8_MMA(0, 0, At, B0); PG8_MMA(0, 1, At, B1); PG8_BAR; PG8_SCHED;
	s_waitcnt lgkmcnt(0)
	v_mfma_f32_16x16x32_bf16 v[60:63], v[128:131], v[184:187], 0
	v_mfma_f32_16x16x32_bf16 v[56:59], v[136:139], v[184:187], 0
	v_mfma_f32_16x16x32_bf16 v[52:55], v[128:131], v[192:195], 0
	v_mfma_f32_16x16x32_bf16 v[48:51], v[136:139], v[192:195], 0
	v_mfma_f32_16x16x32_bf16 v[44:47], v[128:131], v[200:203], 0
	v_mfma_f32_16x16x32_bf16 v[32:35], v[136:139], v[200:203], 0
	v_mfma_f32_16x16x32_bf16 v[20:23], v[128:131], v[208:211], 0
	v_mfma_f32_16x16x32_bf16 v[8:11], v[136:139], v[208:211], 0
	v_mfma_f32_16x16x32_bf16 v[60:63], v[132:135], v[188:191], v[60:63]
	v_mfma_f32_16x16x32_bf16 v[56:59], v[140:143], v[188:191], v[56:59]
	v_mfma_f32_16x16x32_bf16 v[52:55], v[132:135], v[196:199], v[52:55]
	v_mfma_f32_16x16x32_bf16 v[48:51], v[140:143], v[196:199], v[48:51]
	v_mfma_f32_16x16x32_bf16 v[44:47], v[132:135], v[204:207], v[44:47]
	v_mfma_f32_16x16x32_bf16 v[32:35], v[140:143], v[204:207], v[32:35]
	v_mfma_f32_16x16x32_bf16 v[20:23], v[132:135], v[214:217], v[20:23]
	v_mfma_f32_16x16x32_bf16 v[8:11], v[140:143], v[214:217], v[8:11]
	v_mfma_f32_16x16x32_bf16 v[40:43], v[160:163], v[184:187], 0
	v_mfma_f32_16x16x32_bf16 v[36:39], v[176:179], v[184:187], 0
	v_mfma_f32_16x16x32_bf16 v[28:31], v[160:163], v[192:195], 0
	v_mfma_f32_16x16x32_bf16 v[24:27], v[176:179], v[192:195], 0
	v_mfma_f32_16x16x32_bf16 v[16:19], v[160:163], v[200:203], 0
	v_mfma_f32_16x16x32_bf16 v[12:15], v[176:179], v[200:203], 0
	v_mfma_f32_16x16x32_bf16 v[4:7], v[160:163], v[208:211], 0
	v_mfma_f32_16x16x32_bf16 v[0:3], v[176:179], v[208:211], 0
	v_mfma_f32_16x16x32_bf16 v[40:43], v[172:175], v[188:191], v[40:43]
	v_mfma_f32_16x16x32_bf16 v[36:39], v[180:183], v[188:191], v[36:39]
	v_mfma_f32_16x16x32_bf16 v[28:31], v[172:175], v[196:199], v[28:31]
	v_mfma_f32_16x16x32_bf16 v[24:27], v[180:183], v[196:199], v[24:27]
	v_mfma_f32_16x16x32_bf16 v[16:19], v[172:175], v[204:207], v[16:19]
	v_mfma_f32_16x16x32_bf16 v[12:15], v[180:183], v[204:207], v[12:15]
	v_mfma_f32_16x16x32_bf16 v[4:7], v[172:175], v[214:217], v[4:7]
	v_mfma_f32_16x16x32_bf16 v[0:3], v[180:183], v[214:217], v[0:3]
	s_barrier
	s_add_i32 s72, 0, 0x18000
	s_add_i32 s73, 0, 0x1c000
	v_add_u32_e32 v140, s72, v167
	v_add_u32_e32 v180, s73, v167
	ds_read_b128 v[128:131], v140
	ds_read_b128 v[132:135], v140 offset:1024
	ds_read_b128 v[136:139], v140 offset:2048
	ds_read_b128 v[140:143], v140 offset:3072
	ds_read_b128 v[160:163], v180
	ds_read_b128 v[172:175], v180 offset:1024
	ds_read_b128 v[176:179], v180 offset:2048
	ds_read_b128 v[180:183], v180 offset:3072
	s_add_u32 s84, s50, 0x80
	s_addc_u32 s85, s51, 0
	s_add_u32 s50, s50, 0x80000
	s_addc_u32 s51, s51, 0
	s_mov_b32 m0, s55
	ds_read_b128 v[184:187], v171 offset:32768
	ds_read_b128 v[188:191], v171 offset:33792
	ds_read_b128 v[192:195], v171 offset:34816
	ds_read_b128 v[196:199], v171 offset:35840
	ds_read_b128 v[200:203], v171 offset:36864
	ds_read_b128 v[204:207], v171 offset:37888
	ds_read_b128 v[208:211], v171 offset:38912
	ds_read_b128 v[214:217], v171 offset:39936
	global_load_lds_dwordx4 v144, s[50:51]
	s_mov_b32 m0, s56
	s_nop 0
	global_load_lds_dwordx4 v148, s[50:51]
	s_waitcnt vmcnt(8)
	s_waitcnt lgkmcnt(0)
	s_barrier
	s_waitcnt lgkmcnt(0)
	v_mfma_f32_16x16x32_bf16 v[124:127], v[128:131], v[184:187], v[124:127]
	v_mfma_f32_16x16x32_bf16 v[120:123], v[136:139], v[184:187], v[120:123]
	v_mfma_f32_16x16x32_bf16 v[116:119], v[128:131], v[192:195], v[116:119]
	v_mfma_f32_16x16x32_bf16 v[112:115], v[136:139], v[192:195], v[112:115]
	v_mfma_f32_16x16x32_bf16 v[108:111], v[128:131], v[200:203], v[108:111]
	v_mfma_f32_16x16x32_bf16 v[96:99], v[136:139], v[200:203], v[96:99]
	v_mfma_f32_16x16x32_bf16 v[80:83], v[128:131], v[208:211], v[80:83]
	v_mfma_f32_16x16x32_bf16 v[72:75], v[136:139], v[208:211], v[72:75]
	v_mfma_f32_16x16x32_bf16 v[124:127], v[132:135], v[188:191], v[124:127]
	v_mfma_f32_16x16x32_bf16 v[120:123], v[140:143], v[188:191], v[120:123]
	v_mfma_f32_16x16x32_bf16 v[116:119], v[132:135], v[196:199], v[116:119]
	v_mfma_f32_16x16x32_bf16 v[112:115], v[140:143], v[196:199], v[112:115]
	v_mfma_f32_16x16x32_bf16 v[108:111], v[132:135], v[204:207], v[108:111]
	v_mfma_f32_16x16x32_bf16 v[96:99], v[140:143], v[204:207], v[96:99]
	v_mfma_f32_16x16x32_bf16 v[80:83], v[132:135], v[214:217], v[80:83]
	v_mfma_f32_16x16x32_bf16 v[72:75], v[140:143], v[214:217], v[72:75]
	v_mfma_f32_16x16x32_bf16 v[104:107], v[160:163], v[184:187], v[104:107]
	v_mfma_f32_16x16x32_bf16 v[100:103], v[176:179], v[184:187], v[100:103]
	v_mfma_f32_16x16x32_bf16 v[92:95], v[160:163], v[192:195], v[92:95]
	v_mfma_f32_16x16x32_bf16 v[88:91], v[176:179], v[192:195], v[88:91]
	v_mfma_f32_16x16x32_bf16 v[84:87], v[160:163], v[200:203], v[84:87]
	v_mfma_f32_16x16x32_bf16 v[76:79], v[176:179], v[200:203], v[76:79]
	v_mfma_f32_16x16x32_bf16 v[68:71], v[160:163], v[208:211], v[68:71]
	v_mfma_f32_16x16x32_bf16 v[64:67], v[176:179], v[208:211], v[64:67]
	v_mfma_f32_16x16x32_bf16 v[104:107], v[172:175], v[188:191], v[104:107]
	v_mfma_f32_16x16x32_bf16 v[100:103], v[180:183], v[188:191], v[100:103]
	v_mfma_f32_16x16x32_bf16 v[92:95], v[172:175], v[196:199], v[92:95]
	v_mfma_f32_16x16x32_bf16 v[88:91], v[180:183], v[196:199], v[88:91]
	v_mfma_f32_16x16x32_bf16 v[84:87], v[172:175], v[204:207], v[84:87]
	v_mfma_f32_16x16x32_bf16 v[76:79], v[180:183], v[204:207], v[76:79]
	v_mfma_f32_16x16x32_bf16 v[68:71], v[172:175], v[214:217], v[68:71]
	v_mfma_f32_16x16x32_bf16 v[64:67], v[180:183], v[214:217], v[64:67]
	s_barrier
; #define PG8_STAGE(bufoff, gbase, voff) do { _Pragma("unroll") for (int _i = 0; _i < 2; ++_i) \
;         __builtin_amdgcn_global_load_lds((const unsigned*)((const char*)(gbase) + (voff)[_i]), (PG8_LAS unsigned*)(lds + (bufoff) + ldsw + _i * 8192), 16, 0, 0); } while (0)
; #define PG8_LDA(dst, b, h) do { _Pragma("unroll") for (int m = 0; m < 4; ++m) _Pragma("unroll") for (int k = 0; k < 2; ++k) dst[m][k] = *(const PG8_LAS bf16x8*)(lds + PG8_SA(b, h) + aoff + m * 2048 + k * 1024); } while (0)
; #define PG8_MMA(ai, bj, At, Bt) do { __builtin_amdgcn_s_setprio(1); _Pragma("unroll") for (int m = 0; m < 4; ++m) _Pragma("unroll") for (int n = 0; n < 2; ++n) _Pragma("unroll") for (int k = 0; k < 2; ++k) \
;         acc[ai][bj][m][n] = __builtin_amdgcn_mfma_f32_16x16x32_bf16(Bt[n][k], At[m][k], acc[ai][bj][m][n], 0, 0, 0); __builtin_amdgcn_s_setprio(0); } while (0)
; #define PG8_WAIT_V(n) asm volatile("s_waitcnt vmcnt(" #n ")" ::: "memory")
; #define PG8_WAIT_L(n) asm volatile("s_waitcnt lgkmcnt(" #n ")" ::: "memory")
; #define PG8_BAR __builtin_amdgcn_s_barrier()
; #define PG8_SCHED __builtin_amdgcn_sched_barrier(0)
; template <class Epi, class Sched, bool ALIGN_EPI = false, bool SP2 = false>
; __device__ __forceinline__ void gemm_phase(PG8_LAS unsigned char* lds, const Gemm g, const Sched& S, const Epi& E) {
;     ...
;             PG8_LDA(At, 1, 1); PG8_STAGE(PG8_SB(1, 0), b3, voffB); PG8_STAGE(PG8_SB(1, 1), b3 + hstep, voffB); PG8_STAGE(PG8_SA(1, 0), a3, voffA);
;             PG8_WAIT_V(8); PG8_WAIT_L(0); PG8_BAR; PG8_MMA(1, 0, At, B0); PG8_MMA(1, 1, At, B1); PG8_BAR; PG8_SCHED;
	s_add_i32 s50, s72, s53
	s_add_u32 s86, s48, 0x80
	s_addc_u32 s87, s49, 0
	s_mov_b32 m0, s50
	ds_read_b128 v[184:187], v171 offset:49152
	ds_read_b128 v[188:191], v171 offset:50176
	ds_read_b128 v[192:195], v171 offset:51200
	ds_read_b128 v[196:199], v171 offset:52224
	ds_read_b128 v[200:203], v171 offset:53248
	ds_read_b128 v[204:207], v171 offset:54272
	ds_read_b128 v[208:211], v171 offset:55296
	ds_read_b128 v[214:217], v171 offset:56320
	global_load_lds_dwordx4 v146, s[86:87]
	s_add_i32 m0, s50, 0x2000
	s_add_u32 s48, s48, 0x80080
	s_addc_u32 s49, s49, 0
	s_add_i32 s50, s73, s53
	global_load_lds_dwordx4 v150, s[86:87]
	s_mov_b32 m0, s50
	s_nop 0
	global_load_lds_dwordx4 v146, s[48:49]
	s_add_i32 m0, s50, 0x2000
	s_nop 0
	global_load_lds_dwordx4 v150, s[48:49]
	s_mov_b32 m0, s60
	s_nop 0
	global_load_lds_dwordx4 v144, s[84:85]
	s_mov_b32 m0, s61
	s_nop 0
	global_load_lds_dwordx4 v148, s[84:85]
	s_waitcnt vmcnt(8)
	s_waitcnt lgkmcnt(0)
	s_barrier
	s_waitcnt lgkmcnt(0)
	v_mfma_f32_16x16x32_bf16 v[60:63], v[128:131], v[184:187], v[60:63]
	v_mfma_f32_16x16x32_bf16 v[56:59], v[136:139], v[184:187], v[56:59]
	v_mfma_f32_16x16x32_bf16 v[52:55], v[128:131], v[192:195], v[52:55]
	v_mfma_f32_16x16x32_bf16 v[48:51], v[136:139], v[192:195], v[48:51]
	v_mfma_f32_16x16x32_bf16 v[44:47], v[128:131], v[200:203], v[44:47]
	v_mfma_f32_16x16x32_bf16 v[32:35], v[136:139], v[200:203], v[32:35]
	v_mfma_f32_16x16x32_bf16 v[20:23], v[128:131], v[208:211], v[20:23]
	v_mfma_f32_16x16x32_bf16 v[8:11], v[136:139], v[208:211], v[8:11]
	v_mfma_f32_16x16x32_bf16 v[60:63], v[132:135], v[188:191], v[60:63]
	v_mfma_f32_16x16x32_bf16 v[56:59], v[140:143], v[188:191], v[56:59]
	v_mfma_f32_16x16x32_bf16 v[52:55], v[132:135], v[196:199], v[52:55]
	v_mfma_f32_16x16x32_bf16 v[48:51], v[140:143], v[196:199], v[48:51]
	v_mfma_f32_16x16x32_bf16 v[44:47], v[132:135], v[204:207], v[44:47]
	v_mfma_f32_16x16x32_bf16 v[32:35], v[140:143], v[204:207], v[32:35]
	v_mfma_f32_16x16x32_bf16 v[20:23], v[132:135], v[214:217], v[20:23]
	v_mfma_f32_16x16x32_bf16 v[8:11], v[140:143], v[214:217], v[8:11]
	v_mfma_f32_16x16x32_bf16 v[40:43], v[160:163], v[184:187], v[40:43]
	v_mfma_f32_16x16x32_bf16 v[36:39], v[176:179], v[184:187], v[36:39]
	v_mfma_f32_16x16x32_bf16 v[28:31], v[160:163], v[192:195], v[28:31]
	v_mfma_f32_16x16x32_bf16 v[24:27], v[176:179], v[192:195], v[24:27]
	v_mfma_f32_16x16x32_bf16 v[16:19], v[160:163], v[200:203], v[16:19]
	v_mfma_f32_16x16x32_bf16 v[12:15], v[176:179], v[200:203], v[12:15]
	v_mfma_f32_16x16x32_bf16 v[4:7], v[160:163], v[208:211], v[4:7]
	v_mfma_f32_16x16x32_bf16 v[0:3], v[176:179], v[208:211], v[0:3]
	v_mfma_f32_16x16x32_bf16 v[40:43], v[172:175], v[188:191], v[40:43]
	v_mfma_f32_16x16x32_bf16 v[36:39], v[180:183], v[188:191], v[36:39]
	v_mfma_f32_16x16x32_bf16 v[28:31], v[172:175], v[196:199], v[28:31]
	v_mfma_f32_16x16x32_bf16 v[24:27], v[180:183], v[196:199], v[24:27]
	v_mfma_f32_16x16x32_bf16 v[16:19], v[172:175], v[204:207], v[16:19]
	v_mfma_f32_16x16x32_bf16 v[12:15], v[180:183], v[204:207], v[12:15]
	v_mfma_f32_16x16x32_bf16 v[4:7], v[172:175], v[214:217], v[4:7]
	v_mfma_f32_16x16x32_bf16 v[0:3], v[180:183], v[214:217], v[0:3]
	s_barrier
	s_add_i32 s71, s71, 2
	s_add_u32 s46, s46, 0x100
	s_addc_u32 s47, s47, 0
	s_add_u32 s69, s69, 0x100
	s_addc_u32 s70, s70, 0
	s_cmp_gt_u32 s71, 29
	.p2align	6

; #define PG8_STAGE(bufoff, gbase, voff) do { _Pragma("unroll") for (int _i = 0; _i < 2; ++_i) \
;         __builtin_amdgcn_global_load_lds((const unsigned*)((const char*)(gbase) + (voff)[_i]), (PG8_LAS unsigned*)(lds + (bufoff) + ldsw + _i * 8192), 16, 0, 0); } while (0)
; #define PG8_LDA(dst, b, h) do { _Pragma("unroll") for (int m = 0; m < 4; ++m) _Pragma("unroll") for (int k = 0; k < 2; ++k) dst[m][k] = *(const PG8_LAS bf16x8*)(lds + PG8_SA(b, h) + aoff + m * 2048 + k * 1024); } while (0)
; #define PG8_LDB(dst, b, h) do { _Pragma("unroll") for (int n = 0; n < 2; ++n) _Pragma("unroll") for (int k = 0; k < 2; ++k) dst[n][k] = *(const PG8_LAS bf16x8*)(lds + PG8_SB(b, h) + boff + n * 2048 + k * 1024); } while (0)
; #define PG8_MMA(ai, bj, At, Bt) do { __builtin_amdgcn_s_setprio(1); _Pragma("unroll") for (int m = 0; m < 4; ++m) _Pragma("unroll") for (int n = 0; n < 2; ++n) _Pragma("unroll") for (int k = 0; k < 2; ++k) \
;         acc[ai][bj][m][n] = __builtin_amdgcn_mfma_f32_16x16x32_bf16(Bt[n][k], At[m][k], acc[ai][bj][m][n], 0, 0, 0); __builtin_amdgcn_s_setprio(0); } while (0)
; #define PG8_BAR __builtin_amdgcn_s_barrier()
; template <class Epi, class Sched, bool ALIGN_EPI = false, bool SP2 = false>
; __device__ __forceinline__ void gemm_phase(PG8_LAS unsigned char* lds, const Gemm g, const Sched& S, const Epi& E) {
;     ...
;         const bool has_next = S.next(ui + 1, nxt);
;         const char* nA = has_next ? (const char*)g.A + (size_t)nxt.pm * tstep : cA; const char* nB = has_next ? (const char*)g.Bt + (size_t)nxt.pn * tstep : cB;
;         for (int t = 0; t < nt; t += 2) {
;             const bool last = (t == nt - 2);
;             const char* a1 = cA + (size_t)(t + 1) * kstep;
;             const char* a2 = last ? nA : cA + (size_t)(t + 2) * kstep; const char* b2 = last ? nB : cB + (size_t)(t + 2) * kstep;
;             const char* a3 = a2 + kstep; const char* b3 = b2 + kstep;
;             if (last && has_next) S.a_ready(nxt);
;             if constexpr (SP2) {
;             PG8_LDB(B0, 0, 0); PG8_LDB(B1, 0, 1); PG8_SCHED; PG8_LDA(At, 0, 0); PG8_STAGE(PG8_SA(1, 1), a1 + hstep, voffA);
;             PG8_WAIT_V(8); PG8_WAIT_L(0); PG8_BAR; PG8_MMA(0, 0, At, B0); PG8_MMA(0, 1, At, B1); PG8_BAR; PG8_SCHED;
;             PG8_LDA(At, 0, 1); PG8_STAGE(PG8_SB(0, 0), b2, voffB); PG8_STAGE(PG8_SB(0, 1), b2 + hstep, voffB); PG8_STAGE(PG8_SA(0, 0), a2, voffA);
.LBB0_944:
	s_ashr_i32 s23, s22, 31
	v_cmp_lt_i64_e32 vcc, s[24:25], v[140:141]
	s_lshl_b64 s[24:25], s[22:23], 20
	s_add_u32 s24, s38, s24
	s_addc_u32 s25, s39, s25
	s_and_b64 s[26:27], vcc, exec
	s_cselect_b32 s23, s25, s31
	s_cselect_b32 s57, s24, s30
	s_ashr_i32 s15, s14, 31
	s_lshl_b64 s[26:27], s[14:15], 20
	s_add_u32 s26, s40, s26
	s_addc_u32 s27, s41, s27
	s_and_b64 s[36:37], vcc, exec
	s_cselect_b32 s15, s27, s35
	s_cselect_b32 s58, s26, s34
	s_add_u32 s30, s30, 0x80080
	s_addc_u32 s31, s31, 0
	s_add_u32 s59, s34, 0x100
	s_addc_u32 s60, s35, 0
	s_mov_b32 s61, -2
	ds_read_b128 v[152:155], v149
	ds_read_b128 v[156:159], v149 offset:1024
	ds_read_b128 v[160:163], v149 offset:2048
	ds_read_b128 v[164:167], v149 offset:3072
	ds_read_b128 v[168:171], v150
	ds_read_b128 v[172:175], v150 offset:1024
	ds_read_b128 v[176:179], v150 offset:2048
	ds_read_b128 v[180:183], v150 offset:3072
	s_add_u32 s34, s30, 0xfff80080
	s_addc_u32 s35, s31, -1
	s_cmp_eq_u32 s61, 28
	s_cselect_b32 s37, s23, s35
	s_cselect_b32 s36, s57, s34
	s_cselect_b32 s35, s15, s60
	s_cselect_b32 s34, s58, s59
	s_add_i32 m0, s29, 0xc000
	ds_read_b128 v[184:187], v151
	ds_read_b128 v[188:191], v151 offset:1024
	ds_read_b128 v[192:195], v151 offset:2048
	ds_read_b128 v[196:199], v151 offset:3072
	ds_read_b128 v[200:203], v151 offset:4096
	ds_read_b128 v[204:207], v151 offset:5120
	ds_read_b128 v[208:211], v151 offset:6144
	ds_read_b128 v[212:215], v151 offset:7168
	global_load_lds_dwordx4 v136, s[30:31]
	s_add_i32 m0, s29, 0xe000
	s_nop 0
	global_load_lds_dwordx4 v138, s[30:31]
	s_waitcnt vmcnt(8)
	s_waitcnt lgkmcnt(0)
	s_barrier
	s_waitcnt lgkmcnt(0)
	v_mfma_f32_16x16x32_bf16 v[124:127], v[152:155], v[184:187], 0
	v_mfma_f32_16x16x32_bf16 v[120:123], v[160:163], v[184:187], 0
	v_mfma_f32_16x16x32_bf16 v[108:111], v[152:155], v[192:195], 0
	v_mfma_f32_16x16x32_bf16 v[104:107], v[160:163], v[192:195], 0
	v_mfma_f32_16x16x32_bf16 v[92:95], v[152:155], v[200:203], 0
	v_mfma_f32_16x16x32_bf16 v[88:91], v[160:163], v[200:203], 0
	v_mfma_f32_16x16x32_bf16 v[76:79], v[152:155], v[208:211], 0
	v_mfma_f32_16x16x32_bf16 v[72:75], v[160:163], v[208:211], 0
	v_mfma_f32_16x16x32_bf16 v[124:127], v[156:159], v[188:191], v[124:127]
	v_mfma_f32_16x16x32_bf16 v[120:123], v[164:167], v[188:191], v[120:123]
	v_mfma_f32_16x16x32_bf16 v[108:111], v[156:159], v[196:199], v[108:111]
	v_mfma_f32_16x16x32_bf16 v[104:107], v[164:167], v[196:199], v[104:107]
	v_mfma_f32_16x16x32_bf16 v[92:95], v[156:159], v[204:207], v[92:95]
	v_mfma_f32_16x16x32_bf16 v[88:91], v[164:167], v[204:207], v[88:91]
	v_mfma_f32_16x16x32_bf16 v[76:79], v[156:159], v[212:215], v[76:79]
	v_mfma_f32_16x16x32_bf16 v[72:75], v[164:167], v[212:215], v[72:75]
	v_mfma_f32_16x16x32_bf16 v[116:119], v[168:171], v[184:187], 0
	v_mfma_f32_16x16x32_bf16 v[112:115], v[176:179], v[184:187], 0
	v_mfma_f32_16x16x32_bf16 v[100:103], v[168:171], v[192:195], 0
	v_mfma_f32_16x16x32_bf16 v[96:99], v[176:179], v[192:195], 0
	v_mfma_f32_16x16x32_bf16 v[84:87], v[168:171], v[200:203], 0
	v_mfma_f32_16x16x32_bf16 v[80:83], v[176:179], v[200:203], 0
	v_mfma_f32_16x16x32_bf16 v[68:71], v[168:171], v[208:211], 0
	v_mfma_f32_16x16x32_bf16 v[64:67], v[176:179], v[208:211], 0
	v_mfma_f32_16x16x32_bf16 v[116:119], v[172:175], v[188:191], v[116:119]
	v_mfma_f32_16x16x32_bf16 v[112:115], v[180:183], v[188:191], v[112:115]
	v_mfma_f32_16x16x32_bf16 v[100:103], v[172:175], v[196:199], v[100:103]
	v_mfma_f32_16x16x32_bf16 v[96:99], v[180:183], v[196:199], v[96:99]
	v_mfma_f32_16x16x32_bf16 v[84:87], v[172:175], v[204:207], v[84:87]
	v_mfma_f32_16x16x32_bf16 v[80:83], v[180:183], v[204:207], v[80:83]
	v_mfma_f32_16x16x32_bf16 v[68:71], v[172:175], v[212:215], v[68:71]
	v_mfma_f32_16x16x32_bf16 v[64:67], v[180:183], v[212:215], v[64:67]
	s_barrier
	s_add_i32 s62, s53, s42
	s_mov_b32 m0, s62
	ds_read_b128 v[184:187], v151 offset:16384
	ds_read_b128 v[188:191], v151 offset:17408
	ds_read_b128 v[192:195], v151 offset:18432
	ds_read_b128 v[196:199], v151 offset:19456
	ds_read_b128 v[200:203], v151 offset:20480
	ds_read_b128 v[204:207], v151 offset:21504
	ds_read_b128 v[208:211], v151 offset:22528
	ds_read_b128 v[212:215], v151 offset:23552
	global_load_lds_dwordx4 v132, s[34:35]
	s_add_i32 m0, s62, 0x2000
	s_add_u32 s62, s34, 0x80000
	s_addc_u32 s63, s35, 0
	s_add_i32 s64, s54, s42
	global_load_lds_dwordx4 v128, s[34:35]
	s_mov_b32 m0, s64
	s_nop 0
	global_load_lds_dwordx4 v132, s[62:63]
	s_add_i32 m0, s64, 0x2000
	s_nop 0
	global_load_lds_dwordx4 v128, s[62:63]
	s_mov_b32 m0, s29
	s_nop 0
	global_load_lds_dwordx4 v134, s[36:37]
	s_mov_b32 m0, s45
	s_nop 0
	global_load_lds_dwordx4 v130, s[36:37]
	s_waitcnt vmcnt(8)
	s_waitcnt lgkmcnt(0)
	s_barrier
; #define PG8_STAGE(bufoff, gbase, voff) do { _Pragma("unroll") for (int _i = 0; _i < 2; ++_i) \
;         __builtin_amdgcn_global_load_lds((const unsigned*)((const char*)(gbase) + (voff)[_i]), (PG8_LAS unsigned*)(lds + (bufoff) + ldsw + _i * 8192), 16, 0, 0); } while (0)
; #define PG8_LDA(dst, b, h) do { _Pragma("unroll") for (int m = 0; m < 4; ++m) _Pragma("unroll") for (int k = 0; k < 2; ++k) dst[m][k] = *(const PG8_LAS bf16x8*)(lds + PG8_SA(b, h) + aoff + m * 2048 + k * 1024); } while (0)
; #define PG8_LDB(dst, b, h) do { _Pragma("unroll") for (int n = 0; n < 2; ++n) _Pragma("unroll") for (int k = 0; k < 2; ++k) dst[n][k] = *(const PG8_LAS bf16x8*)(lds + PG8_SB(b, h) + boff + n * 2048 + k * 1024); } while (0)
; #define PG8_MMA(ai, bj, At, Bt) do { __builtin_amdgcn_s_setprio(1); _Pragma("unroll") for (int m = 0; m < 4; ++m) _Pragma("unroll") for (int n = 0; n < 2; ++n) _Pragma("unroll") for (int k = 0; k < 2; ++k) \
;         acc[ai][bj][m][n] = __builtin_amdgcn_mfma_f32_16x16x32_bf16(Bt[n][k], At[m][k], acc[ai][bj][m][n], 0, 0, 0); __builtin_amdgcn_s_setprio(0); } while (0)
; #define PG8_WAIT_V(n) asm volatile("s_waitcnt vmcnt(" #n ")" ::: "memory")
; #define PG8_WAIT_L(n) asm volatile("s_waitcnt lgkmcnt(" #n ")" ::: "memory")
; #define PG8_BAR __builtin_amdgcn_s_barrier()
; #define PG8_SCHED __builtin_amdgcn_sched_barrier(0)
; template <class Epi, class Sched, bool ALIGN_EPI = false, bool SP2 = false>
; __device__ __forceinline__ void gemm_phase(PG8_LAS unsigned char* lds, const Gemm g, const Sched& S, const Epi& E) {
;     ...
;             PG8_WAIT_V(8); PG8_WAIT_L(0); PG8_BAR; PG8_MMA(1, 0, At, B0); PG8_MMA(1, 1, At, B1); PG8_BAR; PG8_SCHED;
;             PG8_LDB(B0, 1, 0); PG8_LDB(B1, 1, 1); PG8_SCHED; PG8_LDA(At, 1, 0); PG8_STAGE(PG8_SA(0, 1), a2 + hstep, voffA);
;             PG8_WAIT_V(8); PG8_WAIT_L(0); PG8_BAR; PG8_MMA(0, 0, At, B0); PG8_MMA(0, 1, At, B1); PG8_BAR; PG8_SCHED;
	s_waitcnt lgkmcnt(0)
	v_mfma_f32_16x16x32_bf16 v[60:63], v[152:155], v[184:187], 0
	v_mfma_f32_16x16x32_bf16 v[56:59], v[160:163], v[184:187], 0
	v_mfma_f32_16x16x32_bf16 v[44:47], v[152:155], v[192:195], 0
	v_mfma_f32_16x16x32_bf16 v[40:43], v[160:163], v[192:195], 0
	v_mfma_f32_16x16x32_bf16 v[28:31], v[152:155], v[200:203], 0
	v_mfma_f32_16x16x32_bf16 v[24:27], v[160:163], v[200:203], 0
	v_mfma_f32_16x16x32_bf16 v[12:15], v[152:155], v[208:211], 0
	v_mfma_f32_16x16x32_bf16 v[8:11], v[160:163], v[208:211], 0
	v_mfma_f32_16x16x32_bf16 v[60:63], v[156:159], v[188:191], v[60:63]
	v_mfma_f32_16x16x32_bf16 v[56:59], v[164:167], v[188:191], v[56:59]
	v_mfma_f32_16x16x32_bf16 v[44:47], v[156:159], v[196:199], v[44:47]
	v_mfma_f32_16x16x32_bf16 v[40:43], v[164:167], v[196:199], v[40:43]
	v_mfma_f32_16x16x32_bf16 v[28:31], v[156:159], v[204:207], v[28:31]
	v_mfma_f32_16x16x32_bf16 v[24:27], v[164:167], v[204:207], v[24:27]
	v_mfma_f32_16x16x32_bf16 v[12:15], v[156:159], v[212:215], v[12:15]
	v_mfma_f32_16x16x32_bf16 v[8:11], v[164:167], v[212:215], v[8:11]
	v_mfma_f32_16x16x32_bf16 v[52:55], v[168:171], v[184:187], 0
	v_mfma_f32_16x16x32_bf16 v[48:51], v[176:179], v[184:187], 0
	v_mfma_f32_16x16x32_bf16 v[36:39], v[168:171], v[192:195], 0
	v_mfma_f32_16x16x32_bf16 v[32:35], v[176:179], v[192:195], 0
	v_mfma_f32_16x16x32_bf16 v[20:23], v[168:171], v[200:203], 0
	v_mfma_f32_16x16x32_bf16 v[16:19], v[176:179], v[200:203], 0
	v_mfma_f32_16x16x32_bf16 v[4:7], v[168:171], v[208:211], 0
	v_mfma_f32_16x16x32_bf16 v[0:3], v[176:179], v[208:211], 0
	v_mfma_f32_16x16x32_bf16 v[52:55], v[172:175], v[188:191], v[52:55]
	v_mfma_f32_16x16x32_bf16 v[48:51], v[180:183], v[188:191], v[48:51]
	v_mfma_f32_16x16x32_bf16 v[36:39], v[172:175], v[196:199], v[36:39]
	v_mfma_f32_16x16x32_bf16 v[32:35], v[180:183], v[196:199], v[32:35]
	v_mfma_f32_16x16x32_bf16 v[20:23], v[172:175], v[204:207], v[20:23]
	v_mfma_f32_16x16x32_bf16 v[16:19], v[180:183], v[204:207], v[16:19]
	v_mfma_f32_16x16x32_bf16 v[4:7], v[172:175], v[212:215], v[4:7]
	v_mfma_f32_16x16x32_bf16 v[0:3], v[180:183], v[212:215], v[0:3]
	s_barrier
	s_add_i32 s62, 0, 0x18000
	s_add_i32 s63, 0, 0x1c000
	v_add_u32_e32 v164, s62, v147
	v_add_u32_e32 v180, s63, v147
	ds_read_b128 v[152:155], v164
	ds_read_b128 v[156:159], v164 offset:1024
	ds_read_b128 v[160:163], v164 offset:2048
	ds_read_b128 v[164:167], v164 offset:3072
	ds_read_b128 v[168:171], v180
	ds_read_b128 v[172:175], v180 offset:1024
	ds_read_b128 v[176:179], v180 offset:2048
	ds_read_b128 v[180:183], v180 offset:3072
	s_add_u32 s84, s36, 0x80
	s_addc_u32 s85, s37, 0
	s_add_u32 s36, s36, 0x80000
	s_addc_u32 s37, s37, 0
	s_mov_b32 m0, s46
	ds_read_b128 v[184:187], v151 offset:32768
	ds_read_b128 v[188:191], v151 offset:33792
	ds_read_b128 v[192:195], v151 offset:34816
	ds_read_b128 v[196:199], v151 offset:35840
	ds_read_b128 v[200:203], v151 offset:36864
	ds_read_b128 v[204:207], v151 offset:37888
	ds_read_b128 v[208:211], v151 offset:38912
	ds_read_b128 v[212:215], v151 offset:39936
	global_load_lds_dwordx4 v134, s[36:37]
	s_mov_b32 m0, s47
	s_nop 0
	global_load_lds_dwordx4 v130, s[36:37]
	s_waitcnt vmcnt(8)
	s_waitcnt lgkmcnt(0)
	s_barrier
	s_waitcnt lgkmcnt(0)
	v_mfma_f32_16x16x32_bf16 v[124:127], v[152:155], v[184:187], v[124:127]
	v_mfma_f32_16x16x32_bf16 v[120:123], v[160:163], v[184:187], v[120:123]
	v_mfma_f32_16x16x32_bf16 v[108:111], v[152:155], v[192:195], v[108:111]
	v_mfma_f32_16x16x32_bf16 v[104:107], v[160:163], v[192:195], v[104:107]
	v_mfma_f32_16x16x32_bf16 v[92:95], v[152:155], v[200:203], v[92:95]
	v_mfma_f32_16x16x32_bf16 v[88:91], v[160:163], v[200:203], v[88:91]
	v_mfma_f32_16x16x32_bf16 v[76:79], v[152:155], v[208:211], v[76:79]
	v_mfma_f32_16x16x32_bf16 v[72:75], v[160:163], v[208:211], v[72:75]
	v_mfma_f32_16x16x32_bf16 v[124:127], v[156:159], v[188:191], v[124:127]
	v_mfma_f32_16x16x32_bf16 v[120:123], v[164:167], v[188:191], v[120:123]
	v_mfma_f32_16x16x32_bf16 v[108:111], v[156:159], v[196:199], v[108:111]
	v_mfma_f32_16x16x32_bf16 v[104:107], v[164:167], v[196:199], v[104:107]
	v_mfma_f32_16x16x32_bf16 v[92:95], v[156:159], v[204:207], v[92:95]
	v_mfma_f32_16x16x32_bf16 v[88:91], v[164:167], v[204:207], v[88:91]
	v_mfma_f32_16x16x32_bf16 v[76:79], v[156:159], v[212:215], v[76:79]
	v_mfma_f32_16x16x32_bf16 v[72:75], v[164:167], v[212:215], v[72:75]
	v_mfma_f32_16x16x32_bf16 v[116:119], v[168:171], v[184:187], v[116:119]
	v_mfma_f32_16x16x32_bf16 v[112:115], v[176:179], v[184:187], v[112:115]
	v_mfma_f32_16x16x32_bf16 v[100:103], v[168:171], v[192:195], v[100:103]
	v_mfma_f32_16x16x32_bf16 v[96:99], v[176:179], v[192:195], v[96:99]
	v_mfma_f32_16x16x32_bf16 v[84:87], v[168:171], v[200:203], v[84:87]
	v_mfma_f32_16x16x32_bf16 v[80:83], v[176:179], v[200:203], v[80:83]
	v_mfma_f32_16x16x32_bf16 v[68:71], v[168:171], v[208:211], v[68:71]
	v_mfma_f32_16x16x32_bf16 v[64:67], v[176:179], v[208:211], v[64:67]
	v_mfma_f32_16x16x32_bf16 v[116:119], v[172:175], v[188:191], v[116:119]
	v_mfma_f32_16x16x32_bf16 v[112:115], v[180:183], v[188:191], v[112:115]
	v_mfma_f32_16x16x32_bf16 v[100:103], v[172:175], v[196:199], v[100:103]
	v_mfma_f32_16x16x32_bf16 v[96:99], v[180:183], v[196:199], v[96:99]
	v_mfma_f32_16x16x32_bf16 v[84:87], v[172:175], v[204:207], v[84:87]
	v_mfma_f32_16x16x32_bf16 v[80:83], v[180:183], v[204:207], v[80:83]
	v_mfma_f32_16x16x32_bf16 v[68:71], v[172:175], v[212:215], v[68:71]
	v_mfma_f32_16x16x32_bf16 v[64:67], v[180:183], v[212:215], v[64:67]
	s_barrier
; #define PG8_STAGE(bufoff, gbase, voff) do { _Pragma("unroll") for (int _i = 0; _i < 2; ++_i) \
;         __builtin_amdgcn_global_load_lds((const unsigned*)((const char*)(gbase) + (voff)[_i]), (PG8_LAS unsigned*)(lds + (bufoff) + ldsw + _i * 8192), 16, 0, 0); } while (0)
; #define PG8_LDA(dst, b, h) do { _Pragma("unroll") for (int m = 0; m < 4; ++m) _Pragma("unroll") for (int k = 0; k < 2; ++k) dst[m][k] = *(const PG8_LAS bf16x8*)(lds + PG8_SA(b, h) + aoff + m * 2048 + k * 1024); } while (0)
; #define PG8_MMA(ai, bj, At, Bt) do { __builtin_amdgcn_s_setprio(1); _Pragma("unroll") for (int m = 0; m < 4; ++m) _Pragma("unroll") for (int n = 0; n < 2; ++n) _Pragma("unroll") for (int k = 0; k < 2; ++k) \
;         acc[ai][bj][m][n] = __builtin_amdgcn_mfma_f32_16x16x32_bf16(Bt[n][k], At[m][k], acc[ai][bj][m][n], 0, 0, 0); __builtin_amdgcn_s_setprio(0); } while (0)
; #define PG8_WAIT_V(n) asm volatile("s_waitcnt vmcnt(" #n ")" ::: "memory")
; #define PG8_WAIT_L(n) asm volatile("s_waitcnt lgkmcnt(" #n ")" ::: "memory")
; #define PG8_BAR __builtin_amdgcn_s_barrier()
; #define PG8_SCHED __builtin_amdgcn_sched_barrier(0)
; template <class Epi, class Sched, bool ALIGN_EPI = false, bool SP2 = false>
; __device__ __forceinline__ void gemm_phase(PG8_LAS unsigned char* lds, const Gemm g, const Sched& S, const Epi& E) {
;     ...
;             PG8_LDA(At, 1, 1); PG8_STAGE(PG8_SB(1, 0), b3, voffB); PG8_STAGE(PG8_SB(1, 1), b3 + hstep, voffB); PG8_STAGE(PG8_SA(1, 0), a3, voffA);
;             PG8_WAIT_V(8); PG8_WAIT_L(0); PG8_BAR; PG8_MMA(1, 0, At, B0); PG8_MMA(1, 1, At, B1); PG8_BAR; PG8_SCHED;
	s_add_i32 s36, s62, s42
	s_add_u32 s86, s34, 0x80
	s_addc_u32 s87, s35, 0
	s_mov_b32 m0, s36
	ds_read_b128 v[184:187], v151 offset:49152
	ds_read_b128 v[188:191], v151 offset:50176
	ds_read_b128 v[192:195], v151 offset:51200
	ds_read_b128 v[196:199], v151 offset:52224
	ds_read_b128 v[200:203], v151 offset:53248
	ds_read_b128 v[204:207], v151 offset:54272
	ds_read_b128 v[208:211], v151 offset:55296
	ds_read_b128 v[212:215], v151 offset:56320
	global_load_lds_dwordx4 v132, s[86:87]
	s_add_i32 m0, s36, 0x2000
	s_add_u32 s34, s34, 0x80080
	s_addc_u32 s35, s35, 0
	s_add_i32 s36, s63, s42
	global_load_lds_dwordx4 v128, s[86:87]
	s_mov_b32 m0, s36
	s_nop 0
	global_load_lds_dwordx4 v132, s[34:35]
	s_add_i32 m0, s36, 0x2000
	s_nop 0
	global_load_lds_dwordx4 v128, s[34:35]
	s_mov_b32 m0, s49
	s_nop 0
	global_load_lds_dwordx4 v134, s[84:85]
	s_mov_b32 m0, s50
	s_nop 0
	global_load_lds_dwordx4 v130, s[84:85]
	s_waitcnt vmcnt(8)
	s_waitcnt lgkmcnt(0)
	s_barrier
	s_waitcnt lgkmcnt(0)
	v_mfma_f32_16x16x32_bf16 v[60:63], v[152:155], v[184:187], v[60:63]
	v_mfma_f32_16x16x32_bf16 v[56:59], v[160:163], v[184:187], v[56:59]
	v_mfma_f32_16x16x32_bf16 v[44:47], v[152:155], v[192:195], v[44:47]
	v_mfma_f32_16x16x32_bf16 v[40:43], v[160:163], v[192:195], v[40:43]
	v_mfma_f32_16x16x32_bf16 v[28:31], v[152:155], v[200:203], v[28:31]
	v_mfma_f32_16x16x32_bf16 v[24:27], v[160:163], v[200:203], v[24:27]
	v_mfma_f32_16x16x32_bf16 v[12:15], v[152:155], v[208:211], v[12:15]
	v_mfma_f32_16x16x32_bf16 v[8:11], v[160:163], v[208:211], v[8:11]
	v_mfma_f32_16x16x32_bf16 v[60:63], v[156:159], v[188:191], v[60:63]
	v_mfma_f32_16x16x32_bf16 v[56:59], v[164:167], v[188:191], v[56:59]
	v_mfma_f32_16x16x32_bf16 v[44:47], v[156:159], v[196:199], v[44:47]
	v_mfma_f32_16x16x32_bf16 v[40:43], v[164:167], v[196:199], v[40:43]
	v_mfma_f32_16x16x32_bf16 v[28:31], v[156:159], v[204:207], v[28:31]
	v_mfma_f32_16x16x32_bf16 v[24:27], v[164:167], v[204:207], v[24:27]
	v_mfma_f32_16x16x32_bf16 v[12:15], v[156:159], v[212:215], v[12:15]
	v_mfma_f32_16x16x32_bf16 v[8:11], v[164:167], v[212:215], v[8:11]
	v_mfma_f32_16x16x32_bf16 v[52:55], v[168:171], v[184:187], v[52:55]
	v_mfma_f32_16x16x32_bf16 v[48:51], v[176:179], v[184:187], v[48:51]
	v_mfma_f32_16x16x32_bf16 v[36:39], v[168:171], v[192:195], v[36:39]
	v_mfma_f32_16x16x32_bf16 v[32:35], v[176:179], v[192:195], v[32:35]
	v_mfma_f32_16x16x32_bf16 v[20:23], v[168:171], v[200:203], v[20:23]
	v_mfma_f32_16x16x32_bf16 v[16:19], v[176:179], v[200:203], v[16:19]
	v_mfma_f32_16x16x32_bf16 v[4:7], v[168:171], v[208:211], v[4:7]
	v_mfma_f32_16x16x32_bf16 v[0:3], v[176:179], v[208:211], v[0:3]
	v_mfma_f32_16x16x32_bf16 v[52:55], v[172:175], v[188:191], v[52:55]
	v_mfma_f32_16x16x32_bf16 v[48:51], v[180:183], v[188:191], v[48:51]
	v_mfma_f32_16x16x32_bf16 v[36:39], v[172:175], v[196:199], v[36:39]
	v_mfma_f32_16x16x32_bf16 v[32:35], v[180:183], v[196:199], v[32:35]
	v_mfma_f32_16x16x32_bf16 v[20:23], v[172:175], v[204:207], v[20:23]
	v_mfma_f32_16x16x32_bf16 v[16:19], v[180:183], v[204:207], v[16:19]
	v_mfma_f32_16x16x32_bf16 v[4:7], v[172:175], v[212:215], v[4:7]
	v_mfma_f32_16x16x32_bf16 v[0:3], v[180:183], v[212:215], v[0:3]
	s_barrier
	s_add_i32 s61, s61, 2
	s_add_u32 s30, s30, 0x100
	s_addc_u32 s31, s31, 0
	s_add_u32 s59, s59, 0x100
	s_addc_u32 s60, s60, 0
	s_cmp_gt_u32 s61, 29
	.p2align	6

; #define PG8_STAGE(bufoff, gbase, voff) do { _Pragma("unroll") for (int _i = 0; _i < 2; ++_i) \
;         __builtin_amdgcn_global_load_lds((const unsigned*)((const char*)(gbase) + (voff)[_i]), (PG8_LAS unsigned*)(lds + (bufoff) + ldsw + _i * 8192), 16, 0, 0); } while (0)
; #define PG8_LDA(dst, b, h) do { _Pragma("unroll") for (int m = 0; m < 4; ++m) _Pragma("unroll") for (int k = 0; k < 2; ++k) dst[m][k] = *(const PG8_LAS bf16x8*)(lds + PG8_SA(b, h) + aoff + m * 2048 + k * 1024); } while (0)
; #define PG8_LDB(dst, b, h) do { _Pragma("unroll") for (int n = 0; n < 2; ++n) _Pragma("unroll") for (int k = 0; k < 2; ++k) dst[n][k] = *(const PG8_LAS bf16x8*)(lds + PG8_SB(b, h) + boff + n * 2048 + k * 1024); } while (0)
; #define PG8_MMA(ai, bj, At, Bt) do { __builtin_amdgcn_s_setprio(1); _Pragma("unroll") for (int m = 0; m < 4; ++m) _Pragma("unroll") for (int n = 0; n < 2; ++n) _Pragma("unroll") for (int k = 0; k < 2; ++k) \
;         acc[ai][bj][m][n] = __builtin_amdgcn_mfma_f32_16x16x32_bf16(Bt[n][k], At[m][k], acc[ai][bj][m][n], 0, 0, 0); __builtin_amdgcn_s_setprio(0); } while (0)
; #define PG8_WAIT_V(n) asm volatile("s_waitcnt vmcnt(" #n ")" ::: "memory")
; #define PG8_WAIT_L(n) asm volatile("s_waitcnt lgkmcnt(" #n ")" ::: "memory")
; #define PG8_BAR __builtin_amdgcn_s_barrier()
; #define PG8_SCHED __builtin_amdgcn_sched_barrier(0)
; template <class Epi, class Sched, bool ALIGN_EPI = false, bool SP2 = false>
; __device__ __forceinline__ void gemm_phase(PG8_LAS unsigned char* lds, const Gemm g, const Sched& S, const Epi& E) {
;     ...
;             PG8_LDB(B0, 0, 0); PG8_LDB(B1, 0, 1); PG8_SCHED; PG8_LDA(At, 0, 0); PG8_STAGE(PG8_SA(1, 1), a1 + hstep, voffA);
;             PG8_WAIT_V(8); PG8_WAIT_L(0); PG8_BAR; PG8_MMA(0, 0, At, B0); PG8_MMA(0, 1, At, B1); PG8_BAR; PG8_SCHED;
;             PG8_LDA(At, 0, 1); PG8_STAGE(PG8_SB(0, 0), b2, voffB); PG8_STAGE(PG8_SB(0, 1), b2 + hstep, voffB); PG8_STAGE(PG8_SA(0, 0), a2, voffA);
;             PG8_WAIT_V(8); PG8_WAIT_L(0); PG8_BAR; PG8_MMA(1, 0, At, B0); PG8_MMA(1, 1, At, B1); PG8_BAR; PG8_SCHED;
.LBB0_1020:
	s_add_u32 s54, s26, 0x100
	s_addc_u32 s55, s27, 0
	s_mov_b32 s56, -2
	ds_read_b128 v[144:147], v169
	ds_read_b128 v[148:151], v169 offset:1024
	ds_read_b128 v[152:155], v169 offset:2048
	ds_read_b128 v[156:159], v169 offset:3072
	ds_read_b128 v[160:163], v170
	ds_read_b128 v[172:175], v170 offset:1024
	ds_read_b128 v[176:179], v170 offset:2048
	ds_read_b128 v[180:183], v170 offset:3072
	s_add_u32 s26, s24, 0x100
	s_addc_u32 s27, s25, 0
	s_cmpk_eq_i32 s56, 0x54
	s_cselect_b32 s31, s5, s27
	s_cselect_b32 s30, s4, s26
	s_cselect_b32 s29, s7, s55
	s_cselect_b32 s28, s6, s54
	s_add_i32 m0, s38, 0xc000
	ds_read_b128 v[184:187], v171
	ds_read_b128 v[188:191], v171 offset:1024
	ds_read_b128 v[192:195], v171 offset:2048
	ds_read_b128 v[196:199], v171 offset:3072
	ds_read_b128 v[200:203], v171 offset:4096
	ds_read_b128 v[204:207], v171 offset:5120
	ds_read_b128 v[208:211], v171 offset:6144
	ds_read_b128 v[212:215], v171 offset:7168
	global_load_lds_dwordx4 v136, s[24:25]
	s_add_i32 m0, s38, 0xe000
	s_nop 0
	global_load_lds_dwordx4 v138, s[24:25]
	s_waitcnt vmcnt(8)
	s_waitcnt lgkmcnt(0)
	s_barrier
	s_waitcnt lgkmcnt(0)
	v_mfma_f32_16x16x32_bf16 v[124:127], v[144:147], v[184:187], 0
	v_mfma_f32_16x16x32_bf16 v[120:123], v[152:155], v[184:187], 0
	v_mfma_f32_16x16x32_bf16 v[116:119], v[144:147], v[192:195], 0
	v_mfma_f32_16x16x32_bf16 v[112:115], v[152:155], v[192:195], 0
	v_mfma_f32_16x16x32_bf16 v[108:111], v[144:147], v[200:203], 0
	v_mfma_f32_16x16x32_bf16 v[96:99], v[152:155], v[200:203], 0
	v_mfma_f32_16x16x32_bf16 v[84:87], v[144:147], v[208:211], 0
	v_mfma_f32_16x16x32_bf16 v[76:79], v[152:155], v[208:211], 0
	v_mfma_f32_16x16x32_bf16 v[124:127], v[148:151], v[188:191], v[124:127]
	v_mfma_f32_16x16x32_bf16 v[120:123], v[156:159], v[188:191], v[120:123]
	v_mfma_f32_16x16x32_bf16 v[116:119], v[148:151], v[196:199], v[116:119]
	v_mfma_f32_16x16x32_bf16 v[112:115], v[156:159], v[196:199], v[112:115]
	v_mfma_f32_16x16x32_bf16 v[108:111], v[148:151], v[204:207], v[108:111]
	v_mfma_f32_16x16x32_bf16 v[96:99], v[156:159], v[204:207], v[96:99]
	v_mfma_f32_16x16x32_bf16 v[84:87], v[148:151], v[212:215], v[84:87]
	v_mfma_f32_16x16x32_bf16 v[76:79], v[156:159], v[212:215], v[76:79]
	v_mfma_f32_16x16x32_bf16 v[104:107], v[160:163], v[184:187], 0
	v_mfma_f32_16x16x32_bf16 v[100:103], v[176:179], v[184:187], 0
	v_mfma_f32_16x16x32_bf16 v[92:95], v[160:163], v[192:195], 0
	v_mfma_f32_16x16x32_bf16 v[88:91], v[176:179], v[192:195], 0
	v_mfma_f32_16x16x32_bf16 v[80:83], v[160:163], v[200:203], 0
	v_mfma_f32_16x16x32_bf16 v[72:75], v[176:179], v[200:203], 0
	v_mfma_f32_16x16x32_bf16 v[68:71], v[160:163], v[208:211], 0
	v_mfma_f32_16x16x32_bf16 v[64:67], v[176:179], v[208:211], 0
	v_mfma_f32_16x16x32_bf16 v[104:107], v[172:175], v[188:191], v[104:107]
	v_mfma_f32_16x16x32_bf16 v[100:103], v[180:183], v[188:191], v[100:103]
	v_mfma_f32_16x16x32_bf16 v[92:95], v[172:175], v[196:199], v[92:95]
	v_mfma_f32_16x16x32_bf16 v[88:91], v[180:183], v[196:199], v[88:91]
	v_mfma_f32_16x16x32_bf16 v[80:83], v[172:175], v[204:207], v[80:83]
	v_mfma_f32_16x16x32_bf16 v[72:75], v[180:183], v[204:207], v[72:75]
	v_mfma_f32_16x16x32_bf16 v[68:71], v[172:175], v[212:215], v[68:71]
	v_mfma_f32_16x16x32_bf16 v[64:67], v[180:183], v[212:215], v[64:67]
	s_barrier
	s_add_i32 s24, s48, s37
	s_mov_b32 m0, s24
	ds_read_b128 v[184:187], v171 offset:16384
	ds_read_b128 v[188:191], v171 offset:17408
	ds_read_b128 v[192:195], v171 offset:18432
	ds_read_b128 v[196:199], v171 offset:19456
	ds_read_b128 v[200:203], v171 offset:20480
	ds_read_b128 v[204:207], v171 offset:21504
	ds_read_b128 v[208:211], v171 offset:22528
	ds_read_b128 v[212:215], v171 offset:23552
	global_load_lds_dwordx4 v130, s[28:29]
	s_add_i32 m0, s24, 0x2000
	s_add_u32 s24, s28, 0x160000
	s_addc_u32 s25, s29, 0
	s_add_i32 s57, s49, s37
	global_load_lds_dwordx4 v134, s[28:29]
	s_mov_b32 m0, s57
	s_nop 0
	global_load_lds_dwordx4 v130, s[24:25]
	s_add_i32 m0, s57, 0x2000
	s_nop 0
	global_load_lds_dwordx4 v134, s[24:25]
	s_mov_b32 m0, s38
	s_nop 0
	global_load_lds_dwordx4 v128, s[30:31]
	s_mov_b32 m0, s39
	s_nop 0
	global_load_lds_dwordx4 v132, s[30:31]
	s_waitcnt vmcnt(8)
	s_waitcnt lgkmcnt(0)
	s_barrier
	s_waitcnt lgkmcnt(0)
	v_mfma_f32_16x16x32_bf16 v[60:63], v[144:147], v[184:187], 0
	v_mfma_f32_16x16x32_bf16 v[56:59], v[152:155], v[184:187], 0
	v_mfma_f32_16x16x32_bf16 v[52:55], v[144:147], v[192:195], 0
	v_mfma_f32_16x16x32_bf16 v[48:51], v[152:155], v[192:195], 0
	v_mfma_f32_16x16x32_bf16 v[44:47], v[144:147], v[200:203], 0
	v_mfma_f32_16x16x32_bf16 v[32:35], v[152:155], v[200:203], 0
	v_mfma_f32_16x16x32_bf16 v[20:23], v[144:147], v[208:211], 0
	v_mfma_f32_16x16x32_bf16 v[12:15], v[152:155], v[208:211], 0
	v_mfma_f32_16x16x32_bf16 v[60:63], v[148:151], v[188:191], v[60:63]
	v_mfma_f32_16x16x32_bf16 v[56:59], v[156:159], v[188:191], v[56:59]
	v_mfma_f32_16x16x32_bf16 v[52:55], v[148:151], v[196:199], v[52:55]
	v_mfma_f32_16x16x32_bf16 v[48:51], v[156:159], v[196:199], v[48:51]
	v_mfma_f32_16x16x32_bf16 v[44:47], v[148:151], v[204:207], v[44:47]
	v_mfma_f32_16x16x32_bf16 v[32:35], v[156:159], v[204:207], v[32:35]
	v_mfma_f32_16x16x32_bf16 v[20:23], v[148:151], v[212:215], v[20:23]
	v_mfma_f32_16x16x32_bf16 v[12:15], v[156:159], v[212:215], v[12:15]
	v_mfma_f32_16x16x32_bf16 v[40:43], v[160:163], v[184:187], 0
	v_mfma_f32_16x16x32_bf16 v[36:39], v[176:179], v[184:187], 0
	v_mfma_f32_16x16x32_bf16 v[28:31], v[160:163], v[192:195], 0
	v_mfma_f32_16x16x32_bf16 v[24:27], v[176:179], v[192:195], 0
	v_mfma_f32_16x16x32_bf16 v[16:19], v[160:163], v[200:203], 0
	v_mfma_f32_16x16x32_bf16 v[8:11], v[176:179], v[200:203], 0
	v_mfma_f32_16x16x32_bf16 v[4:7], v[160:163], v[208:211], 0
	v_mfma_f32_16x16x32_bf16 v[0:3], v[176:179], v[208:211], 0
	v_mfma_f32_16x16x32_bf16 v[40:43], v[172:175], v[188:191], v[40:43]
	v_mfma_f32_16x16x32_bf16 v[36:39], v[180:183], v[188:191], v[36:39]
	v_mfma_f32_16x16x32_bf16 v[28:31], v[172:175], v[196:199], v[28:31]
	v_mfma_f32_16x16x32_bf16 v[24:27], v[180:183], v[196:199], v[24:27]
	v_mfma_f32_16x16x32_bf16 v[16:19], v[172:175], v[204:207], v[16:19]
	v_mfma_f32_16x16x32_bf16 v[8:11], v[180:183], v[204:207], v[8:11]
	v_mfma_f32_16x16x32_bf16 v[4:7], v[172:175], v[212:215], v[4:7]
	v_mfma_f32_16x16x32_bf16 v[0:3], v[180:183], v[212:215], v[0:3]
	s_barrier
; #define PG8_STAGE(bufoff, gbase, voff) do { _Pragma("unroll") for (int _i = 0; _i < 2; ++_i) \
;         __builtin_amdgcn_global_load_lds((const unsigned*)((const char*)(gbase) + (voff)[_i]), (PG8_LAS unsigned*)(lds + (bufoff) + ldsw + _i * 8192), 16, 0, 0); } while (0)
; #define PG8_LDA(dst, b, h) do { _Pragma("unroll") for (int m = 0; m < 4; ++m) _Pragma("unroll") for (int k = 0; k < 2; ++k) dst[m][k] = *(const PG8_LAS bf16x8*)(lds + PG8_SA(b, h) + aoff + m * 2048 + k * 1024); } while (0)
; #define PG8_LDB(dst, b, h) do { _Pragma("unroll") for (int n = 0; n < 2; ++n) _Pragma("unroll") for (int k = 0; k < 2; ++k) dst[n][k] = *(const PG8_LAS bf16x8*)(lds + PG8_SB(b, h) + boff + n * 2048 + k * 1024); } while (0)
; #define PG8_MMA(ai, bj, At, Bt) do { __builtin_amdgcn_s_setprio(1); _Pragma("unroll") for (int m = 0; m < 4; ++m) _Pragma("unroll") for (int n = 0; n < 2; ++n) _Pragma("unroll") for (int k = 0; k < 2; ++k) \
;         acc[ai][bj][m][n] = __builtin_amdgcn_mfma_f32_16x16x32_bf16(Bt[n][k], At[m][k], acc[ai][bj][m][n], 0, 0, 0); __builtin_amdgcn_s_setprio(0); } while (0)
; #define PG8_WAIT_V(n) asm volatile("s_waitcnt vmcnt(" #n ")" ::: "memory")
; #define PG8_WAIT_L(n) asm volatile("s_waitcnt lgkmcnt(" #n ")" ::: "memory")
; #define PG8_BAR __builtin_amdgcn_s_barrier()
; #define PG8_SCHED __builtin_amdgcn_sched_barrier(0)
; template <class Epi, class Sched, bool ALIGN_EPI = false, bool SP2 = false>
; __device__ __forceinline__ void gemm_phase(PG8_LAS unsigned char* lds, const Gemm g, const Sched& S, const Epi& E) {
;     ...
;             PG8_LDB(B0, 1, 0); PG8_LDB(B1, 1, 1); PG8_SCHED; PG8_LDA(At, 1, 0); PG8_STAGE(PG8_SA(0, 1), a2 + hstep, voffA);
;             PG8_WAIT_V(8); PG8_WAIT_L(0); PG8_BAR; PG8_MMA(0, 0, At, B0); PG8_MMA(0, 1, At, B1); PG8_BAR; PG8_SCHED;
;             PG8_LDA(At, 1, 1); PG8_STAGE(PG8_SB(1, 0), b3, voffB); PG8_STAGE(PG8_SB(1, 1), b3 + hstep, voffB); PG8_STAGE(PG8_SA(1, 0), a3, voffA);
;             PG8_WAIT_V(8); PG8_WAIT_L(0); PG8_BAR; PG8_MMA(1, 0, At, B0); PG8_MMA(1, 1, At, B1); PG8_BAR; PG8_SCHED;
	s_add_i32 s57, 0, 0x18000
	s_add_i32 s58, 0, 0x1c000
	v_add_u32_e32 v156, s57, v167
	v_add_u32_e32 v180, s58, v167
	ds_read_b128 v[144:147], v156
	ds_read_b128 v[148:151], v156 offset:1024
	ds_read_b128 v[152:155], v156 offset:2048
	ds_read_b128 v[156:159], v156 offset:3072
	ds_read_b128 v[160:163], v180
	ds_read_b128 v[172:175], v180 offset:1024
	ds_read_b128 v[176:179], v180 offset:2048
	ds_read_b128 v[180:183], v180 offset:3072
	s_add_u32 s24, s30, 0x160000
	s_addc_u32 s25, s31, 0
	s_mov_b32 m0, s40
	ds_read_b128 v[184:187], v171 offset:32768
	ds_read_b128 v[188:191], v171 offset:33792
	ds_read_b128 v[192:195], v171 offset:34816
	ds_read_b128 v[196:199], v171 offset:35840
	ds_read_b128 v[200:203], v171 offset:36864
	ds_read_b128 v[204:207], v171 offset:37888
	ds_read_b128 v[208:211], v171 offset:38912
	ds_read_b128 v[212:215], v171 offset:39936
	global_load_lds_dwordx4 v128, s[24:25]
	s_mov_b32 m0, s41
	s_nop 0
	global_load_lds_dwordx4 v132, s[24:25]
	s_waitcnt vmcnt(8)
	s_waitcnt lgkmcnt(0)
	s_barrier
	s_waitcnt lgkmcnt(0)
	v_mfma_f32_16x16x32_bf16 v[124:127], v[144:147], v[184:187], v[124:127]
	v_mfma_f32_16x16x32_bf16 v[120:123], v[152:155], v[184:187], v[120:123]
	v_mfma_f32_16x16x32_bf16 v[116:119], v[144:147], v[192:195], v[116:119]
	v_mfma_f32_16x16x32_bf16 v[112:115], v[152:155], v[192:195], v[112:115]
	v_mfma_f32_16x16x32_bf16 v[108:111], v[144:147], v[200:203], v[108:111]
	v_mfma_f32_16x16x32_bf16 v[96:99], v[152:155], v[200:203], v[96:99]
	v_mfma_f32_16x16x32_bf16 v[84:87], v[144:147], v[208:211], v[84:87]
	v_mfma_f32_16x16x32_bf16 v[76:79], v[152:155], v[208:211], v[76:79]
	v_mfma_f32_16x16x32_bf16 v[124:127], v[148:151], v[188:191], v[124:127]
	v_mfma_f32_16x16x32_bf16 v[120:123], v[156:159], v[188:191], v[120:123]
	v_mfma_f32_16x16x32_bf16 v[116:119], v[148:151], v[196:199], v[116:119]
	v_mfma_f32_16x16x32_bf16 v[112:115], v[156:159], v[196:199], v[112:115]
	v_mfma_f32_16x16x32_bf16 v[108:111], v[148:151], v[204:207], v[108:111]
	v_mfma_f32_16x16x32_bf16 v[96:99], v[156:159], v[204:207], v[96:99]
	v_mfma_f32_16x16x32_bf16 v[84:87], v[148:151], v[212:215], v[84:87]
	v_mfma_f32_16x16x32_bf16 v[76:79], v[156:159], v[212:215], v[76:79]
	v_mfma_f32_16x16x32_bf16 v[104:107], v[160:163], v[184:187], v[104:107]
	v_mfma_f32_16x16x32_bf16 v[100:103], v[176:179], v[184:187], v[100:103]
	v_mfma_f32_16x16x32_bf16 v[92:95], v[160:163], v[192:195], v[92:95]
	v_mfma_f32_16x16x32_bf16 v[88:91], v[176:179], v[192:195], v[88:91]
	v_mfma_f32_16x16x32_bf16 v[80:83], v[160:163], v[200:203], v[80:83]
	v_mfma_f32_16x16x32_bf16 v[72:75], v[176:179], v[200:203], v[72:75]
	v_mfma_f32_16x16x32_bf16 v[68:71], v[160:163], v[208:211], v[68:71]
	v_mfma_f32_16x16x32_bf16 v[64:67], v[176:179], v[208:211], v[64:67]
	v_mfma_f32_16x16x32_bf16 v[104:107], v[172:175], v[188:191], v[104:107]
	v_mfma_f32_16x16x32_bf16 v[100:103], v[180:183], v[188:191], v[100:103]
	v_mfma_f32_16x16x32_bf16 v[92:95], v[172:175], v[196:199], v[92:95]
	v_mfma_f32_16x16x32_bf16 v[88:91], v[180:183], v[196:199], v[88:91]
	v_mfma_f32_16x16x32_bf16 v[80:83], v[172:175], v[204:207], v[80:83]
	v_mfma_f32_16x16x32_bf16 v[72:75], v[180:183], v[204:207], v[72:75]
	v_mfma_f32_16x16x32_bf16 v[68:71], v[172:175], v[212:215], v[68:71]
	v_mfma_f32_16x16x32_bf16 v[64:67], v[180:183], v[212:215], v[64:67]
	s_barrier
	s_add_i32 s24, s57, s37
	s_add_u32 s86, s28, 0x80
	s_addc_u32 s87, s29, 0
	s_mov_b32 m0, s24
	ds_read_b128 v[184:187], v171 offset:49152
	ds_read_b128 v[188:191], v171 offset:50176
	ds_read_b128 v[192:195], v171 offset:51200
	ds_read_b128 v[196:199], v171 offset:52224
	ds_read_b128 v[200:203], v171 offset:53248
	ds_read_b128 v[204:207], v171 offset:54272
	ds_read_b128 v[208:211], v171 offset:55296
	ds_read_b128 v[212:215], v171 offset:56320
	global_load_lds_dwordx4 v130, s[86:87]
	s_add_i32 m0, s24, 0x2000
	s_add_u32 s24, s28, 0x160080
	s_addc_u32 s25, s29, 0
	s_add_i32 s28, s58, s37
	global_load_lds_dwordx4 v134, s[86:87]
	s_mov_b32 m0, s28
	s_nop 0
	global_load_lds_dwordx4 v130, s[24:25]
	s_add_i32 m0, s28, 0x2000
	s_nop 0
	global_load_lds_dwordx4 v134, s[24:25]
	s_add_u32 s84, s30, 0x80
	s_addc_u32 s85, s31, 0
	s_mov_b32 m0, s45
	s_nop 0
	global_load_lds_dwordx4 v128, s[84:85]
	s_mov_b32 m0, s46
	s_nop 0
	global_load_lds_dwordx4 v132, s[84:85]
	s_waitcnt vmcnt(8)
	s_waitcnt lgkmcnt(0)
	s_barrier
	s_waitcnt lgkmcnt(0)
	v_mfma_f32_16x16x32_bf16 v[60:63], v[144:147], v[184:187], v[60:63]
	v_mfma_f32_16x16x32_bf16 v[56:59], v[152:155], v[184:187], v[56:59]
	v_mfma_f32_16x16x32_bf16 v[52:55], v[144:147], v[192:195], v[52:55]
	v_mfma_f32_16x16x32_bf16 v[48:51], v[152:155], v[192:195], v[48:51]
	v_mfma_f32_16x16x32_bf16 v[44:47], v[144:147], v[200:203], v[44:47]
	v_mfma_f32_16x16x32_bf16 v[32:35], v[152:155], v[200:203], v[32:35]
	v_mfma_f32_16x16x32_bf16 v[20:23], v[144:147], v[208:211], v[20:23]
	v_mfma_f32_16x16x32_bf16 v[12:15], v[152:155], v[208:211], v[12:15]
	v_mfma_f32_16x16x32_bf16 v[60:63], v[148:151], v[188:191], v[60:63]
	v_mfma_f32_16x16x32_bf16 v[56:59], v[156:159], v[188:191], v[56:59]
	v_mfma_f32_16x16x32_bf16 v[52:55], v[148:151], v[196:199], v[52:55]
	v_mfma_f32_16x16x32_bf16 v[48:51], v[156:159], v[196:199], v[48:51]
	v_mfma_f32_16x16x32_bf16 v[44:47], v[148:151], v[204:207], v[44:47]
	v_mfma_f32_16x16x32_bf16 v[32:35], v[156:159], v[204:207], v[32:35]
	v_mfma_f32_16x16x32_bf16 v[20:23], v[148:151], v[212:215], v[20:23]
	v_mfma_f32_16x16x32_bf16 v[12:15], v[156:159], v[212:215], v[12:15]
	v_mfma_f32_16x16x32_bf16 v[40:43], v[160:163], v[184:187], v[40:43]
	v_mfma_f32_16x16x32_bf16 v[36:39], v[176:179], v[184:187], v[36:39]
	v_mfma_f32_16x16x32_bf16 v[28:31], v[160:163], v[192:195], v[28:31]
	v_mfma_f32_16x16x32_bf16 v[24:27], v[176:179], v[192:195], v[24:27]
	v_mfma_f32_16x16x32_bf16 v[16:19], v[160:163], v[200:203], v[16:19]
	v_mfma_f32_16x16x32_bf16 v[8:11], v[176:179], v[200:203], v[8:11]
	v_mfma_f32_16x16x32_bf16 v[4:7], v[160:163], v[208:211], v[4:7]
	v_mfma_f32_16x16x32_bf16 v[0:3], v[176:179], v[208:211], v[0:3]
	v_mfma_f32_16x16x32_bf16 v[40:43], v[172:175], v[188:191], v[40:43]
	v_mfma_f32_16x16x32_bf16 v[36:39], v[180:183], v[188:191], v[36:39]
	v_mfma_f32_16x16x32_bf16 v[28:31], v[172:175], v[196:199], v[28:31]
	v_mfma_f32_16x16x32_bf16 v[24:27], v[180:183], v[196:199], v[24:27]
	v_mfma_f32_16x16x32_bf16 v[16:19], v[172:175], v[204:207], v[16:19]
	v_mfma_f32_16x16x32_bf16 v[8:11], v[180:183], v[204:207], v[8:11]
	v_mfma_f32_16x16x32_bf16 v[4:7], v[172:175], v[212:215], v[4:7]
	v_mfma_f32_16x16x32_bf16 v[0:3], v[180:183], v[212:215], v[0:3]
	s_barrier
	s_add_i32 s56, s56, 2
	s_add_u32 s54, s54, 0x100
	s_addc_u32 s55, s55, 0
	s_cmpk_gt_u32 s56, 0x55
	s_mov_b64 s[24:25], s[26:27]
	.p2align	6
